# plus: gdn_prep forward substitution rewritten by hand with packed f32 FMAs (x kept in aligned register pairs, L rows streamed through a 16-quad LDS read ring)
# speedup vs baseline: 1.0120x; 1.0017x over previous
; #define SUB_LROW(buf, i_, j0_, n_) do { _Pragma("unroll") for (int j4 = 0; j4 < (n_); ++j4) buf[j4] = *(const f32x4*)(Ls + (i_) * 68 + 4 * ((j0_) + j4)); } while (0)
; #define SUB_FROW(buf, j0_, n_) do { _Pragma("unroll") for (int j4 = 0; j4 < (n_); ++j4) { const f32x4 l = buf[j4]; \
;                 acc -= l.x * x[4 * ((j0_) + j4)]; acc -= l.y * x[4 * ((j0_) + j4) + 1]; acc -= l.z * x[4 * ((j0_) + j4) + 2]; acc -= l.w * x[4 * ((j0_) + j4) + 3]; } } while (0)
; __device__ __forceinline__ void gdn_prep(KA a, int layer, unsigned char* lds, const int tid_, const int bid_) {
;     ...
;         if (tid < 256) {
;             float x[64];
; #pragma unroll
;             for (int i = 0; i < 64; ++i) x[i] = RHS[i * 260 + tid];
;             f32x4 bufA[8], bufB[8];
;     ...
; #pragma unroll
;             for (int j4 = 0; j4 < 8; ++j4) { bufA[j4] = (f32x4){0.f, 0.f, 0.f, 0.f}; bufB[j4] = (f32x4){0.f, 0.f, 0.f, 0.f}; }
;             SUB_LROW(bufA, 1, 0, 1);
; #pragma unroll
;             for (int i = 1; i <= 32; ++i) {
;                 const int nn = (i + 4) / 4 < 8 ? (i + 4) / 4 : 8;
;                 float acc = x[i];
;                 if (i & 1) { SUB_LROW(bufB, i + 1, 0, nn); __builtin_amdgcn_sched_barrier(0); SUB_FROW(bufA, 0, (i + 3) / 4); }
;                 else       { SUB_LROW(bufA, i + 1, 0, nn); __builtin_amdgcn_sched_barrier(0); SUB_FROW(bufB, 0, (i + 3) / 4); }
;                 x[i] = acc;
;                 __builtin_amdgcn_sched_barrier(0);
;             }
.LBB0_221:
	s_or_saveexec_b64 s[90:91], s[90:91]
	s_nop 0
	v_mov_b64_e32 v[2:3], s[18:19]
	s_xor_b64 exec, exec, s[90:91]
	s_cbranch_execz .LBB0_208
	ds_read_b32 v2, v154 offset:52224
	ds_read_b32 v3, v154 offset:53264
	ds_read_b32 v4, v154 offset:54304
	ds_read_b32 v5, v154 offset:55344
	ds_read_b32 v6, v154 offset:56384
	ds_read_b32 v7, v154 offset:57424
	ds_read_b32 v8, v154 offset:58464
	ds_read_b32 v9, v154 offset:59504
	ds_read_b32 v10, v154 offset:60544
	ds_read_b32 v11, v154 offset:61584
	ds_read_b32 v12, v154 offset:62624
	ds_read_b32 v13, v154 offset:63664
	ds_read_b32 v14, v154 offset:64704
	ds_read_b32 v15, v155 offset:13520
	ds_read_b32 v16, v155 offset:14560
	ds_read_b32 v17, v155 offset:15600
	ds_read_b32 v18, v155 offset:16640
	ds_read_b32 v19, v155 offset:17680
	ds_read_b32 v20, v155 offset:18720
	ds_read_b32 v21, v155 offset:19760
	ds_read_b32 v22, v155 offset:20800
	ds_read_b32 v23, v155 offset:21840
	ds_read_b32 v24, v155 offset:22880
	ds_read_b32 v25, v155 offset:23920
	ds_read_b32 v26, v155 offset:24960
	ds_read_b32 v27, v155 offset:26000
	ds_read_b32 v28, v155 offset:27040
	ds_read_b32 v29, v155 offset:28080
	ds_read_b32 v30, v155 offset:29120
	ds_read_b32 v31, v155 offset:30160
	ds_read_b32 v32, v155 offset:31200
	ds_read_b32 v33, v155 offset:32240
	ds_read_b32 v34, v155 offset:33280
	ds_read_b32 v35, v155 offset:34320
	ds_read_b32 v36, v155 offset:35360
	ds_read_b32 v37, v155 offset:36400
	ds_read_b32 v38, v155 offset:37440
	ds_read_b32 v39, v155 offset:38480
	ds_read_b32 v40, v155 offset:39520
	ds_read_b32 v41, v155 offset:40560
	ds_read_b32 v42, v155 offset:41600
	ds_read_b32 v43, v155 offset:42640
	ds_read_b32 v44, v155 offset:43680
	ds_read_b32 v45, v155 offset:44720
	ds_read_b32 v46, v155 offset:45760
	ds_read_b32 v47, v155 offset:46800
	ds_read_b32 v48, v155 offset:47840
	ds_read_b32 v49, v155 offset:48880
	ds_read_b32 v50, v155 offset:49920
	ds_read_b32 v51, v155 offset:50960
	ds_read_b32 v52, v155 offset:52000
	ds_read_b32 v53, v155 offset:53040
	ds_read_b32 v54, v155 offset:54080
	ds_read_b32 v55, v155 offset:55120
	ds_read_b32 v56, v155 offset:56160
	ds_read_b32 v57, v155 offset:57200
	ds_read_b32 v58, v155 offset:58240
	ds_read_b32 v59, v155 offset:59280
	ds_read_b32 v60, v155 offset:60320
	ds_read_b32 v61, v155 offset:61360
	ds_read_b32 v62, v155 offset:62400
	ds_read_b32 v63, v155 offset:63440
	ds_read_b32 v64, v155 offset:64480
	ds_read_b32 v65, v155 offset:65520
	s_waitcnt lgkmcnt(0)
	ds_read_b128 v[66:69], v1 offset:35088
	ds_read_b128 v[70:73], v1 offset:35360
	ds_read_b128 v[74:77], v1 offset:35632
	ds_read_b128 v[78:81], v1 offset:35904
	ds_read_b128 v[82:85], v1 offset:36176
	ds_read_b128 v[86:89], v1 offset:36192
	ds_read_b128 v[116:119], v1 offset:36448
	ds_read_b128 v[120:123], v1 offset:36464
	ds_read_b128 v[124:127], v1 offset:36720
	ds_read_b128 v[128:131], v1 offset:36736
	ds_read_b128 v[132:135], v1 offset:36992
	ds_read_b128 v[136:139], v1 offset:37008
	ds_read_b128 v[140:143], v1 offset:37264
	ds_read_b128 v[200:203], v1 offset:37280
	ds_read_b128 v[204:207], v1 offset:37296
	s_waitcnt lgkmcnt(14)
	v_pk_mul_f32 v[242:243], v[2:3], v[66:67] neg_lo:[1,0] neg_hi:[1,0]
	v_pk_mul_f32 v[244:245], v[4:5], v[68:69] neg_lo:[1,0] neg_hi:[1,0]
	ds_read_b128 v[246:249], v1 offset:37536
	s_nop 0
	v_pk_add_f32 v[242:243], v[242:243], v[244:245]
	s_nop 0
	v_add_f32_e32 v242, v242, v243
	v_add_f32_e32 v3, v3, v242
	s_waitcnt lgkmcnt(14)
	v_pk_mul_f32 v[242:243], v[2:3], v[70:71] neg_lo:[1,0] neg_hi:[1,0]
	v_pk_mul_f32 v[244:245], v[4:5], v[72:73] neg_lo:[1,0] neg_hi:[1,0]
	ds_read_b128 v[66:69], v1 offset:37552
	s_nop 0
	v_pk_add_f32 v[242:243], v[242:243], v[244:245]
	s_nop 0
	v_add_f32_e32 v242, v242, v243
	v_add_f32_e32 v4, v4, v242
	s_waitcnt lgkmcnt(14)
	v_pk_mul_f32 v[242:243], v[2:3], v[74:75] neg_lo:[1,0] neg_hi:[1,0]
	v_pk_mul_f32 v[244:245], v[4:5], v[76:77] neg_lo:[1,0] neg_hi:[1,0]
	ds_read_b128 v[70:73], v1 offset:37568
	s_nop 0
	v_pk_add_f32 v[242:243], v[242:243], v[244:245]
	s_nop 0
	v_add_f32_e32 v242, v242, v243
	v_add_f32_e32 v5, v5, v242
	s_waitcnt lgkmcnt(14)
	v_pk_mul_f32 v[242:243], v[2:3], v[78:79] neg_lo:[1,0] neg_hi:[1,0]
	v_pk_mul_f32 v[244:245], v[4:5], v[80:81] neg_lo:[1,0] neg_hi:[1,0]
	ds_read_b128 v[74:77], v1 offset:37808
	s_nop 0
	v_pk_add_f32 v[242:243], v[242:243], v[244:245]
	s_nop 0
	v_add_f32_e32 v242, v242, v243
	v_add_f32_e32 v6, v6, v242
	s_waitcnt lgkmcnt(14)
	v_pk_mul_f32 v[242:243], v[2:3], v[82:83] neg_lo:[1,0] neg_hi:[1,0]
	v_pk_mul_f32 v[244:245], v[4:5], v[84:85] neg_lo:[1,0] neg_hi:[1,0]
	ds_read_b128 v[78:81], v1 offset:37824
	s_waitcnt lgkmcnt(14)
	v_pk_fma_f32 v[242:243], v[6:7], v[86:87], v[242:243] neg_lo:[1,0,0] neg_hi:[1,0,0]
	v_pk_fma_f32 v[244:245], v[8:9], v[88:89], v[244:245] neg_lo:[1,0,0] neg_hi:[1,0,0]
	ds_read_b128 v[82:85], v1 offset:37840
	s_nop 0
	v_pk_add_f32 v[242:243], v[242:243], v[244:245]
	s_nop 0
	v_add_f32_e32 v242, v242, v243
	v_add_f32_e32 v7, v7, v242
	s_waitcnt lgkmcnt(14)
	v_pk_mul_f32 v[242:243], v[2:3], v[116:117] neg_lo:[1,0] neg_hi:[1,0]
	v_pk_mul_f32 v[244:245], v[4:5], v[118:119] neg_lo:[1,0] neg_hi:[1,0]
	ds_read_b128 v[86:89], v1 offset:38080
	s_waitcnt lgkmcnt(14)
	v_pk_fma_f32 v[242:243], v[6:7], v[120:121], v[242:243] neg_lo:[1,0,0] neg_hi:[1,0,0]
	v_pk_fma_f32 v[244:245], v[8:9], v[122:123], v[244:245] neg_lo:[1,0,0] neg_hi:[1,0,0]
	ds_read_b128 v[116:119], v1 offset:38096
	s_nop 0
	v_pk_add_f32 v[242:243], v[242:243], v[244:245]
	s_nop 0
	v_add_f32_e32 v242, v242, v243
	v_add_f32_e32 v8, v8, v242
	s_waitcnt lgkmcnt(14)
; #define SUB_LROW(buf, i_, j0_, n_) do { _Pragma("unroll") for (int j4 = 0; j4 < (n_); ++j4) buf[j4] = *(const f32x4*)(Ls + (i_) * 68 + 4 * ((j0_) + j4)); } while (0)
; #define SUB_FROW(buf, j0_, n_) do { _Pragma("unroll") for (int j4 = 0; j4 < (n_); ++j4) { const f32x4 l = buf[j4]; \
;                 acc -= l.x * x[4 * ((j0_) + j4)]; acc -= l.y * x[4 * ((j0_) + j4) + 1]; acc -= l.z * x[4 * ((j0_) + j4) + 2]; acc -= l.w * x[4 * ((j0_) + j4) + 3]; } } while (0)
; __device__ __forceinline__ void gdn_prep(KA a, int layer, unsigned char* lds, const int tid_, const int bid_) {
;     ...
; #pragma unroll
;             for (int j4 = 0; j4 < 8; ++j4) { bufA[j4] = (f32x4){0.f, 0.f, 0.f, 0.f}; bufB[j4] = (f32x4){0.f, 0.f, 0.f, 0.f}; }
;             SUB_LROW(bufA, 1, 0, 1);
; #pragma unroll
;             for (int i = 1; i <= 32; ++i) {
;                 const int nn = (i + 4) / 4 < 8 ? (i + 4) / 4 : 8;
;                 float acc = x[i];
;                 if (i & 1) { SUB_LROW(bufB, i + 1, 0, nn); __builtin_amdgcn_sched_barrier(0); SUB_FROW(bufA, 0, (i + 3) / 4); }
;                 else       { SUB_LROW(bufA, i + 1, 0, nn); __builtin_amdgcn_sched_barrier(0); SUB_FROW(bufB, 0, (i + 3) / 4); }
;                 x[i] = acc;
;                 __builtin_amdgcn_sched_barrier(0);
;             }
	v_pk_mul_f32 v[242:243], v[2:3], v[124:125] neg_lo:[1,0] neg_hi:[1,0]
	v_pk_mul_f32 v[244:245], v[4:5], v[126:127] neg_lo:[1,0] neg_hi:[1,0]
	ds_read_b128 v[120:123], v1 offset:38112
	s_waitcnt lgkmcnt(14)
	v_pk_fma_f32 v[242:243], v[6:7], v[128:129], v[242:243] neg_lo:[1,0,0] neg_hi:[1,0,0]
	v_pk_fma_f32 v[244:245], v[8:9], v[130:131], v[244:245] neg_lo:[1,0,0] neg_hi:[1,0,0]
	ds_read_b128 v[124:127], v1 offset:38352
	s_nop 0
	v_pk_add_f32 v[242:243], v[242:243], v[244:245]
	s_nop 0
	v_add_f32_e32 v242, v242, v243
	v_add_f32_e32 v9, v9, v242
	s_waitcnt lgkmcnt(14)
	v_pk_mul_f32 v[242:243], v[2:3], v[132:133] neg_lo:[1,0] neg_hi:[1,0]
	v_pk_mul_f32 v[244:245], v[4:5], v[134:135] neg_lo:[1,0] neg_hi:[1,0]
	ds_read_b128 v[128:131], v1 offset:38368
	s_waitcnt lgkmcnt(14)
	v_pk_fma_f32 v[242:243], v[6:7], v[136:137], v[242:243] neg_lo:[1,0,0] neg_hi:[1,0,0]
	v_pk_fma_f32 v[244:245], v[8:9], v[138:139], v[244:245] neg_lo:[1,0,0] neg_hi:[1,0,0]
	ds_read_b128 v[132:135], v1 offset:38384
	s_nop 0
	v_pk_add_f32 v[242:243], v[242:243], v[244:245]
	s_nop 0
	v_add_f32_e32 v242, v242, v243
	v_add_f32_e32 v10, v10, v242
	s_waitcnt lgkmcnt(14)
	v_pk_mul_f32 v[242:243], v[2:3], v[140:141] neg_lo:[1,0] neg_hi:[1,0]
	v_pk_mul_f32 v[244:245], v[4:5], v[142:143] neg_lo:[1,0] neg_hi:[1,0]
	ds_read_b128 v[136:139], v1 offset:38400
	s_waitcnt lgkmcnt(14)
	v_pk_fma_f32 v[242:243], v[6:7], v[200:201], v[242:243] neg_lo:[1,0,0] neg_hi:[1,0,0]
	v_pk_fma_f32 v[244:245], v[8:9], v[202:203], v[244:245] neg_lo:[1,0,0] neg_hi:[1,0,0]
	ds_read_b128 v[140:143], v1 offset:38624
	s_waitcnt lgkmcnt(14)
	v_pk_fma_f32 v[242:243], v[10:11], v[204:205], v[242:243] neg_lo:[1,0,0] neg_hi:[1,0,0]
	v_pk_fma_f32 v[244:245], v[12:13], v[206:207], v[244:245] neg_lo:[1,0,0] neg_hi:[1,0,0]
	ds_read_b128 v[200:203], v1 offset:38640
	s_nop 0
	v_pk_add_f32 v[242:243], v[242:243], v[244:245]
	s_nop 0
	v_add_f32_e32 v242, v242, v243
	v_add_f32_e32 v11, v11, v242
	s_waitcnt lgkmcnt(14)
	v_pk_mul_f32 v[242:243], v[2:3], v[246:247] neg_lo:[1,0] neg_hi:[1,0]
	v_pk_mul_f32 v[244:245], v[4:5], v[248:249] neg_lo:[1,0] neg_hi:[1,0]
	ds_read_b128 v[204:207], v1 offset:38656
	s_waitcnt lgkmcnt(14)
	v_pk_fma_f32 v[242:243], v[6:7], v[66:67], v[242:243] neg_lo:[1,0,0] neg_hi:[1,0,0]
	v_pk_fma_f32 v[244:245], v[8:9], v[68:69], v[244:245] neg_lo:[1,0,0] neg_hi:[1,0,0]
	ds_read_b128 v[246:249], v1 offset:38672
	s_waitcnt lgkmcnt(14)
	v_pk_fma_f32 v[242:243], v[10:11], v[70:71], v[242:243] neg_lo:[1,0,0] neg_hi:[1,0,0]
	v_pk_fma_f32 v[244:245], v[12:13], v[72:73], v[244:245] neg_lo:[1,0,0] neg_hi:[1,0,0]
	ds_read_b128 v[66:69], v1 offset:38896
	s_nop 0
	v_pk_add_f32 v[242:243], v[242:243], v[244:245]
	s_nop 0
	v_add_f32_e32 v242, v242, v243
	v_add_f32_e32 v12, v12, v242
	s_waitcnt lgkmcnt(14)
	v_pk_mul_f32 v[242:243], v[2:3], v[74:75] neg_lo:[1,0] neg_hi:[1,0]
	v_pk_mul_f32 v[244:245], v[4:5], v[76:77] neg_lo:[1,0] neg_hi:[1,0]
	ds_read_b128 v[70:73], v1 offset:38912
	s_waitcnt lgkmcnt(14)
	v_pk_fma_f32 v[242:243], v[6:7], v[78:79], v[242:243] neg_lo:[1,0,0] neg_hi:[1,0,0]
	v_pk_fma_f32 v[244:245], v[8:9], v[80:81], v[244:245] neg_lo:[1,0,0] neg_hi:[1,0,0]
	ds_read_b128 v[74:77], v1 offset:38928
	s_waitcnt lgkmcnt(14)
	v_pk_fma_f32 v[242:243], v[10:11], v[82:83], v[242:243] neg_lo:[1,0,0] neg_hi:[1,0,0]
	v_pk_fma_f32 v[244:245], v[12:13], v[84:85], v[244:245] neg_lo:[1,0,0] neg_hi:[1,0,0]
	ds_read_b128 v[78:81], v1 offset:38944
	s_nop 0
	v_pk_add_f32 v[242:243], v[242:243], v[244:245]
	s_nop 0
	v_add_f32_e32 v242, v242, v243
	v_add_f32_e32 v13, v13, v242
	s_waitcnt lgkmcnt(14)
	v_pk_mul_f32 v[242:243], v[2:3], v[86:87] neg_lo:[1,0] neg_hi:[1,0]
	v_pk_mul_f32 v[244:245], v[4:5], v[88:89] neg_lo:[1,0] neg_hi:[1,0]
	ds_read_b128 v[82:85], v1 offset:39168
	s_waitcnt lgkmcnt(14)
	v_pk_fma_f32 v[242:243], v[6:7], v[116:117], v[242:243] neg_lo:[1,0,0] neg_hi:[1,0,0]
	v_pk_fma_f32 v[244:245], v[8:9], v[118:119], v[244:245] neg_lo:[1,0,0] neg_hi:[1,0,0]
	ds_read_b128 v[86:89], v1 offset:39184
	s_waitcnt lgkmcnt(14)
	v_pk_fma_f32 v[242:243], v[10:11], v[120:121], v[242:243] neg_lo:[1,0,0] neg_hi:[1,0,0]
	v_pk_fma_f32 v[244:245], v[12:13], v[122:123], v[244:245] neg_lo:[1,0,0] neg_hi:[1,0,0]
	ds_read_b128 v[116:119], v1 offset:39200
	s_nop 0
	v_pk_add_f32 v[242:243], v[242:243], v[244:245]
	s_nop 0
	v_add_f32_e32 v242, v242, v243
	v_add_f32_e32 v14, v14, v242
	s_waitcnt lgkmcnt(14)
	v_pk_mul_f32 v[242:243], v[2:3], v[124:125] neg_lo:[1,0] neg_hi:[1,0]
	v_pk_mul_f32 v[244:245], v[4:5], v[126:127] neg_lo:[1,0] neg_hi:[1,0]
	ds_read_b128 v[120:123], v1 offset:39216
	s_waitcnt lgkmcnt(14)
	v_pk_fma_f32 v[242:243], v[6:7], v[128:129], v[242:243] neg_lo:[1,0,0] neg_hi:[1,0,0]
	v_pk_fma_f32 v[244:245], v[8:9], v[130:131], v[244:245] neg_lo:[1,0,0] neg_hi:[1,0,0]
	ds_read_b128 v[124:127], v1 offset:39440
	s_waitcnt lgkmcnt(14)
	v_pk_fma_f32 v[242:243], v[10:11], v[132:133], v[242:243] neg_lo:[1,0,0] neg_hi:[1,0,0]
	v_pk_fma_f32 v[244:245], v[12:13], v[134:135], v[244:245] neg_lo:[1,0,0] neg_hi:[1,0,0]
	ds_read_b128 v[128:131], v1 offset:39456
	s_waitcnt lgkmcnt(14)
	v_pk_fma_f32 v[242:243], v[14:15], v[136:137], v[242:243] neg_lo:[1,0,0] neg_hi:[1,0,0]
	v_pk_fma_f32 v[244:245], v[16:17], v[138:139], v[244:245] neg_lo:[1,0,0] neg_hi:[1,0,0]
	ds_read_b128 v[132:135], v1 offset:39472
	s_nop 0
	v_pk_add_f32 v[242:243], v[242:243], v[244:245]
	s_nop 0
	v_add_f32_e32 v242, v242, v243
	v_add_f32_e32 v15, v15, v242
	s_waitcnt lgkmcnt(14)
	v_pk_mul_f32 v[242:243], v[2:3], v[140:141] neg_lo:[1,0] neg_hi:[1,0]
	v_pk_mul_f32 v[244:245], v[4:5], v[142:143] neg_lo:[1,0] neg_hi:[1,0]
	ds_read_b128 v[136:139], v1 offset:39488
	s_waitcnt lgkmcnt(14)
; #define SUB_LROW(buf, i_, j0_, n_) do { _Pragma("unroll") for (int j4 = 0; j4 < (n_); ++j4) buf[j4] = *(const f32x4*)(Ls + (i_) * 68 + 4 * ((j0_) + j4)); } while (0)
; #define SUB_FROW(buf, j0_, n_) do { _Pragma("unroll") for (int j4 = 0; j4 < (n_); ++j4) { const f32x4 l = buf[j4]; \
;                 acc -= l.x * x[4 * ((j0_) + j4)]; acc -= l.y * x[4 * ((j0_) + j4) + 1]; acc -= l.z * x[4 * ((j0_) + j4) + 2]; acc -= l.w * x[4 * ((j0_) + j4) + 3]; } } while (0)
; __device__ __forceinline__ void gdn_prep(KA a, int layer, unsigned char* lds, const int tid_, const int bid_) {
;     ...
; #pragma unroll
;             for (int j4 = 0; j4 < 8; ++j4) { bufA[j4] = (f32x4){0.f, 0.f, 0.f, 0.f}; bufB[j4] = (f32x4){0.f, 0.f, 0.f, 0.f}; }
;             SUB_LROW(bufA, 1, 0, 1);
; #pragma unroll
;             for (int i = 1; i <= 32; ++i) {
;                 const int nn = (i + 4) / 4 < 8 ? (i + 4) / 4 : 8;
;                 float acc = x[i];
;                 if (i & 1) { SUB_LROW(bufB, i + 1, 0, nn); __builtin_amdgcn_sched_barrier(0); SUB_FROW(bufA, 0, (i + 3) / 4); }
;                 else       { SUB_LROW(bufA, i + 1, 0, nn); __builtin_amdgcn_sched_barrier(0); SUB_FROW(bufB, 0, (i + 3) / 4); }
;                 x[i] = acc;
;                 __builtin_amdgcn_sched_barrier(0);
;             }
	v_pk_fma_f32 v[242:243], v[6:7], v[200:201], v[242:243] neg_lo:[1,0,0] neg_hi:[1,0,0]
	v_pk_fma_f32 v[244:245], v[8:9], v[202:203], v[244:245] neg_lo:[1,0,0] neg_hi:[1,0,0]
	ds_read_b128 v[140:143], v1 offset:39504
	s_waitcnt lgkmcnt(14)
	v_pk_fma_f32 v[242:243], v[10:11], v[204:205], v[242:243] neg_lo:[1,0,0] neg_hi:[1,0,0]
	v_pk_fma_f32 v[244:245], v[12:13], v[206:207], v[244:245] neg_lo:[1,0,0] neg_hi:[1,0,0]
	ds_read_b128 v[200:203], v1 offset:39712
	s_waitcnt lgkmcnt(14)
	v_pk_fma_f32 v[242:243], v[14:15], v[246:247], v[242:243] neg_lo:[1,0,0] neg_hi:[1,0,0]
	v_pk_fma_f32 v[244:245], v[16:17], v[248:249], v[244:245] neg_lo:[1,0,0] neg_hi:[1,0,0]
	ds_read_b128 v[204:207], v1 offset:39728
	s_nop 0
	v_pk_add_f32 v[242:243], v[242:243], v[244:245]
	s_nop 0
	v_add_f32_e32 v242, v242, v243
	v_add_f32_e32 v16, v16, v242
	s_waitcnt lgkmcnt(14)
	v_pk_mul_f32 v[242:243], v[2:3], v[66:67] neg_lo:[1,0] neg_hi:[1,0]
	v_pk_mul_f32 v[244:245], v[4:5], v[68:69] neg_lo:[1,0] neg_hi:[1,0]
	ds_read_b128 v[246:249], v1 offset:39744
	s_waitcnt lgkmcnt(14)
	v_pk_fma_f32 v[242:243], v[6:7], v[70:71], v[242:243] neg_lo:[1,0,0] neg_hi:[1,0,0]
	v_pk_fma_f32 v[244:245], v[8:9], v[72:73], v[244:245] neg_lo:[1,0,0] neg_hi:[1,0,0]
	ds_read_b128 v[66:69], v1 offset:39760
	s_waitcnt lgkmcnt(14)
	v_pk_fma_f32 v[242:243], v[10:11], v[74:75], v[242:243] neg_lo:[1,0,0] neg_hi:[1,0,0]
	v_pk_fma_f32 v[244:245], v[12:13], v[76:77], v[244:245] neg_lo:[1,0,0] neg_hi:[1,0,0]
	ds_read_b128 v[70:73], v1 offset:39776
	s_waitcnt lgkmcnt(14)
	v_pk_fma_f32 v[242:243], v[14:15], v[78:79], v[242:243] neg_lo:[1,0,0] neg_hi:[1,0,0]
	v_pk_fma_f32 v[244:245], v[16:17], v[80:81], v[244:245] neg_lo:[1,0,0] neg_hi:[1,0,0]
	ds_read_b128 v[74:77], v1 offset:39984
	s_nop 0
	v_pk_add_f32 v[242:243], v[242:243], v[244:245]
	s_nop 0
	v_add_f32_e32 v242, v242, v243
	v_add_f32_e32 v17, v17, v242
	s_waitcnt lgkmcnt(14)
	v_pk_mul_f32 v[242:243], v[2:3], v[82:83] neg_lo:[1,0] neg_hi:[1,0]
	v_pk_mul_f32 v[244:245], v[4:5], v[84:85] neg_lo:[1,0] neg_hi:[1,0]
	ds_read_b128 v[78:81], v1 offset:40000
	s_waitcnt lgkmcnt(14)
	v_pk_fma_f32 v[242:243], v[6:7], v[86:87], v[242:243] neg_lo:[1,0,0] neg_hi:[1,0,0]
	v_pk_fma_f32 v[244:245], v[8:9], v[88:89], v[244:245] neg_lo:[1,0,0] neg_hi:[1,0,0]
	ds_read_b128 v[82:85], v1 offset:40016
	s_waitcnt lgkmcnt(14)
	v_pk_fma_f32 v[242:243], v[10:11], v[116:117], v[242:243] neg_lo:[1,0,0] neg_hi:[1,0,0]
	v_pk_fma_f32 v[244:245], v[12:13], v[118:119], v[244:245] neg_lo:[1,0,0] neg_hi:[1,0,0]
	ds_read_b128 v[86:89], v1 offset:40032
	s_waitcnt lgkmcnt(14)
	v_pk_fma_f32 v[242:243], v[14:15], v[120:121], v[242:243] neg_lo:[1,0,0] neg_hi:[1,0,0]
	v_pk_fma_f32 v[244:245], v[16:17], v[122:123], v[244:245] neg_lo:[1,0,0] neg_hi:[1,0,0]
	ds_read_b128 v[116:119], v1 offset:40048
	s_nop 0
	v_pk_add_f32 v[242:243], v[242:243], v[244:245]
	s_nop 0
	v_add_f32_e32 v242, v242, v243
	v_add_f32_e32 v18, v18, v242
	s_waitcnt lgkmcnt(14)
	v_pk_mul_f32 v[242:243], v[2:3], v[124:125] neg_lo:[1,0] neg_hi:[1,0]
	v_pk_mul_f32 v[244:245], v[4:5], v[126:127] neg_lo:[1,0] neg_hi:[1,0]
	ds_read_b128 v[120:123], v1 offset:40256
	s_waitcnt lgkmcnt(14)
	v_pk_fma_f32 v[242:243], v[6:7], v[128:129], v[242:243] neg_lo:[1,0,0] neg_hi:[1,0,0]
	v_pk_fma_f32 v[244:245], v[8:9], v[130:131], v[244:245] neg_lo:[1,0,0] neg_hi:[1,0,0]
	ds_read_b128 v[124:127], v1 offset:40272
	s_waitcnt lgkmcnt(14)
	v_pk_fma_f32 v[242:243], v[10:11], v[132:133], v[242:243] neg_lo:[1,0,0] neg_hi:[1,0,0]
	v_pk_fma_f32 v[244:245], v[12:13], v[134:135], v[244:245] neg_lo:[1,0,0] neg_hi:[1,0,0]
	ds_read_b128 v[128:131], v1 offset:40288
	s_waitcnt lgkmcnt(14)
	v_pk_fma_f32 v[242:243], v[14:15], v[136:137], v[242:243] neg_lo:[1,0,0] neg_hi:[1,0,0]
	v_pk_fma_f32 v[244:245], v[16:17], v[138:139], v[244:245] neg_lo:[1,0,0] neg_hi:[1,0,0]
	ds_read_b128 v[132:135], v1 offset:40304
	s_waitcnt lgkmcnt(14)
	v_pk_fma_f32 v[242:243], v[18:19], v[140:141], v[242:243] neg_lo:[1,0,0] neg_hi:[1,0,0]
	v_pk_fma_f32 v[244:245], v[20:21], v[142:143], v[244:245] neg_lo:[1,0,0] neg_hi:[1,0,0]
	ds_read_b128 v[136:139], v1 offset:40320
	s_nop 0
	v_pk_add_f32 v[242:243], v[242:243], v[244:245]
	s_nop 0
	v_add_f32_e32 v242, v242, v243
	v_add_f32_e32 v19, v19, v242
	s_waitcnt lgkmcnt(14)
	v_pk_mul_f32 v[242:243], v[2:3], v[200:201] neg_lo:[1,0] neg_hi:[1,0]
	v_pk_mul_f32 v[244:245], v[4:5], v[202:203] neg_lo:[1,0] neg_hi:[1,0]
	ds_read_b128 v[140:143], v1 offset:40528
	s_waitcnt lgkmcnt(14)
	v_pk_fma_f32 v[242:243], v[6:7], v[204:205], v[242:243] neg_lo:[1,0,0] neg_hi:[1,0,0]
	v_pk_fma_f32 v[244:245], v[8:9], v[206:207], v[244:245] neg_lo:[1,0,0] neg_hi:[1,0,0]
	ds_read_b128 v[200:203], v1 offset:40544
	s_waitcnt lgkmcnt(14)
	v_pk_fma_f32 v[242:243], v[10:11], v[246:247], v[242:243] neg_lo:[1,0,0] neg_hi:[1,0,0]
	v_pk_fma_f32 v[244:245], v[12:13], v[248:249], v[244:245] neg_lo:[1,0,0] neg_hi:[1,0,0]
	ds_read_b128 v[204:207], v1 offset:40560
	s_waitcnt lgkmcnt(14)
	v_pk_fma_f32 v[242:243], v[14:15], v[66:67], v[242:243] neg_lo:[1,0,0] neg_hi:[1,0,0]
	v_pk_fma_f32 v[244:245], v[16:17], v[68:69], v[244:245] neg_lo:[1,0,0] neg_hi:[1,0,0]
	ds_read_b128 v[246:249], v1 offset:40576
	s_waitcnt lgkmcnt(14)
	v_pk_fma_f32 v[242:243], v[18:19], v[70:71], v[242:243] neg_lo:[1,0,0] neg_hi:[1,0,0]
	v_pk_fma_f32 v[244:245], v[20:21], v[72:73], v[244:245] neg_lo:[1,0,0] neg_hi:[1,0,0]
	ds_read_b128 v[66:69], v1 offset:40592
	s_nop 0
	v_pk_add_f32 v[242:243], v[242:243], v[244:245]
	s_nop 0
	v_add_f32_e32 v242, v242, v243
	v_add_f32_e32 v20, v20, v242
	s_waitcnt lgkmcnt(14)
	v_pk_mul_f32 v[242:243], v[2:3], v[74:75] neg_lo:[1,0] neg_hi:[1,0]
	v_pk_mul_f32 v[244:245], v[4:5], v[76:77] neg_lo:[1,0] neg_hi:[1,0]
	ds_read_b128 v[70:73], v1 offset:40608
	s_waitcnt lgkmcnt(14)
; #define SUB_LROW(buf, i_, j0_, n_) do { _Pragma("unroll") for (int j4 = 0; j4 < (n_); ++j4) buf[j4] = *(const f32x4*)(Ls + (i_) * 68 + 4 * ((j0_) + j4)); } while (0)
; #define SUB_FROW(buf, j0_, n_) do { _Pragma("unroll") for (int j4 = 0; j4 < (n_); ++j4) { const f32x4 l = buf[j4]; \
;                 acc -= l.x * x[4 * ((j0_) + j4)]; acc -= l.y * x[4 * ((j0_) + j4) + 1]; acc -= l.z * x[4 * ((j0_) + j4) + 2]; acc -= l.w * x[4 * ((j0_) + j4) + 3]; } } while (0)
; __device__ __forceinline__ void gdn_prep(KA a, int layer, unsigned char* lds, const int tid_, const int bid_) {
;     ...
; #pragma unroll
;             for (int j4 = 0; j4 < 8; ++j4) { bufA[j4] = (f32x4){0.f, 0.f, 0.f, 0.f}; bufB[j4] = (f32x4){0.f, 0.f, 0.f, 0.f}; }
;             SUB_LROW(bufA, 1, 0, 1);
; #pragma unroll
;             for (int i = 1; i <= 32; ++i) {
;                 const int nn = (i + 4) / 4 < 8 ? (i + 4) / 4 : 8;
;                 float acc = x[i];
;                 if (i & 1) { SUB_LROW(bufB, i + 1, 0, nn); __builtin_amdgcn_sched_barrier(0); SUB_FROW(bufA, 0, (i + 3) / 4); }
;                 else       { SUB_LROW(bufA, i + 1, 0, nn); __builtin_amdgcn_sched_barrier(0); SUB_FROW(bufB, 0, (i + 3) / 4); }
;                 x[i] = acc;
;                 __builtin_amdgcn_sched_barrier(0);
;             }
	v_pk_fma_f32 v[242:243], v[6:7], v[78:79], v[242:243] neg_lo:[1,0,0] neg_hi:[1,0,0]
	v_pk_fma_f32 v[244:245], v[8:9], v[80:81], v[244:245] neg_lo:[1,0,0] neg_hi:[1,0,0]
	ds_read_b128 v[74:77], v1 offset:40800
	s_waitcnt lgkmcnt(14)
	v_pk_fma_f32 v[242:243], v[10:11], v[82:83], v[242:243] neg_lo:[1,0,0] neg_hi:[1,0,0]
	v_pk_fma_f32 v[244:245], v[12:13], v[84:85], v[244:245] neg_lo:[1,0,0] neg_hi:[1,0,0]
	ds_read_b128 v[78:81], v1 offset:40816
	s_waitcnt lgkmcnt(14)
	v_pk_fma_f32 v[242:243], v[14:15], v[86:87], v[242:243] neg_lo:[1,0,0] neg_hi:[1,0,0]
	v_pk_fma_f32 v[244:245], v[16:17], v[88:89], v[244:245] neg_lo:[1,0,0] neg_hi:[1,0,0]
	ds_read_b128 v[82:85], v1 offset:40832
	s_waitcnt lgkmcnt(14)
	v_pk_fma_f32 v[242:243], v[18:19], v[116:117], v[242:243] neg_lo:[1,0,0] neg_hi:[1,0,0]
	v_pk_fma_f32 v[244:245], v[20:21], v[118:119], v[244:245] neg_lo:[1,0,0] neg_hi:[1,0,0]
	ds_read_b128 v[86:89], v1 offset:40848
	s_nop 0
	v_pk_add_f32 v[242:243], v[242:243], v[244:245]
	s_nop 0
	v_add_f32_e32 v242, v242, v243
	v_add_f32_e32 v21, v21, v242
	s_waitcnt lgkmcnt(14)
	v_pk_mul_f32 v[242:243], v[2:3], v[120:121] neg_lo:[1,0] neg_hi:[1,0]
	v_pk_mul_f32 v[244:245], v[4:5], v[122:123] neg_lo:[1,0] neg_hi:[1,0]
	ds_read_b128 v[116:119], v1 offset:40864
	s_waitcnt lgkmcnt(14)
	v_pk_fma_f32 v[242:243], v[6:7], v[124:125], v[242:243] neg_lo:[1,0,0] neg_hi:[1,0,0]
	v_pk_fma_f32 v[244:245], v[8:9], v[126:127], v[244:245] neg_lo:[1,0,0] neg_hi:[1,0,0]
	ds_read_b128 v[120:123], v1 offset:40880
	s_waitcnt lgkmcnt(14)
	v_pk_fma_f32 v[242:243], v[10:11], v[128:129], v[242:243] neg_lo:[1,0,0] neg_hi:[1,0,0]
	v_pk_fma_f32 v[244:245], v[12:13], v[130:131], v[244:245] neg_lo:[1,0,0] neg_hi:[1,0,0]
	ds_read_b128 v[124:127], v1 offset:41072
	s_waitcnt lgkmcnt(14)
	v_pk_fma_f32 v[242:243], v[14:15], v[132:133], v[242:243] neg_lo:[1,0,0] neg_hi:[1,0,0]
	v_pk_fma_f32 v[244:245], v[16:17], v[134:135], v[244:245] neg_lo:[1,0,0] neg_hi:[1,0,0]
	ds_read_b128 v[128:131], v1 offset:41088
	s_waitcnt lgkmcnt(14)
	v_pk_fma_f32 v[242:243], v[18:19], v[136:137], v[242:243] neg_lo:[1,0,0] neg_hi:[1,0,0]
	v_pk_fma_f32 v[244:245], v[20:21], v[138:139], v[244:245] neg_lo:[1,0,0] neg_hi:[1,0,0]
	ds_read_b128 v[132:135], v1 offset:41104
	s_nop 0
	v_pk_add_f32 v[242:243], v[242:243], v[244:245]
	s_nop 0
	v_add_f32_e32 v242, v242, v243
	v_add_f32_e32 v22, v22, v242
	s_waitcnt lgkmcnt(14)
	v_pk_mul_f32 v[242:243], v[2:3], v[140:141] neg_lo:[1,0] neg_hi:[1,0]
	v_pk_mul_f32 v[244:245], v[4:5], v[142:143] neg_lo:[1,0] neg_hi:[1,0]
	ds_read_b128 v[136:139], v1 offset:41120
	s_waitcnt lgkmcnt(14)
	v_pk_fma_f32 v[242:243], v[6:7], v[200:201], v[242:243] neg_lo:[1,0,0] neg_hi:[1,0,0]
	v_pk_fma_f32 v[244:245], v[8:9], v[202:203], v[244:245] neg_lo:[1,0,0] neg_hi:[1,0,0]
	ds_read_b128 v[140:143], v1 offset:41136
	s_waitcnt lgkmcnt(14)
	v_pk_fma_f32 v[242:243], v[10:11], v[204:205], v[242:243] neg_lo:[1,0,0] neg_hi:[1,0,0]
	v_pk_fma_f32 v[244:245], v[12:13], v[206:207], v[244:245] neg_lo:[1,0,0] neg_hi:[1,0,0]
	ds_read_b128 v[200:203], v1 offset:41152
	s_waitcnt lgkmcnt(14)
	v_pk_fma_f32 v[242:243], v[14:15], v[246:247], v[242:243] neg_lo:[1,0,0] neg_hi:[1,0,0]
	v_pk_fma_f32 v[244:245], v[16:17], v[248:249], v[244:245] neg_lo:[1,0,0] neg_hi:[1,0,0]
	ds_read_b128 v[204:207], v1 offset:41344
	s_waitcnt lgkmcnt(14)
	v_pk_fma_f32 v[242:243], v[18:19], v[66:67], v[242:243] neg_lo:[1,0,0] neg_hi:[1,0,0]
	v_pk_fma_f32 v[244:245], v[20:21], v[68:69], v[244:245] neg_lo:[1,0,0] neg_hi:[1,0,0]
	ds_read_b128 v[246:249], v1 offset:41360
	s_waitcnt lgkmcnt(14)
	v_pk_fma_f32 v[242:243], v[22:23], v[70:71], v[242:243] neg_lo:[1,0,0] neg_hi:[1,0,0]
	v_pk_fma_f32 v[244:245], v[24:25], v[72:73], v[244:245] neg_lo:[1,0,0] neg_hi:[1,0,0]
	ds_read_b128 v[66:69], v1 offset:41376
	s_nop 0
	v_pk_add_f32 v[242:243], v[242:243], v[244:245]
	s_nop 0
	v_add_f32_e32 v242, v242, v243
	v_add_f32_e32 v23, v23, v242
	s_waitcnt lgkmcnt(14)
	v_pk_mul_f32 v[242:243], v[2:3], v[74:75] neg_lo:[1,0] neg_hi:[1,0]
	v_pk_mul_f32 v[244:245], v[4:5], v[76:77] neg_lo:[1,0] neg_hi:[1,0]
	ds_read_b128 v[70:73], v1 offset:41392
	s_waitcnt lgkmcnt(14)
	v_pk_fma_f32 v[242:243], v[6:7], v[78:79], v[242:243] neg_lo:[1,0,0] neg_hi:[1,0,0]
	v_pk_fma_f32 v[244:245], v[8:9], v[80:81], v[244:245] neg_lo:[1,0,0] neg_hi:[1,0,0]
	ds_read_b128 v[74:77], v1 offset:41408
	s_waitcnt lgkmcnt(14)
	v_pk_fma_f32 v[242:243], v[10:11], v[82:83], v[242:243] neg_lo:[1,0,0] neg_hi:[1,0,0]
	v_pk_fma_f32 v[244:245], v[12:13], v[84:85], v[244:245] neg_lo:[1,0,0] neg_hi:[1,0,0]
	ds_read_b128 v[78:81], v1 offset:41424
	s_waitcnt lgkmcnt(14)
	v_pk_fma_f32 v[242:243], v[14:15], v[86:87], v[242:243] neg_lo:[1,0,0] neg_hi:[1,0,0]
	v_pk_fma_f32 v[244:245], v[16:17], v[88:89], v[244:245] neg_lo:[1,0,0] neg_hi:[1,0,0]
	ds_read_b128 v[82:85], v1 offset:41616
	s_waitcnt lgkmcnt(14)
	v_pk_fma_f32 v[242:243], v[18:19], v[116:117], v[242:243] neg_lo:[1,0,0] neg_hi:[1,0,0]
	v_pk_fma_f32 v[244:245], v[20:21], v[118:119], v[244:245] neg_lo:[1,0,0] neg_hi:[1,0,0]
	ds_read_b128 v[86:89], v1 offset:41632
	s_waitcnt lgkmcnt(14)
	v_pk_fma_f32 v[242:243], v[22:23], v[120:121], v[242:243] neg_lo:[1,0,0] neg_hi:[1,0,0]
	v_pk_fma_f32 v[244:245], v[24:25], v[122:123], v[244:245] neg_lo:[1,0,0] neg_hi:[1,0,0]
	ds_read_b128 v[116:119], v1 offset:41648
	s_nop 0
	v_pk_add_f32 v[242:243], v[242:243], v[244:245]
	s_nop 0
	v_add_f32_e32 v242, v242, v243
	v_add_f32_e32 v24, v24, v242
	s_waitcnt lgkmcnt(14)
	v_pk_mul_f32 v[242:243], v[2:3], v[124:125] neg_lo:[1,0] neg_hi:[1,0]
	v_pk_mul_f32 v[244:245], v[4:5], v[126:127] neg_lo:[1,0] neg_hi:[1,0]
	ds_read_b128 v[120:123], v1 offset:41664
	s_waitcnt lgkmcnt(14)
; #define SUB_LROW(buf, i_, j0_, n_) do { _Pragma("unroll") for (int j4 = 0; j4 < (n_); ++j4) buf[j4] = *(const f32x4*)(Ls + (i_) * 68 + 4 * ((j0_) + j4)); } while (0)
; #define SUB_FROW(buf, j0_, n_) do { _Pragma("unroll") for (int j4 = 0; j4 < (n_); ++j4) { const f32x4 l = buf[j4]; \
;                 acc -= l.x * x[4 * ((j0_) + j4)]; acc -= l.y * x[4 * ((j0_) + j4) + 1]; acc -= l.z * x[4 * ((j0_) + j4) + 2]; acc -= l.w * x[4 * ((j0_) + j4) + 3]; } } while (0)
; __device__ __forceinline__ void gdn_prep(KA a, int layer, unsigned char* lds, const int tid_, const int bid_) {
;     ...
; #pragma unroll
;             for (int j4 = 0; j4 < 8; ++j4) { bufA[j4] = (f32x4){0.f, 0.f, 0.f, 0.f}; bufB[j4] = (f32x4){0.f, 0.f, 0.f, 0.f}; }
;             SUB_LROW(bufA, 1, 0, 1);
; #pragma unroll
;             for (int i = 1; i <= 32; ++i) {
;                 const int nn = (i + 4) / 4 < 8 ? (i + 4) / 4 : 8;
;                 float acc = x[i];
;                 if (i & 1) { SUB_LROW(bufB, i + 1, 0, nn); __builtin_amdgcn_sched_barrier(0); SUB_FROW(bufA, 0, (i + 3) / 4); }
;                 else       { SUB_LROW(bufA, i + 1, 0, nn); __builtin_amdgcn_sched_barrier(0); SUB_FROW(bufB, 0, (i + 3) / 4); }
;                 x[i] = acc;
;                 __builtin_amdgcn_sched_barrier(0);
;             }
	v_pk_fma_f32 v[242:243], v[6:7], v[128:129], v[242:243] neg_lo:[1,0,0] neg_hi:[1,0,0]
	v_pk_fma_f32 v[244:245], v[8:9], v[130:131], v[244:245] neg_lo:[1,0,0] neg_hi:[1,0,0]
	ds_read_b128 v[124:127], v1 offset:41680
	s_waitcnt lgkmcnt(14)
	v_pk_fma_f32 v[242:243], v[10:11], v[132:133], v[242:243] neg_lo:[1,0,0] neg_hi:[1,0,0]
	v_pk_fma_f32 v[244:245], v[12:13], v[134:135], v[244:245] neg_lo:[1,0,0] neg_hi:[1,0,0]
	ds_read_b128 v[128:131], v1 offset:41696
	s_waitcnt lgkmcnt(14)
	v_pk_fma_f32 v[242:243], v[14:15], v[136:137], v[242:243] neg_lo:[1,0,0] neg_hi:[1,0,0]
	v_pk_fma_f32 v[244:245], v[16:17], v[138:139], v[244:245] neg_lo:[1,0,0] neg_hi:[1,0,0]
	ds_read_b128 v[132:135], v1 offset:41712
	s_waitcnt lgkmcnt(14)
	v_pk_fma_f32 v[242:243], v[18:19], v[140:141], v[242:243] neg_lo:[1,0,0] neg_hi:[1,0,0]
	v_pk_fma_f32 v[244:245], v[20:21], v[142:143], v[244:245] neg_lo:[1,0,0] neg_hi:[1,0,0]
	ds_read_b128 v[136:139], v1 offset:41888
	s_waitcnt lgkmcnt(14)
	v_pk_fma_f32 v[242:243], v[22:23], v[200:201], v[242:243] neg_lo:[1,0,0] neg_hi:[1,0,0]
	v_pk_fma_f32 v[244:245], v[24:25], v[202:203], v[244:245] neg_lo:[1,0,0] neg_hi:[1,0,0]
	ds_read_b128 v[140:143], v1 offset:41904
	s_nop 0
	v_pk_add_f32 v[242:243], v[242:243], v[244:245]
	s_nop 0
	v_add_f32_e32 v242, v242, v243
	v_add_f32_e32 v25, v25, v242
	s_waitcnt lgkmcnt(14)
	v_pk_mul_f32 v[242:243], v[2:3], v[204:205] neg_lo:[1,0] neg_hi:[1,0]
	v_pk_mul_f32 v[244:245], v[4:5], v[206:207] neg_lo:[1,0] neg_hi:[1,0]
	ds_read_b128 v[200:203], v1 offset:41920
	s_waitcnt lgkmcnt(14)
	v_pk_fma_f32 v[242:243], v[6:7], v[246:247], v[242:243] neg_lo:[1,0,0] neg_hi:[1,0,0]
	v_pk_fma_f32 v[244:245], v[8:9], v[248:249], v[244:245] neg_lo:[1,0,0] neg_hi:[1,0,0]
	ds_read_b128 v[204:207], v1 offset:41936
	s_waitcnt lgkmcnt(14)
	v_pk_fma_f32 v[242:243], v[10:11], v[66:67], v[242:243] neg_lo:[1,0,0] neg_hi:[1,0,0]
	v_pk_fma_f32 v[244:245], v[12:13], v[68:69], v[244:245] neg_lo:[1,0,0] neg_hi:[1,0,0]
	ds_read_b128 v[246:249], v1 offset:41952
	s_waitcnt lgkmcnt(14)
	v_pk_fma_f32 v[242:243], v[14:15], v[70:71], v[242:243] neg_lo:[1,0,0] neg_hi:[1,0,0]
	v_pk_fma_f32 v[244:245], v[16:17], v[72:73], v[244:245] neg_lo:[1,0,0] neg_hi:[1,0,0]
	ds_read_b128 v[66:69], v1 offset:41968
	s_waitcnt lgkmcnt(14)
	v_pk_fma_f32 v[242:243], v[18:19], v[74:75], v[242:243] neg_lo:[1,0,0] neg_hi:[1,0,0]
	v_pk_fma_f32 v[244:245], v[20:21], v[76:77], v[244:245] neg_lo:[1,0,0] neg_hi:[1,0,0]
	ds_read_b128 v[70:73], v1 offset:41984
	s_waitcnt lgkmcnt(14)
	v_pk_fma_f32 v[242:243], v[22:23], v[78:79], v[242:243] neg_lo:[1,0,0] neg_hi:[1,0,0]
	v_pk_fma_f32 v[244:245], v[24:25], v[80:81], v[244:245] neg_lo:[1,0,0] neg_hi:[1,0,0]
	ds_read_b128 v[74:77], v1 offset:42160
	s_nop 0
	v_pk_add_f32 v[242:243], v[242:243], v[244:245]
	s_nop 0
	v_add_f32_e32 v242, v242, v243
	v_add_f32_e32 v26, v26, v242
	s_waitcnt lgkmcnt(14)
	v_pk_mul_f32 v[242:243], v[2:3], v[82:83] neg_lo:[1,0] neg_hi:[1,0]
	v_pk_mul_f32 v[244:245], v[4:5], v[84:85] neg_lo:[1,0] neg_hi:[1,0]
	ds_read_b128 v[78:81], v1 offset:42176
	s_waitcnt lgkmcnt(14)
	v_pk_fma_f32 v[242:243], v[6:7], v[86:87], v[242:243] neg_lo:[1,0,0] neg_hi:[1,0,0]
	v_pk_fma_f32 v[244:245], v[8:9], v[88:89], v[244:245] neg_lo:[1,0,0] neg_hi:[1,0,0]
	ds_read_b128 v[82:85], v1 offset:42192
	s_waitcnt lgkmcnt(14)
	v_pk_fma_f32 v[242:243], v[10:11], v[116:117], v[242:243] neg_lo:[1,0,0] neg_hi:[1,0,0]
	v_pk_fma_f32 v[244:245], v[12:13], v[118:119], v[244:245] neg_lo:[1,0,0] neg_hi:[1,0,0]
	ds_read_b128 v[86:89], v1 offset:42208
	s_waitcnt lgkmcnt(14)
	v_pk_fma_f32 v[242:243], v[14:15], v[120:121], v[242:243] neg_lo:[1,0,0] neg_hi:[1,0,0]
	v_pk_fma_f32 v[244:245], v[16:17], v[122:123], v[244:245] neg_lo:[1,0,0] neg_hi:[1,0,0]
	ds_read_b128 v[116:119], v1 offset:42224
	s_waitcnt lgkmcnt(14)
	v_pk_fma_f32 v[242:243], v[18:19], v[124:125], v[242:243] neg_lo:[1,0,0] neg_hi:[1,0,0]
	v_pk_fma_f32 v[244:245], v[20:21], v[126:127], v[244:245] neg_lo:[1,0,0] neg_hi:[1,0,0]
	ds_read_b128 v[120:123], v1 offset:42240
	s_waitcnt lgkmcnt(14)
	v_pk_fma_f32 v[242:243], v[22:23], v[128:129], v[242:243] neg_lo:[1,0,0] neg_hi:[1,0,0]
	v_pk_fma_f32 v[244:245], v[24:25], v[130:131], v[244:245] neg_lo:[1,0,0] neg_hi:[1,0,0]
	ds_read_b128 v[124:127], v1 offset:42256
	s_waitcnt lgkmcnt(14)
	v_pk_fma_f32 v[242:243], v[26:27], v[132:133], v[242:243] neg_lo:[1,0,0] neg_hi:[1,0,0]
	v_pk_fma_f32 v[244:245], v[28:29], v[134:135], v[244:245] neg_lo:[1,0,0] neg_hi:[1,0,0]
	ds_read_b128 v[128:131], v1 offset:42432
	s_nop 0
	v_pk_add_f32 v[242:243], v[242:243], v[244:245]
	s_nop 0
	v_add_f32_e32 v242, v242, v243
	v_add_f32_e32 v27, v27, v242
	s_waitcnt lgkmcnt(14)
	v_pk_mul_f32 v[242:243], v[2:3], v[136:137] neg_lo:[1,0] neg_hi:[1,0]
	v_pk_mul_f32 v[244:245], v[4:5], v[138:139] neg_lo:[1,0] neg_hi:[1,0]
	ds_read_b128 v[132:135], v1 offset:42448
	s_waitcnt lgkmcnt(14)
	v_pk_fma_f32 v[242:243], v[6:7], v[140:141], v[242:243] neg_lo:[1,0,0] neg_hi:[1,0,0]
	v_pk_fma_f32 v[244:245], v[8:9], v[142:143], v[244:245] neg_lo:[1,0,0] neg_hi:[1,0,0]
	ds_read_b128 v[136:139], v1 offset:42464
	s_waitcnt lgkmcnt(14)
	v_pk_fma_f32 v[242:243], v[10:11], v[200:201], v[242:243] neg_lo:[1,0,0] neg_hi:[1,0,0]
	v_pk_fma_f32 v[244:245], v[12:13], v[202:203], v[244:245] neg_lo:[1,0,0] neg_hi:[1,0,0]
	ds_read_b128 v[140:143], v1 offset:42480
	s_waitcnt lgkmcnt(14)
	v_pk_fma_f32 v[242:243], v[14:15], v[204:205], v[242:243] neg_lo:[1,0,0] neg_hi:[1,0,0]
	v_pk_fma_f32 v[244:245], v[16:17], v[206:207], v[244:245] neg_lo:[1,0,0] neg_hi:[1,0,0]
	ds_read_b128 v[200:203], v1 offset:42496
	s_waitcnt lgkmcnt(14)
; #define SUB_LROW(buf, i_, j0_, n_) do { _Pragma("unroll") for (int j4 = 0; j4 < (n_); ++j4) buf[j4] = *(const f32x4*)(Ls + (i_) * 68 + 4 * ((j0_) + j4)); } while (0)
; #define SUB_FROW(buf, j0_, n_) do { _Pragma("unroll") for (int j4 = 0; j4 < (n_); ++j4) { const f32x4 l = buf[j4]; \
;                 acc -= l.x * x[4 * ((j0_) + j4)]; acc -= l.y * x[4 * ((j0_) + j4) + 1]; acc -= l.z * x[4 * ((j0_) + j4) + 2]; acc -= l.w * x[4 * ((j0_) + j4) + 3]; } } while (0)
; __device__ __forceinline__ void gdn_prep(KA a, int layer, unsigned char* lds, const int tid_, const int bid_) {
;     ...
; #pragma unroll
;             for (int j4 = 0; j4 < 8; ++j4) { bufA[j4] = (f32x4){0.f, 0.f, 0.f, 0.f}; bufB[j4] = (f32x4){0.f, 0.f, 0.f, 0.f}; }
;             SUB_LROW(bufA, 1, 0, 1);
; #pragma unroll
;             for (int i = 1; i <= 32; ++i) {
;                 const int nn = (i + 4) / 4 < 8 ? (i + 4) / 4 : 8;
;                 float acc = x[i];
;                 if (i & 1) { SUB_LROW(bufB, i + 1, 0, nn); __builtin_amdgcn_sched_barrier(0); SUB_FROW(bufA, 0, (i + 3) / 4); }
;                 else       { SUB_LROW(bufA, i + 1, 0, nn); __builtin_amdgcn_sched_barrier(0); SUB_FROW(bufB, 0, (i + 3) / 4); }
;                 x[i] = acc;
;                 __builtin_amdgcn_sched_barrier(0);
;             }
	v_pk_fma_f32 v[242:243], v[18:19], v[246:247], v[242:243] neg_lo:[1,0,0] neg_hi:[1,0,0]
	v_pk_fma_f32 v[244:245], v[20:21], v[248:249], v[244:245] neg_lo:[1,0,0] neg_hi:[1,0,0]
	ds_read_b128 v[204:207], v1 offset:42512
	s_waitcnt lgkmcnt(14)
	v_pk_fma_f32 v[242:243], v[22:23], v[66:67], v[242:243] neg_lo:[1,0,0] neg_hi:[1,0,0]
	v_pk_fma_f32 v[244:245], v[24:25], v[68:69], v[244:245] neg_lo:[1,0,0] neg_hi:[1,0,0]
	ds_read_b128 v[246:249], v1 offset:42528
	s_waitcnt lgkmcnt(14)
	v_pk_fma_f32 v[242:243], v[26:27], v[70:71], v[242:243] neg_lo:[1,0,0] neg_hi:[1,0,0]
	v_pk_fma_f32 v[244:245], v[28:29], v[72:73], v[244:245] neg_lo:[1,0,0] neg_hi:[1,0,0]
	ds_read_b128 v[66:69], v1 offset:42704
	s_nop 0
	v_pk_add_f32 v[242:243], v[242:243], v[244:245]
	s_nop 0
	v_add_f32_e32 v242, v242, v243
	v_add_f32_e32 v28, v28, v242
	s_waitcnt lgkmcnt(14)
	v_pk_mul_f32 v[242:243], v[2:3], v[74:75] neg_lo:[1,0] neg_hi:[1,0]
	v_pk_mul_f32 v[244:245], v[4:5], v[76:77] neg_lo:[1,0] neg_hi:[1,0]
	ds_read_b128 v[70:73], v1 offset:42720
	s_waitcnt lgkmcnt(14)
	v_pk_fma_f32 v[242:243], v[6:7], v[78:79], v[242:243] neg_lo:[1,0,0] neg_hi:[1,0,0]
	v_pk_fma_f32 v[244:245], v[8:9], v[80:81], v[244:245] neg_lo:[1,0,0] neg_hi:[1,0,0]
	ds_read_b128 v[74:77], v1 offset:42736
	s_waitcnt lgkmcnt(14)
	v_pk_fma_f32 v[242:243], v[10:11], v[82:83], v[242:243] neg_lo:[1,0,0] neg_hi:[1,0,0]
	v_pk_fma_f32 v[244:245], v[12:13], v[84:85], v[244:245] neg_lo:[1,0,0] neg_hi:[1,0,0]
	ds_read_b128 v[78:81], v1 offset:42752
	s_waitcnt lgkmcnt(14)
	v_pk_fma_f32 v[242:243], v[14:15], v[86:87], v[242:243] neg_lo:[1,0,0] neg_hi:[1,0,0]
	v_pk_fma_f32 v[244:245], v[16:17], v[88:89], v[244:245] neg_lo:[1,0,0] neg_hi:[1,0,0]
	ds_read_b128 v[82:85], v1 offset:42768
	s_waitcnt lgkmcnt(14)
	v_pk_fma_f32 v[242:243], v[18:19], v[116:117], v[242:243] neg_lo:[1,0,0] neg_hi:[1,0,0]
	v_pk_fma_f32 v[244:245], v[20:21], v[118:119], v[244:245] neg_lo:[1,0,0] neg_hi:[1,0,0]
	ds_read_b128 v[86:89], v1 offset:42784
	s_waitcnt lgkmcnt(14)
	v_pk_fma_f32 v[242:243], v[22:23], v[120:121], v[242:243] neg_lo:[1,0,0] neg_hi:[1,0,0]
	v_pk_fma_f32 v[244:245], v[24:25], v[122:123], v[244:245] neg_lo:[1,0,0] neg_hi:[1,0,0]
	ds_read_b128 v[116:119], v1 offset:42800
	s_waitcnt lgkmcnt(14)
	v_pk_fma_f32 v[242:243], v[26:27], v[124:125], v[242:243] neg_lo:[1,0,0] neg_hi:[1,0,0]
	v_pk_fma_f32 v[244:245], v[28:29], v[126:127], v[244:245] neg_lo:[1,0,0] neg_hi:[1,0,0]
	ds_read_b128 v[120:123], v1 offset:42816
	s_nop 0
	v_pk_add_f32 v[242:243], v[242:243], v[244:245]
	s_nop 0
	v_add_f32_e32 v242, v242, v243
	v_add_f32_e32 v29, v29, v242
	s_waitcnt lgkmcnt(14)
	v_pk_mul_f32 v[242:243], v[2:3], v[128:129] neg_lo:[1,0] neg_hi:[1,0]
	v_pk_mul_f32 v[244:245], v[4:5], v[130:131] neg_lo:[1,0] neg_hi:[1,0]
	ds_read_b128 v[124:127], v1 offset:42976
	s_waitcnt lgkmcnt(14)
	v_pk_fma_f32 v[242:243], v[6:7], v[132:133], v[242:243] neg_lo:[1,0,0] neg_hi:[1,0,0]
	v_pk_fma_f32 v[244:245], v[8:9], v[134:135], v[244:245] neg_lo:[1,0,0] neg_hi:[1,0,0]
	ds_read_b128 v[128:131], v1 offset:42992
	s_waitcnt lgkmcnt(14)
	v_pk_fma_f32 v[242:243], v[10:11], v[136:137], v[242:243] neg_lo:[1,0,0] neg_hi:[1,0,0]
	v_pk_fma_f32 v[244:245], v[12:13], v[138:139], v[244:245] neg_lo:[1,0,0] neg_hi:[1,0,0]
	ds_read_b128 v[132:135], v1 offset:43008
	s_waitcnt lgkmcnt(14)
	v_pk_fma_f32 v[242:243], v[14:15], v[140:141], v[242:243] neg_lo:[1,0,0] neg_hi:[1,0,0]
	v_pk_fma_f32 v[244:245], v[16:17], v[142:143], v[244:245] neg_lo:[1,0,0] neg_hi:[1,0,0]
	ds_read_b128 v[136:139], v1 offset:43024
	s_waitcnt lgkmcnt(14)
	v_pk_fma_f32 v[242:243], v[18:19], v[200:201], v[242:243] neg_lo:[1,0,0] neg_hi:[1,0,0]
	v_pk_fma_f32 v[244:245], v[20:21], v[202:203], v[244:245] neg_lo:[1,0,0] neg_hi:[1,0,0]
	ds_read_b128 v[140:143], v1 offset:43040
	s_waitcnt lgkmcnt(14)
	v_pk_fma_f32 v[242:243], v[22:23], v[204:205], v[242:243] neg_lo:[1,0,0] neg_hi:[1,0,0]
	v_pk_fma_f32 v[244:245], v[24:25], v[206:207], v[244:245] neg_lo:[1,0,0] neg_hi:[1,0,0]
	ds_read_b128 v[200:203], v1 offset:43056
	s_waitcnt lgkmcnt(14)
	v_pk_fma_f32 v[242:243], v[26:27], v[246:247], v[242:243] neg_lo:[1,0,0] neg_hi:[1,0,0]
	v_pk_fma_f32 v[244:245], v[28:29], v[248:249], v[244:245] neg_lo:[1,0,0] neg_hi:[1,0,0]
	ds_read_b128 v[204:207], v1 offset:43072
	s_nop 0
	v_pk_add_f32 v[242:243], v[242:243], v[244:245]
	s_nop 0
	v_add_f32_e32 v242, v242, v243
	v_add_f32_e32 v30, v30, v242
	s_waitcnt lgkmcnt(14)
	v_pk_mul_f32 v[242:243], v[2:3], v[66:67] neg_lo:[1,0] neg_hi:[1,0]
	v_pk_mul_f32 v[244:245], v[4:5], v[68:69] neg_lo:[1,0] neg_hi:[1,0]
	ds_read_b128 v[246:249], v1 offset:43088
	s_waitcnt lgkmcnt(14)
	v_pk_fma_f32 v[242:243], v[6:7], v[70:71], v[242:243] neg_lo:[1,0,0] neg_hi:[1,0,0]
	v_pk_fma_f32 v[244:245], v[8:9], v[72:73], v[244:245] neg_lo:[1,0,0] neg_hi:[1,0,0]
	ds_read_b128 v[66:69], v1 offset:43248
	s_waitcnt lgkmcnt(14)
	v_pk_fma_f32 v[242:243], v[10:11], v[74:75], v[242:243] neg_lo:[1,0,0] neg_hi:[1,0,0]
	v_pk_fma_f32 v[244:245], v[12:13], v[76:77], v[244:245] neg_lo:[1,0,0] neg_hi:[1,0,0]
	ds_read_b128 v[70:73], v1 offset:43264
	s_waitcnt lgkmcnt(14)
	v_pk_fma_f32 v[242:243], v[14:15], v[78:79], v[242:243] neg_lo:[1,0,0] neg_hi:[1,0,0]
	v_pk_fma_f32 v[244:245], v[16:17], v[80:81], v[244:245] neg_lo:[1,0,0] neg_hi:[1,0,0]
	ds_read_b128 v[74:77], v1 offset:43280
	s_waitcnt lgkmcnt(14)
	v_pk_fma_f32 v[242:243], v[18:19], v[82:83], v[242:243] neg_lo:[1,0,0] neg_hi:[1,0,0]
	v_pk_fma_f32 v[244:245], v[20:21], v[84:85], v[244:245] neg_lo:[1,0,0] neg_hi:[1,0,0]
	ds_read_b128 v[78:81], v1 offset:43296
	s_waitcnt lgkmcnt(14)
; #define SUB_LROW(buf, i_, j0_, n_) do { _Pragma("unroll") for (int j4 = 0; j4 < (n_); ++j4) buf[j4] = *(const f32x4*)(Ls + (i_) * 68 + 4 * ((j0_) + j4)); } while (0)
; #define SUB_FROW(buf, j0_, n_) do { _Pragma("unroll") for (int j4 = 0; j4 < (n_); ++j4) { const f32x4 l = buf[j4]; \
;                 acc -= l.x * x[4 * ((j0_) + j4)]; acc -= l.y * x[4 * ((j0_) + j4) + 1]; acc -= l.z * x[4 * ((j0_) + j4) + 2]; acc -= l.w * x[4 * ((j0_) + j4) + 3]; } } while (0)
; __device__ __forceinline__ void gdn_prep(KA a, int layer, unsigned char* lds, const int tid_, const int bid_) {
;     ...
; #pragma unroll
;             for (int j4 = 0; j4 < 8; ++j4) { bufA[j4] = (f32x4){0.f, 0.f, 0.f, 0.f}; bufB[j4] = (f32x4){0.f, 0.f, 0.f, 0.f}; }
;             SUB_LROW(bufA, 1, 0, 1);
; #pragma unroll
;             for (int i = 1; i <= 32; ++i) {
;                 const int nn = (i + 4) / 4 < 8 ? (i + 4) / 4 : 8;
;                 float acc = x[i];
;                 if (i & 1) { SUB_LROW(bufB, i + 1, 0, nn); __builtin_amdgcn_sched_barrier(0); SUB_FROW(bufA, 0, (i + 3) / 4); }
;                 else       { SUB_LROW(bufA, i + 1, 0, nn); __builtin_amdgcn_sched_barrier(0); SUB_FROW(bufB, 0, (i + 3) / 4); }
;                 x[i] = acc;
;                 __builtin_amdgcn_sched_barrier(0);
;             }
	v_pk_fma_f32 v[242:243], v[22:23], v[86:87], v[242:243] neg_lo:[1,0,0] neg_hi:[1,0,0]
	v_pk_fma_f32 v[244:245], v[24:25], v[88:89], v[244:245] neg_lo:[1,0,0] neg_hi:[1,0,0]
	ds_read_b128 v[82:85], v1 offset:43312
	s_waitcnt lgkmcnt(14)
	v_pk_fma_f32 v[242:243], v[26:27], v[116:117], v[242:243] neg_lo:[1,0,0] neg_hi:[1,0,0]
	v_pk_fma_f32 v[244:245], v[28:29], v[118:119], v[244:245] neg_lo:[1,0,0] neg_hi:[1,0,0]
	ds_read_b128 v[86:89], v1 offset:43328
	s_waitcnt lgkmcnt(14)
	v_pk_fma_f32 v[242:243], v[30:31], v[120:121], v[242:243] neg_lo:[1,0,0] neg_hi:[1,0,0]
	v_pk_fma_f32 v[244:245], v[32:33], v[122:123], v[244:245] neg_lo:[1,0,0] neg_hi:[1,0,0]
	ds_read_b128 v[116:119], v1 offset:43344
	s_nop 0
	v_pk_add_f32 v[242:243], v[242:243], v[244:245]
	s_nop 0
	v_add_f32_e32 v242, v242, v243
	v_add_f32_e32 v31, v31, v242
	s_waitcnt lgkmcnt(14)
	v_pk_mul_f32 v[242:243], v[2:3], v[124:125] neg_lo:[1,0] neg_hi:[1,0]
	v_pk_mul_f32 v[244:245], v[4:5], v[126:127] neg_lo:[1,0] neg_hi:[1,0]
	ds_read_b128 v[120:123], v1 offset:43360
	s_waitcnt lgkmcnt(14)
	v_pk_fma_f32 v[242:243], v[6:7], v[128:129], v[242:243] neg_lo:[1,0,0] neg_hi:[1,0,0]
	v_pk_fma_f32 v[244:245], v[8:9], v[130:131], v[244:245] neg_lo:[1,0,0] neg_hi:[1,0,0]
	ds_read_b128 v[124:127], v1 offset:43520
	s_waitcnt lgkmcnt(14)
	v_pk_fma_f32 v[242:243], v[10:11], v[132:133], v[242:243] neg_lo:[1,0,0] neg_hi:[1,0,0]
	v_pk_fma_f32 v[244:245], v[12:13], v[134:135], v[244:245] neg_lo:[1,0,0] neg_hi:[1,0,0]
	ds_read_b128 v[128:131], v1 offset:43536
	s_waitcnt lgkmcnt(14)
	v_pk_fma_f32 v[242:243], v[14:15], v[136:137], v[242:243] neg_lo:[1,0,0] neg_hi:[1,0,0]
	v_pk_fma_f32 v[244:245], v[16:17], v[138:139], v[244:245] neg_lo:[1,0,0] neg_hi:[1,0,0]
	ds_read_b128 v[132:135], v1 offset:43552
	s_waitcnt lgkmcnt(14)
	v_pk_fma_f32 v[242:243], v[18:19], v[140:141], v[242:243] neg_lo:[1,0,0] neg_hi:[1,0,0]
	v_pk_fma_f32 v[244:245], v[20:21], v[142:143], v[244:245] neg_lo:[1,0,0] neg_hi:[1,0,0]
	ds_read_b128 v[136:139], v1 offset:43568
	s_waitcnt lgkmcnt(14)
	v_pk_fma_f32 v[242:243], v[22:23], v[200:201], v[242:243] neg_lo:[1,0,0] neg_hi:[1,0,0]
	v_pk_fma_f32 v[244:245], v[24:25], v[202:203], v[244:245] neg_lo:[1,0,0] neg_hi:[1,0,0]
	ds_read_b128 v[140:143], v1 offset:43584
	s_waitcnt lgkmcnt(14)
	v_pk_fma_f32 v[242:243], v[26:27], v[204:205], v[242:243] neg_lo:[1,0,0] neg_hi:[1,0,0]
	v_pk_fma_f32 v[244:245], v[28:29], v[206:207], v[244:245] neg_lo:[1,0,0] neg_hi:[1,0,0]
	ds_read_b128 v[200:203], v1 offset:43600
	s_waitcnt lgkmcnt(14)
	v_pk_fma_f32 v[242:243], v[30:31], v[246:247], v[242:243] neg_lo:[1,0,0] neg_hi:[1,0,0]
	v_pk_fma_f32 v[244:245], v[32:33], v[248:249], v[244:245] neg_lo:[1,0,0] neg_hi:[1,0,0]
	ds_read_b128 v[204:207], v1 offset:43616
	s_nop 0
	v_pk_add_f32 v[242:243], v[242:243], v[244:245]
	s_nop 0
	v_add_f32_e32 v242, v242, v243
	v_add_f32_e32 v32, v32, v242
	s_waitcnt lgkmcnt(14)
	v_pk_mul_f32 v[242:243], v[2:3], v[66:67] neg_lo:[1,0] neg_hi:[1,0]
	v_pk_mul_f32 v[244:245], v[4:5], v[68:69] neg_lo:[1,0] neg_hi:[1,0]
	ds_read_b128 v[246:249], v1 offset:43632
	s_waitcnt lgkmcnt(14)
	v_pk_fma_f32 v[242:243], v[6:7], v[70:71], v[242:243] neg_lo:[1,0,0] neg_hi:[1,0,0]
	v_pk_fma_f32 v[244:245], v[8:9], v[72:73], v[244:245] neg_lo:[1,0,0] neg_hi:[1,0,0]
	ds_read_b128 v[66:69], v1 offset:43792
	s_waitcnt lgkmcnt(14)
	v_pk_fma_f32 v[242:243], v[10:11], v[74:75], v[242:243] neg_lo:[1,0,0] neg_hi:[1,0,0]
	v_pk_fma_f32 v[244:245], v[12:13], v[76:77], v[244:245] neg_lo:[1,0,0] neg_hi:[1,0,0]
	ds_read_b128 v[70:73], v1 offset:43808
	s_waitcnt lgkmcnt(14)
	v_pk_fma_f32 v[242:243], v[14:15], v[78:79], v[242:243] neg_lo:[1,0,0] neg_hi:[1,0,0]
	v_pk_fma_f32 v[244:245], v[16:17], v[80:81], v[244:245] neg_lo:[1,0,0] neg_hi:[1,0,0]
	ds_read_b128 v[74:77], v1 offset:43824
	s_waitcnt lgkmcnt(14)
	v_pk_fma_f32 v[242:243], v[18:19], v[82:83], v[242:243] neg_lo:[1,0,0] neg_hi:[1,0,0]
	v_pk_fma_f32 v[244:245], v[20:21], v[84:85], v[244:245] neg_lo:[1,0,0] neg_hi:[1,0,0]
	ds_read_b128 v[78:81], v1 offset:43840
	s_waitcnt lgkmcnt(14)
	v_pk_fma_f32 v[242:243], v[22:23], v[86:87], v[242:243] neg_lo:[1,0,0] neg_hi:[1,0,0]
	v_pk_fma_f32 v[244:245], v[24:25], v[88:89], v[244:245] neg_lo:[1,0,0] neg_hi:[1,0,0]
	ds_read_b128 v[82:85], v1 offset:43856
	s_waitcnt lgkmcnt(14)
	v_pk_fma_f32 v[242:243], v[26:27], v[116:117], v[242:243] neg_lo:[1,0,0] neg_hi:[1,0,0]
	v_pk_fma_f32 v[244:245], v[28:29], v[118:119], v[244:245] neg_lo:[1,0,0] neg_hi:[1,0,0]
	ds_read_b128 v[86:89], v1 offset:43872
	s_waitcnt lgkmcnt(14)
	v_pk_fma_f32 v[242:243], v[30:31], v[120:121], v[242:243] neg_lo:[1,0,0] neg_hi:[1,0,0]
	v_pk_fma_f32 v[244:245], v[32:33], v[122:123], v[244:245] neg_lo:[1,0,0] neg_hi:[1,0,0]
	ds_read_b128 v[116:119], v1 offset:43888
	s_nop 0
	v_pk_add_f32 v[242:243], v[242:243], v[244:245]
	s_nop 0
	v_add_f32_e32 v242, v242, v243
	v_add_f32_e32 v33, v33, v242
	s_waitcnt lgkmcnt(14)
	v_pk_mul_f32 v[242:243], v[2:3], v[124:125] neg_lo:[1,0] neg_hi:[1,0]
	v_pk_mul_f32 v[244:245], v[4:5], v[126:127] neg_lo:[1,0] neg_hi:[1,0]
	ds_read_b128 v[120:123], v1 offset:43904
	s_waitcnt lgkmcnt(14)
	v_pk_fma_f32 v[242:243], v[6:7], v[128:129], v[242:243] neg_lo:[1,0,0] neg_hi:[1,0,0]
	v_pk_fma_f32 v[244:245], v[8:9], v[130:131], v[244:245] neg_lo:[1,0,0] neg_hi:[1,0,0]
	ds_read_b128 v[124:127], v1 offset:43920
	s_waitcnt lgkmcnt(14)
	v_pk_fma_f32 v[242:243], v[10:11], v[132:133], v[242:243] neg_lo:[1,0,0] neg_hi:[1,0,0]
	v_pk_fma_f32 v[244:245], v[12:13], v[134:135], v[244:245] neg_lo:[1,0,0] neg_hi:[1,0,0]
	ds_read_b128 v[128:131], v1 offset:44064
	s_waitcnt lgkmcnt(14)
; #define SUB_LROW(buf, i_, j0_, n_) do { _Pragma("unroll") for (int j4 = 0; j4 < (n_); ++j4) buf[j4] = *(const f32x4*)(Ls + (i_) * 68 + 4 * ((j0_) + j4)); } while (0)
; #define SUB_FROW(buf, j0_, n_) do { _Pragma("unroll") for (int j4 = 0; j4 < (n_); ++j4) { const f32x4 l = buf[j4]; \
;                 acc -= l.x * x[4 * ((j0_) + j4)]; acc -= l.y * x[4 * ((j0_) + j4) + 1]; acc -= l.z * x[4 * ((j0_) + j4) + 2]; acc -= l.w * x[4 * ((j0_) + j4) + 3]; } } while (0)
; __device__ __forceinline__ void gdn_prep(KA a, int layer, unsigned char* lds, const int tid_, const int bid_) {
;     ...
; #pragma unroll
;             for (int j4 = 0; j4 < 8; ++j4) { bufA[j4] = (f32x4){0.f, 0.f, 0.f, 0.f}; bufB[j4] = (f32x4){0.f, 0.f, 0.f, 0.f}; }
;             SUB_LROW(bufA, 1, 0, 1);
; #pragma unroll
;             for (int i = 1; i <= 32; ++i) {
;                 const int nn = (i + 4) / 4 < 8 ? (i + 4) / 4 : 8;
;                 float acc = x[i];
;                 if (i & 1) { SUB_LROW(bufB, i + 1, 0, nn); __builtin_amdgcn_sched_barrier(0); SUB_FROW(bufA, 0, (i + 3) / 4); }
;                 else       { SUB_LROW(bufA, i + 1, 0, nn); __builtin_amdgcn_sched_barrier(0); SUB_FROW(bufB, 0, (i + 3) / 4); }
;                 x[i] = acc;
;                 __builtin_amdgcn_sched_barrier(0);
;             }
; #pragma unroll
;             for (int i = 33; i < 64; ++i) {
;                 float acc = x[i];
;                 SUB_LROW(bufB, i, 8, (i + 3) / 4 - 8); __builtin_amdgcn_sched_barrier(0);
;                 SUB_FROW(bufA, 0, 8); __builtin_amdgcn_sched_barrier(0);
;                 if (i + 1 < 64) SUB_LROW(bufA, i + 1, 0, 8);
;                 __builtin_amdgcn_sched_barrier(0);
;                 SUB_FROW(bufB, 8, (i + 3) / 4 - 8);
;                 x[i] = acc;
;                 __builtin_amdgcn_sched_barrier(0);
;             }
	v_pk_fma_f32 v[242:243], v[14:15], v[136:137], v[242:243] neg_lo:[1,0,0] neg_hi:[1,0,0]
	v_pk_fma_f32 v[244:245], v[16:17], v[138:139], v[244:245] neg_lo:[1,0,0] neg_hi:[1,0,0]
	ds_read_b128 v[132:135], v1 offset:44080
	s_waitcnt lgkmcnt(14)
	v_pk_fma_f32 v[242:243], v[18:19], v[140:141], v[242:243] neg_lo:[1,0,0] neg_hi:[1,0,0]
	v_pk_fma_f32 v[244:245], v[20:21], v[142:143], v[244:245] neg_lo:[1,0,0] neg_hi:[1,0,0]
	ds_read_b128 v[136:139], v1 offset:44096
	s_waitcnt lgkmcnt(14)
	v_pk_fma_f32 v[242:243], v[22:23], v[200:201], v[242:243] neg_lo:[1,0,0] neg_hi:[1,0,0]
	v_pk_fma_f32 v[244:245], v[24:25], v[202:203], v[244:245] neg_lo:[1,0,0] neg_hi:[1,0,0]
	ds_read_b128 v[140:143], v1 offset:44112
	s_waitcnt lgkmcnt(14)
	v_pk_fma_f32 v[242:243], v[26:27], v[204:205], v[242:243] neg_lo:[1,0,0] neg_hi:[1,0,0]
	v_pk_fma_f32 v[244:245], v[28:29], v[206:207], v[244:245] neg_lo:[1,0,0] neg_hi:[1,0,0]
	ds_read_b128 v[200:203], v1 offset:44128
	s_waitcnt lgkmcnt(14)
	v_pk_fma_f32 v[242:243], v[30:31], v[246:247], v[242:243] neg_lo:[1,0,0] neg_hi:[1,0,0]
	v_pk_fma_f32 v[244:245], v[32:33], v[248:249], v[244:245] neg_lo:[1,0,0] neg_hi:[1,0,0]
	ds_read_b128 v[204:207], v1 offset:44144
	s_nop 0
	v_pk_add_f32 v[242:243], v[242:243], v[244:245]
	s_nop 0
	v_add_f32_e32 v242, v242, v243
	v_add_f32_e32 v34, v34, v242
	s_waitcnt lgkmcnt(14)
	v_pk_mul_f32 v[242:243], v[2:3], v[66:67] neg_lo:[1,0] neg_hi:[1,0]
	v_pk_mul_f32 v[244:245], v[4:5], v[68:69] neg_lo:[1,0] neg_hi:[1,0]
	ds_read_b128 v[246:249], v1 offset:44160
	s_waitcnt lgkmcnt(14)
	v_pk_fma_f32 v[242:243], v[6:7], v[70:71], v[242:243] neg_lo:[1,0,0] neg_hi:[1,0,0]
	v_pk_fma_f32 v[244:245], v[8:9], v[72:73], v[244:245] neg_lo:[1,0,0] neg_hi:[1,0,0]
	ds_read_b128 v[66:69], v1 offset:44176
	s_waitcnt lgkmcnt(14)
	v_pk_fma_f32 v[242:243], v[10:11], v[74:75], v[242:243] neg_lo:[1,0,0] neg_hi:[1,0,0]
	v_pk_fma_f32 v[244:245], v[12:13], v[76:77], v[244:245] neg_lo:[1,0,0] neg_hi:[1,0,0]
	ds_read_b128 v[70:73], v1 offset:44192
	s_waitcnt lgkmcnt(14)
	v_pk_fma_f32 v[242:243], v[14:15], v[78:79], v[242:243] neg_lo:[1,0,0] neg_hi:[1,0,0]
	v_pk_fma_f32 v[244:245], v[16:17], v[80:81], v[244:245] neg_lo:[1,0,0] neg_hi:[1,0,0]
	ds_read_b128 v[74:77], v1 offset:44336
	s_waitcnt lgkmcnt(14)
	v_pk_fma_f32 v[242:243], v[18:19], v[82:83], v[242:243] neg_lo:[1,0,0] neg_hi:[1,0,0]
	v_pk_fma_f32 v[244:245], v[20:21], v[84:85], v[244:245] neg_lo:[1,0,0] neg_hi:[1,0,0]
	ds_read_b128 v[78:81], v1 offset:44352
	s_waitcnt lgkmcnt(14)
	v_pk_fma_f32 v[242:243], v[22:23], v[86:87], v[242:243] neg_lo:[1,0,0] neg_hi:[1,0,0]
	v_pk_fma_f32 v[244:245], v[24:25], v[88:89], v[244:245] neg_lo:[1,0,0] neg_hi:[1,0,0]
	ds_read_b128 v[82:85], v1 offset:44368
	s_waitcnt lgkmcnt(14)
	v_pk_fma_f32 v[242:243], v[26:27], v[116:117], v[242:243] neg_lo:[1,0,0] neg_hi:[1,0,0]
	v_pk_fma_f32 v[244:245], v[28:29], v[118:119], v[244:245] neg_lo:[1,0,0] neg_hi:[1,0,0]
	ds_read_b128 v[86:89], v1 offset:44384
	s_waitcnt lgkmcnt(14)
	v_pk_fma_f32 v[242:243], v[30:31], v[120:121], v[242:243] neg_lo:[1,0,0] neg_hi:[1,0,0]
	v_pk_fma_f32 v[244:245], v[32:33], v[122:123], v[244:245] neg_lo:[1,0,0] neg_hi:[1,0,0]
	ds_read_b128 v[116:119], v1 offset:44400
	s_waitcnt lgkmcnt(14)
	v_pk_fma_f32 v[242:243], v[34:35], v[124:125], v[242:243] neg_lo:[1,0,0] neg_hi:[1,0,0]
	v_pk_fma_f32 v[244:245], v[36:37], v[126:127], v[244:245] neg_lo:[1,0,0] neg_hi:[1,0,0]
	ds_read_b128 v[120:123], v1 offset:44416
	s_nop 0
	v_pk_add_f32 v[242:243], v[242:243], v[244:245]
	s_nop 0
	v_add_f32_e32 v242, v242, v243
	v_add_f32_e32 v35, v35, v242
	s_waitcnt lgkmcnt(14)
	v_pk_mul_f32 v[242:243], v[2:3], v[128:129] neg_lo:[1,0] neg_hi:[1,0]
	v_pk_mul_f32 v[244:245], v[4:5], v[130:131] neg_lo:[1,0] neg_hi:[1,0]
	ds_read_b128 v[124:127], v1 offset:44432
	s_waitcnt lgkmcnt(14)
	v_pk_fma_f32 v[242:243], v[6:7], v[132:133], v[242:243] neg_lo:[1,0,0] neg_hi:[1,0,0]
	v_pk_fma_f32 v[244:245], v[8:9], v[134:135], v[244:245] neg_lo:[1,0,0] neg_hi:[1,0,0]
	ds_read_b128 v[128:131], v1 offset:44448
	s_waitcnt lgkmcnt(14)
	v_pk_fma_f32 v[242:243], v[10:11], v[136:137], v[242:243] neg_lo:[1,0,0] neg_hi:[1,0,0]
	v_pk_fma_f32 v[244:245], v[12:13], v[138:139], v[244:245] neg_lo:[1,0,0] neg_hi:[1,0,0]
	ds_read_b128 v[132:135], v1 offset:44464
	s_waitcnt lgkmcnt(14)
	v_pk_fma_f32 v[242:243], v[14:15], v[140:141], v[242:243] neg_lo:[1,0,0] neg_hi:[1,0,0]
	v_pk_fma_f32 v[244:245], v[16:17], v[142:143], v[244:245] neg_lo:[1,0,0] neg_hi:[1,0,0]
	ds_read_b128 v[136:139], v1 offset:44608
	s_waitcnt lgkmcnt(14)
	v_pk_fma_f32 v[242:243], v[18:19], v[200:201], v[242:243] neg_lo:[1,0,0] neg_hi:[1,0,0]
	v_pk_fma_f32 v[244:245], v[20:21], v[202:203], v[244:245] neg_lo:[1,0,0] neg_hi:[1,0,0]
	ds_read_b128 v[140:143], v1 offset:44624
	s_waitcnt lgkmcnt(14)
	v_pk_fma_f32 v[242:243], v[22:23], v[204:205], v[242:243] neg_lo:[1,0,0] neg_hi:[1,0,0]
	v_pk_fma_f32 v[244:245], v[24:25], v[206:207], v[244:245] neg_lo:[1,0,0] neg_hi:[1,0,0]
	ds_read_b128 v[200:203], v1 offset:44640
	s_waitcnt lgkmcnt(14)
	v_pk_fma_f32 v[242:243], v[26:27], v[246:247], v[242:243] neg_lo:[1,0,0] neg_hi:[1,0,0]
	v_pk_fma_f32 v[244:245], v[28:29], v[248:249], v[244:245] neg_lo:[1,0,0] neg_hi:[1,0,0]
	ds_read_b128 v[204:207], v1 offset:44656
	s_waitcnt lgkmcnt(14)
	v_pk_fma_f32 v[242:243], v[30:31], v[66:67], v[242:243] neg_lo:[1,0,0] neg_hi:[1,0,0]
	v_pk_fma_f32 v[244:245], v[32:33], v[68:69], v[244:245] neg_lo:[1,0,0] neg_hi:[1,0,0]
	ds_read_b128 v[246:249], v1 offset:44672
	s_waitcnt lgkmcnt(14)
; #define SUB_LROW(buf, i_, j0_, n_) do { _Pragma("unroll") for (int j4 = 0; j4 < (n_); ++j4) buf[j4] = *(const f32x4*)(Ls + (i_) * 68 + 4 * ((j0_) + j4)); } while (0)
; #define SUB_FROW(buf, j0_, n_) do { _Pragma("unroll") for (int j4 = 0; j4 < (n_); ++j4) { const f32x4 l = buf[j4]; \
;                 acc -= l.x * x[4 * ((j0_) + j4)]; acc -= l.y * x[4 * ((j0_) + j4) + 1]; acc -= l.z * x[4 * ((j0_) + j4) + 2]; acc -= l.w * x[4 * ((j0_) + j4) + 3]; } } while (0)
; __device__ __forceinline__ void gdn_prep(KA a, int layer, unsigned char* lds, const int tid_, const int bid_) {
;     ...
;             for (int i = 33; i < 64; ++i) {
;                 float acc = x[i];
;                 SUB_LROW(bufB, i, 8, (i + 3) / 4 - 8); __builtin_amdgcn_sched_barrier(0);
;                 SUB_FROW(bufA, 0, 8); __builtin_amdgcn_sched_barrier(0);
;                 if (i + 1 < 64) SUB_LROW(bufA, i + 1, 0, 8);
;                 __builtin_amdgcn_sched_barrier(0);
;                 SUB_FROW(bufB, 8, (i + 3) / 4 - 8);
;                 x[i] = acc;
;                 __builtin_amdgcn_sched_barrier(0);
;             }
	v_pk_fma_f32 v[242:243], v[34:35], v[70:71], v[242:243] neg_lo:[1,0,0] neg_hi:[1,0,0]
	v_pk_fma_f32 v[244:245], v[36:37], v[72:73], v[244:245] neg_lo:[1,0,0] neg_hi:[1,0,0]
	ds_read_b128 v[66:69], v1 offset:44688
	s_nop 0
	v_pk_add_f32 v[242:243], v[242:243], v[244:245]
	s_nop 0
	v_add_f32_e32 v242, v242, v243
	v_add_f32_e32 v36, v36, v242
	s_waitcnt lgkmcnt(14)
	v_pk_mul_f32 v[242:243], v[2:3], v[74:75] neg_lo:[1,0] neg_hi:[1,0]
	v_pk_mul_f32 v[244:245], v[4:5], v[76:77] neg_lo:[1,0] neg_hi:[1,0]
	ds_read_b128 v[70:73], v1 offset:44704
	s_waitcnt lgkmcnt(14)
	v_pk_fma_f32 v[242:243], v[6:7], v[78:79], v[242:243] neg_lo:[1,0,0] neg_hi:[1,0,0]
	v_pk_fma_f32 v[244:245], v[8:9], v[80:81], v[244:245] neg_lo:[1,0,0] neg_hi:[1,0,0]
	ds_read_b128 v[74:77], v1 offset:44720
	s_waitcnt lgkmcnt(14)
	v_pk_fma_f32 v[242:243], v[10:11], v[82:83], v[242:243] neg_lo:[1,0,0] neg_hi:[1,0,0]
	v_pk_fma_f32 v[244:245], v[12:13], v[84:85], v[244:245] neg_lo:[1,0,0] neg_hi:[1,0,0]
	ds_read_b128 v[78:81], v1 offset:44736
	s_waitcnt lgkmcnt(14)
	v_pk_fma_f32 v[242:243], v[14:15], v[86:87], v[242:243] neg_lo:[1,0,0] neg_hi:[1,0,0]
	v_pk_fma_f32 v[244:245], v[16:17], v[88:89], v[244:245] neg_lo:[1,0,0] neg_hi:[1,0,0]
	ds_read_b128 v[82:85], v1 offset:44880
	s_waitcnt lgkmcnt(14)
	v_pk_fma_f32 v[242:243], v[18:19], v[116:117], v[242:243] neg_lo:[1,0,0] neg_hi:[1,0,0]
	v_pk_fma_f32 v[244:245], v[20:21], v[118:119], v[244:245] neg_lo:[1,0,0] neg_hi:[1,0,0]
	ds_read_b128 v[86:89], v1 offset:44896
	s_waitcnt lgkmcnt(14)
	v_pk_fma_f32 v[242:243], v[22:23], v[120:121], v[242:243] neg_lo:[1,0,0] neg_hi:[1,0,0]
	v_pk_fma_f32 v[244:245], v[24:25], v[122:123], v[244:245] neg_lo:[1,0,0] neg_hi:[1,0,0]
	ds_read_b128 v[116:119], v1 offset:44912
	s_waitcnt lgkmcnt(14)
	v_pk_fma_f32 v[242:243], v[26:27], v[124:125], v[242:243] neg_lo:[1,0,0] neg_hi:[1,0,0]
	v_pk_fma_f32 v[244:245], v[28:29], v[126:127], v[244:245] neg_lo:[1,0,0] neg_hi:[1,0,0]
	ds_read_b128 v[120:123], v1 offset:44928
	s_waitcnt lgkmcnt(14)
	v_pk_fma_f32 v[242:243], v[30:31], v[128:129], v[242:243] neg_lo:[1,0,0] neg_hi:[1,0,0]
	v_pk_fma_f32 v[244:245], v[32:33], v[130:131], v[244:245] neg_lo:[1,0,0] neg_hi:[1,0,0]
	ds_read_b128 v[124:127], v1 offset:44944
	s_waitcnt lgkmcnt(14)
	v_pk_fma_f32 v[242:243], v[34:35], v[132:133], v[242:243] neg_lo:[1,0,0] neg_hi:[1,0,0]
	v_pk_fma_f32 v[244:245], v[36:37], v[134:135], v[244:245] neg_lo:[1,0,0] neg_hi:[1,0,0]
	ds_read_b128 v[128:131], v1 offset:44960
	s_nop 0
	v_pk_add_f32 v[242:243], v[242:243], v[244:245]
	s_nop 0
	v_add_f32_e32 v242, v242, v243
	v_add_f32_e32 v37, v37, v242
	s_waitcnt lgkmcnt(14)
	v_pk_mul_f32 v[242:243], v[2:3], v[136:137] neg_lo:[1,0] neg_hi:[1,0]
	v_pk_mul_f32 v[244:245], v[4:5], v[138:139] neg_lo:[1,0] neg_hi:[1,0]
	ds_read_b128 v[132:135], v1 offset:44976
	s_waitcnt lgkmcnt(14)
	v_pk_fma_f32 v[242:243], v[6:7], v[140:141], v[242:243] neg_lo:[1,0,0] neg_hi:[1,0,0]
	v_pk_fma_f32 v[244:245], v[8:9], v[142:143], v[244:245] neg_lo:[1,0,0] neg_hi:[1,0,0]
	ds_read_b128 v[136:139], v1 offset:44992
	s_waitcnt lgkmcnt(14)
	v_pk_fma_f32 v[242:243], v[10:11], v[200:201], v[242:243] neg_lo:[1,0,0] neg_hi:[1,0,0]
	v_pk_fma_f32 v[244:245], v[12:13], v[202:203], v[244:245] neg_lo:[1,0,0] neg_hi:[1,0,0]
	ds_read_b128 v[140:143], v1 offset:45008
	s_waitcnt lgkmcnt(14)
	v_pk_fma_f32 v[242:243], v[14:15], v[204:205], v[242:243] neg_lo:[1,0,0] neg_hi:[1,0,0]
	v_pk_fma_f32 v[244:245], v[16:17], v[206:207], v[244:245] neg_lo:[1,0,0] neg_hi:[1,0,0]
	ds_read_b128 v[200:203], v1 offset:45024
	s_waitcnt lgkmcnt(14)
	v_pk_fma_f32 v[242:243], v[18:19], v[246:247], v[242:243] neg_lo:[1,0,0] neg_hi:[1,0,0]
	v_pk_fma_f32 v[244:245], v[20:21], v[248:249], v[244:245] neg_lo:[1,0,0] neg_hi:[1,0,0]
	ds_read_b128 v[204:207], v1 offset:45152
	s_waitcnt lgkmcnt(14)
	v_pk_fma_f32 v[242:243], v[22:23], v[66:67], v[242:243] neg_lo:[1,0,0] neg_hi:[1,0,0]
	v_pk_fma_f32 v[244:245], v[24:25], v[68:69], v[244:245] neg_lo:[1,0,0] neg_hi:[1,0,0]
	ds_read_b128 v[246:249], v1 offset:45168
	s_waitcnt lgkmcnt(14)
	v_pk_fma_f32 v[242:243], v[26:27], v[70:71], v[242:243] neg_lo:[1,0,0] neg_hi:[1,0,0]
	v_pk_fma_f32 v[244:245], v[28:29], v[72:73], v[244:245] neg_lo:[1,0,0] neg_hi:[1,0,0]
	ds_read_b128 v[66:69], v1 offset:45184
	s_waitcnt lgkmcnt(14)
	v_pk_fma_f32 v[242:243], v[30:31], v[74:75], v[242:243] neg_lo:[1,0,0] neg_hi:[1,0,0]
	v_pk_fma_f32 v[244:245], v[32:33], v[76:77], v[244:245] neg_lo:[1,0,0] neg_hi:[1,0,0]
	ds_read_b128 v[70:73], v1 offset:45200
	s_waitcnt lgkmcnt(14)
	v_pk_fma_f32 v[242:243], v[34:35], v[78:79], v[242:243] neg_lo:[1,0,0] neg_hi:[1,0,0]
	v_pk_fma_f32 v[244:245], v[36:37], v[80:81], v[244:245] neg_lo:[1,0,0] neg_hi:[1,0,0]
	ds_read_b128 v[74:77], v1 offset:45216
	s_nop 0
	v_pk_add_f32 v[242:243], v[242:243], v[244:245]
	s_nop 0
	v_add_f32_e32 v242, v242, v243
	v_add_f32_e32 v38, v38, v242
	s_waitcnt lgkmcnt(14)
	v_pk_mul_f32 v[242:243], v[2:3], v[82:83] neg_lo:[1,0] neg_hi:[1,0]
	v_pk_mul_f32 v[244:245], v[4:5], v[84:85] neg_lo:[1,0] neg_hi:[1,0]
	ds_read_b128 v[78:81], v1 offset:45232
	s_waitcnt lgkmcnt(14)
	v_pk_fma_f32 v[242:243], v[6:7], v[86:87], v[242:243] neg_lo:[1,0,0] neg_hi:[1,0,0]
	v_pk_fma_f32 v[244:245], v[8:9], v[88:89], v[244:245] neg_lo:[1,0,0] neg_hi:[1,0,0]
	ds_read_b128 v[82:85], v1 offset:45248
	s_waitcnt lgkmcnt(14)
	v_pk_fma_f32 v[242:243], v[10:11], v[116:117], v[242:243] neg_lo:[1,0,0] neg_hi:[1,0,0]
	v_pk_fma_f32 v[244:245], v[12:13], v[118:119], v[244:245] neg_lo:[1,0,0] neg_hi:[1,0,0]
	ds_read_b128 v[86:89], v1 offset:45264
	s_waitcnt lgkmcnt(14)
; #define SUB_LROW(buf, i_, j0_, n_) do { _Pragma("unroll") for (int j4 = 0; j4 < (n_); ++j4) buf[j4] = *(const f32x4*)(Ls + (i_) * 68 + 4 * ((j0_) + j4)); } while (0)
; #define SUB_FROW(buf, j0_, n_) do { _Pragma("unroll") for (int j4 = 0; j4 < (n_); ++j4) { const f32x4 l = buf[j4]; \
;                 acc -= l.x * x[4 * ((j0_) + j4)]; acc -= l.y * x[4 * ((j0_) + j4) + 1]; acc -= l.z * x[4 * ((j0_) + j4) + 2]; acc -= l.w * x[4 * ((j0_) + j4) + 3]; } } while (0)
; __device__ __forceinline__ void gdn_prep(KA a, int layer, unsigned char* lds, const int tid_, const int bid_) {
;     ...
;             for (int i = 33; i < 64; ++i) {
;                 float acc = x[i];
;                 SUB_LROW(bufB, i, 8, (i + 3) / 4 - 8); __builtin_amdgcn_sched_barrier(0);
;                 SUB_FROW(bufA, 0, 8); __builtin_amdgcn_sched_barrier(0);
;                 if (i + 1 < 64) SUB_LROW(bufA, i + 1, 0, 8);
;                 __builtin_amdgcn_sched_barrier(0);
;                 SUB_FROW(bufB, 8, (i + 3) / 4 - 8);
;                 x[i] = acc;
;                 __builtin_amdgcn_sched_barrier(0);
;             }
	v_pk_fma_f32 v[242:243], v[14:15], v[120:121], v[242:243] neg_lo:[1,0,0] neg_hi:[1,0,0]
	v_pk_fma_f32 v[244:245], v[16:17], v[122:123], v[244:245] neg_lo:[1,0,0] neg_hi:[1,0,0]
	ds_read_b128 v[116:119], v1 offset:45280
	s_waitcnt lgkmcnt(14)
	v_pk_fma_f32 v[242:243], v[18:19], v[124:125], v[242:243] neg_lo:[1,0,0] neg_hi:[1,0,0]
	v_pk_fma_f32 v[244:245], v[20:21], v[126:127], v[244:245] neg_lo:[1,0,0] neg_hi:[1,0,0]
	ds_read_b128 v[120:123], v1 offset:45296
	s_waitcnt lgkmcnt(14)
	v_pk_fma_f32 v[242:243], v[22:23], v[128:129], v[242:243] neg_lo:[1,0,0] neg_hi:[1,0,0]
	v_pk_fma_f32 v[244:245], v[24:25], v[130:131], v[244:245] neg_lo:[1,0,0] neg_hi:[1,0,0]
	ds_read_b128 v[124:127], v1 offset:45424
	s_waitcnt lgkmcnt(14)
	v_pk_fma_f32 v[242:243], v[26:27], v[132:133], v[242:243] neg_lo:[1,0,0] neg_hi:[1,0,0]
	v_pk_fma_f32 v[244:245], v[28:29], v[134:135], v[244:245] neg_lo:[1,0,0] neg_hi:[1,0,0]
	ds_read_b128 v[128:131], v1 offset:45440
	s_waitcnt lgkmcnt(14)
	v_pk_fma_f32 v[242:243], v[30:31], v[136:137], v[242:243] neg_lo:[1,0,0] neg_hi:[1,0,0]
	v_pk_fma_f32 v[244:245], v[32:33], v[138:139], v[244:245] neg_lo:[1,0,0] neg_hi:[1,0,0]
	ds_read_b128 v[132:135], v1 offset:45456
	s_waitcnt lgkmcnt(14)
	v_pk_fma_f32 v[242:243], v[34:35], v[140:141], v[242:243] neg_lo:[1,0,0] neg_hi:[1,0,0]
	v_pk_fma_f32 v[244:245], v[36:37], v[142:143], v[244:245] neg_lo:[1,0,0] neg_hi:[1,0,0]
	ds_read_b128 v[136:139], v1 offset:45472
	s_waitcnt lgkmcnt(14)
	v_pk_fma_f32 v[242:243], v[38:39], v[200:201], v[242:243] neg_lo:[1,0,0] neg_hi:[1,0,0]
	v_pk_fma_f32 v[244:245], v[40:41], v[202:203], v[244:245] neg_lo:[1,0,0] neg_hi:[1,0,0]
	ds_read_b128 v[140:143], v1 offset:45488
	s_nop 0
	v_pk_add_f32 v[242:243], v[242:243], v[244:245]
	s_nop 0
	v_add_f32_e32 v242, v242, v243
	v_add_f32_e32 v39, v39, v242
	s_waitcnt lgkmcnt(14)
	v_pk_mul_f32 v[242:243], v[2:3], v[204:205] neg_lo:[1,0] neg_hi:[1,0]
	v_pk_mul_f32 v[244:245], v[4:5], v[206:207] neg_lo:[1,0] neg_hi:[1,0]
	ds_read_b128 v[200:203], v1 offset:45504
	s_waitcnt lgkmcnt(14)
	v_pk_fma_f32 v[242:243], v[6:7], v[246:247], v[242:243] neg_lo:[1,0,0] neg_hi:[1,0,0]
	v_pk_fma_f32 v[244:245], v[8:9], v[248:249], v[244:245] neg_lo:[1,0,0] neg_hi:[1,0,0]
	ds_read_b128 v[204:207], v1 offset:45520
	s_waitcnt lgkmcnt(14)
	v_pk_fma_f32 v[242:243], v[10:11], v[66:67], v[242:243] neg_lo:[1,0,0] neg_hi:[1,0,0]
	v_pk_fma_f32 v[244:245], v[12:13], v[68:69], v[244:245] neg_lo:[1,0,0] neg_hi:[1,0,0]
	ds_read_b128 v[246:249], v1 offset:45536
	s_waitcnt lgkmcnt(14)
	v_pk_fma_f32 v[242:243], v[14:15], v[70:71], v[242:243] neg_lo:[1,0,0] neg_hi:[1,0,0]
	v_pk_fma_f32 v[244:245], v[16:17], v[72:73], v[244:245] neg_lo:[1,0,0] neg_hi:[1,0,0]
	ds_read_b128 v[66:69], v1 offset:45552
	s_waitcnt lgkmcnt(14)
	v_pk_fma_f32 v[242:243], v[18:19], v[74:75], v[242:243] neg_lo:[1,0,0] neg_hi:[1,0,0]
	v_pk_fma_f32 v[244:245], v[20:21], v[76:77], v[244:245] neg_lo:[1,0,0] neg_hi:[1,0,0]
	ds_read_b128 v[70:73], v1 offset:45568
	s_waitcnt lgkmcnt(14)
	v_pk_fma_f32 v[242:243], v[22:23], v[78:79], v[242:243] neg_lo:[1,0,0] neg_hi:[1,0,0]
	v_pk_fma_f32 v[244:245], v[24:25], v[80:81], v[244:245] neg_lo:[1,0,0] neg_hi:[1,0,0]
	ds_read_b128 v[74:77], v1 offset:45696
	s_waitcnt lgkmcnt(14)
	v_pk_fma_f32 v[242:243], v[26:27], v[82:83], v[242:243] neg_lo:[1,0,0] neg_hi:[1,0,0]
	v_pk_fma_f32 v[244:245], v[28:29], v[84:85], v[244:245] neg_lo:[1,0,0] neg_hi:[1,0,0]
	ds_read_b128 v[78:81], v1 offset:45712
	s_waitcnt lgkmcnt(14)
	v_pk_fma_f32 v[242:243], v[30:31], v[86:87], v[242:243] neg_lo:[1,0,0] neg_hi:[1,0,0]
	v_pk_fma_f32 v[244:245], v[32:33], v[88:89], v[244:245] neg_lo:[1,0,0] neg_hi:[1,0,0]
	ds_read_b128 v[82:85], v1 offset:45728
	s_waitcnt lgkmcnt(14)
	v_pk_fma_f32 v[242:243], v[34:35], v[116:117], v[242:243] neg_lo:[1,0,0] neg_hi:[1,0,0]
	v_pk_fma_f32 v[244:245], v[36:37], v[118:119], v[244:245] neg_lo:[1,0,0] neg_hi:[1,0,0]
	ds_read_b128 v[86:89], v1 offset:45744
	s_waitcnt lgkmcnt(14)
	v_pk_fma_f32 v[242:243], v[38:39], v[120:121], v[242:243] neg_lo:[1,0,0] neg_hi:[1,0,0]
	v_pk_fma_f32 v[244:245], v[40:41], v[122:123], v[244:245] neg_lo:[1,0,0] neg_hi:[1,0,0]
	ds_read_b128 v[116:119], v1 offset:45760
	s_nop 0
	v_pk_add_f32 v[242:243], v[242:243], v[244:245]
	s_nop 0
	v_add_f32_e32 v242, v242, v243
	v_add_f32_e32 v40, v40, v242
	s_waitcnt lgkmcnt(14)
	v_pk_mul_f32 v[242:243], v[2:3], v[124:125] neg_lo:[1,0] neg_hi:[1,0]
	v_pk_mul_f32 v[244:245], v[4:5], v[126:127] neg_lo:[1,0] neg_hi:[1,0]
	ds_read_b128 v[120:123], v1 offset:45776
	s_waitcnt lgkmcnt(14)
	v_pk_fma_f32 v[242:243], v[6:7], v[128:129], v[242:243] neg_lo:[1,0,0] neg_hi:[1,0,0]
	v_pk_fma_f32 v[244:245], v[8:9], v[130:131], v[244:245] neg_lo:[1,0,0] neg_hi:[1,0,0]
	ds_read_b128 v[124:127], v1 offset:45792
	s_waitcnt lgkmcnt(14)
	v_pk_fma_f32 v[242:243], v[10:11], v[132:133], v[242:243] neg_lo:[1,0,0] neg_hi:[1,0,0]
	v_pk_fma_f32 v[244:245], v[12:13], v[134:135], v[244:245] neg_lo:[1,0,0] neg_hi:[1,0,0]
	ds_read_b128 v[128:131], v1 offset:45808
	s_waitcnt lgkmcnt(14)
	v_pk_fma_f32 v[242:243], v[14:15], v[136:137], v[242:243] neg_lo:[1,0,0] neg_hi:[1,0,0]
	v_pk_fma_f32 v[244:245], v[16:17], v[138:139], v[244:245] neg_lo:[1,0,0] neg_hi:[1,0,0]
	ds_read_b128 v[132:135], v1 offset:45824
	s_waitcnt lgkmcnt(14)
	v_pk_fma_f32 v[242:243], v[18:19], v[140:141], v[242:243] neg_lo:[1,0,0] neg_hi:[1,0,0]
	v_pk_fma_f32 v[244:245], v[20:21], v[142:143], v[244:245] neg_lo:[1,0,0] neg_hi:[1,0,0]
	ds_read_b128 v[136:139], v1 offset:45840
	s_waitcnt lgkmcnt(14)
	v_pk_fma_f32 v[242:243], v[22:23], v[200:201], v[242:243] neg_lo:[1,0,0] neg_hi:[1,0,0]
	v_pk_fma_f32 v[244:245], v[24:25], v[202:203], v[244:245] neg_lo:[1,0,0] neg_hi:[1,0,0]
	ds_read_b128 v[140:143], v1 offset:45968
	s_waitcnt lgkmcnt(14)
; #define SUB_LROW(buf, i_, j0_, n_) do { _Pragma("unroll") for (int j4 = 0; j4 < (n_); ++j4) buf[j4] = *(const f32x4*)(Ls + (i_) * 68 + 4 * ((j0_) + j4)); } while (0)
; #define SUB_FROW(buf, j0_, n_) do { _Pragma("unroll") for (int j4 = 0; j4 < (n_); ++j4) { const f32x4 l = buf[j4]; \
;                 acc -= l.x * x[4 * ((j0_) + j4)]; acc -= l.y * x[4 * ((j0_) + j4) + 1]; acc -= l.z * x[4 * ((j0_) + j4) + 2]; acc -= l.w * x[4 * ((j0_) + j4) + 3]; } } while (0)
; __device__ __forceinline__ void gdn_prep(KA a, int layer, unsigned char* lds, const int tid_, const int bid_) {
;     ...
;             for (int i = 33; i < 64; ++i) {
;                 float acc = x[i];
;                 SUB_LROW(bufB, i, 8, (i + 3) / 4 - 8); __builtin_amdgcn_sched_barrier(0);
;                 SUB_FROW(bufA, 0, 8); __builtin_amdgcn_sched_barrier(0);
;                 if (i + 1 < 64) SUB_LROW(bufA, i + 1, 0, 8);
;                 __builtin_amdgcn_sched_barrier(0);
;                 SUB_FROW(bufB, 8, (i + 3) / 4 - 8);
;                 x[i] = acc;
;                 __builtin_amdgcn_sched_barrier(0);
;             }
	v_pk_fma_f32 v[242:243], v[26:27], v[204:205], v[242:243] neg_lo:[1,0,0] neg_hi:[1,0,0]
	v_pk_fma_f32 v[244:245], v[28:29], v[206:207], v[244:245] neg_lo:[1,0,0] neg_hi:[1,0,0]
	ds_read_b128 v[200:203], v1 offset:45984
	s_waitcnt lgkmcnt(14)
	v_pk_fma_f32 v[242:243], v[30:31], v[246:247], v[242:243] neg_lo:[1,0,0] neg_hi:[1,0,0]
	v_pk_fma_f32 v[244:245], v[32:33], v[248:249], v[244:245] neg_lo:[1,0,0] neg_hi:[1,0,0]
	ds_read_b128 v[204:207], v1 offset:46000
	s_waitcnt lgkmcnt(14)
	v_pk_fma_f32 v[242:243], v[34:35], v[66:67], v[242:243] neg_lo:[1,0,0] neg_hi:[1,0,0]
	v_pk_fma_f32 v[244:245], v[36:37], v[68:69], v[244:245] neg_lo:[1,0,0] neg_hi:[1,0,0]
	ds_read_b128 v[246:249], v1 offset:46016
	s_waitcnt lgkmcnt(14)
	v_pk_fma_f32 v[242:243], v[38:39], v[70:71], v[242:243] neg_lo:[1,0,0] neg_hi:[1,0,0]
	v_pk_fma_f32 v[244:245], v[40:41], v[72:73], v[244:245] neg_lo:[1,0,0] neg_hi:[1,0,0]
	ds_read_b128 v[66:69], v1 offset:46032
	s_nop 0
	v_pk_add_f32 v[242:243], v[242:243], v[244:245]
	s_nop 0
	v_add_f32_e32 v242, v242, v243
	v_add_f32_e32 v41, v41, v242
	s_waitcnt lgkmcnt(14)
	v_pk_mul_f32 v[242:243], v[2:3], v[74:75] neg_lo:[1,0] neg_hi:[1,0]
	v_pk_mul_f32 v[244:245], v[4:5], v[76:77] neg_lo:[1,0] neg_hi:[1,0]
	ds_read_b128 v[70:73], v1 offset:46048
	s_waitcnt lgkmcnt(14)
	v_pk_fma_f32 v[242:243], v[6:7], v[78:79], v[242:243] neg_lo:[1,0,0] neg_hi:[1,0,0]
	v_pk_fma_f32 v[244:245], v[8:9], v[80:81], v[244:245] neg_lo:[1,0,0] neg_hi:[1,0,0]
	ds_read_b128 v[74:77], v1 offset:46064
	s_waitcnt lgkmcnt(14)
	v_pk_fma_f32 v[242:243], v[10:11], v[82:83], v[242:243] neg_lo:[1,0,0] neg_hi:[1,0,0]
	v_pk_fma_f32 v[244:245], v[12:13], v[84:85], v[244:245] neg_lo:[1,0,0] neg_hi:[1,0,0]
	ds_read_b128 v[78:81], v1 offset:46080
	s_waitcnt lgkmcnt(14)
	v_pk_fma_f32 v[242:243], v[14:15], v[86:87], v[242:243] neg_lo:[1,0,0] neg_hi:[1,0,0]
	v_pk_fma_f32 v[244:245], v[16:17], v[88:89], v[244:245] neg_lo:[1,0,0] neg_hi:[1,0,0]
	ds_read_b128 v[82:85], v1 offset:46096
	s_waitcnt lgkmcnt(14)
	v_pk_fma_f32 v[242:243], v[18:19], v[116:117], v[242:243] neg_lo:[1,0,0] neg_hi:[1,0,0]
	v_pk_fma_f32 v[244:245], v[20:21], v[118:119], v[244:245] neg_lo:[1,0,0] neg_hi:[1,0,0]
	ds_read_b128 v[86:89], v1 offset:46112
	s_waitcnt lgkmcnt(14)
	v_pk_fma_f32 v[242:243], v[22:23], v[120:121], v[242:243] neg_lo:[1,0,0] neg_hi:[1,0,0]
	v_pk_fma_f32 v[244:245], v[24:25], v[122:123], v[244:245] neg_lo:[1,0,0] neg_hi:[1,0,0]
	ds_read_b128 v[116:119], v1 offset:46128
	s_waitcnt lgkmcnt(14)
	v_pk_fma_f32 v[242:243], v[26:27], v[124:125], v[242:243] neg_lo:[1,0,0] neg_hi:[1,0,0]
	v_pk_fma_f32 v[244:245], v[28:29], v[126:127], v[244:245] neg_lo:[1,0,0] neg_hi:[1,0,0]
	ds_read_b128 v[120:123], v1 offset:46240
	s_waitcnt lgkmcnt(14)
	v_pk_fma_f32 v[242:243], v[30:31], v[128:129], v[242:243] neg_lo:[1,0,0] neg_hi:[1,0,0]
	v_pk_fma_f32 v[244:245], v[32:33], v[130:131], v[244:245] neg_lo:[1,0,0] neg_hi:[1,0,0]
	ds_read_b128 v[124:127], v1 offset:46256
	s_waitcnt lgkmcnt(14)
	v_pk_fma_f32 v[242:243], v[34:35], v[132:133], v[242:243] neg_lo:[1,0,0] neg_hi:[1,0,0]
	v_pk_fma_f32 v[244:245], v[36:37], v[134:135], v[244:245] neg_lo:[1,0,0] neg_hi:[1,0,0]
	ds_read_b128 v[128:131], v1 offset:46272
	s_waitcnt lgkmcnt(14)
	v_pk_fma_f32 v[242:243], v[38:39], v[136:137], v[242:243] neg_lo:[1,0,0] neg_hi:[1,0,0]
	v_pk_fma_f32 v[244:245], v[40:41], v[138:139], v[244:245] neg_lo:[1,0,0] neg_hi:[1,0,0]
	ds_read_b128 v[132:135], v1 offset:46288
	s_nop 0
	v_pk_add_f32 v[242:243], v[242:243], v[244:245]
	s_nop 0
	v_add_f32_e32 v242, v242, v243
	v_add_f32_e32 v42, v42, v242
	s_waitcnt lgkmcnt(14)
	v_pk_mul_f32 v[242:243], v[2:3], v[140:141] neg_lo:[1,0] neg_hi:[1,0]
	v_pk_mul_f32 v[244:245], v[4:5], v[142:143] neg_lo:[1,0] neg_hi:[1,0]
	ds_read_b128 v[136:139], v1 offset:46304
	s_waitcnt lgkmcnt(14)
	v_pk_fma_f32 v[242:243], v[6:7], v[200:201], v[242:243] neg_lo:[1,0,0] neg_hi:[1,0,0]
	v_pk_fma_f32 v[244:245], v[8:9], v[202:203], v[244:245] neg_lo:[1,0,0] neg_hi:[1,0,0]
	ds_read_b128 v[140:143], v1 offset:46320
	s_waitcnt lgkmcnt(14)
	v_pk_fma_f32 v[242:243], v[10:11], v[204:205], v[242:243] neg_lo:[1,0,0] neg_hi:[1,0,0]
	v_pk_fma_f32 v[244:245], v[12:13], v[206:207], v[244:245] neg_lo:[1,0,0] neg_hi:[1,0,0]
	ds_read_b128 v[200:203], v1 offset:46336
	s_waitcnt lgkmcnt(14)
	v_pk_fma_f32 v[242:243], v[14:15], v[246:247], v[242:243] neg_lo:[1,0,0] neg_hi:[1,0,0]
	v_pk_fma_f32 v[244:245], v[16:17], v[248:249], v[244:245] neg_lo:[1,0,0] neg_hi:[1,0,0]
	ds_read_b128 v[204:207], v1 offset:46352
	s_waitcnt lgkmcnt(14)
	v_pk_fma_f32 v[242:243], v[18:19], v[66:67], v[242:243] neg_lo:[1,0,0] neg_hi:[1,0,0]
	v_pk_fma_f32 v[244:245], v[20:21], v[68:69], v[244:245] neg_lo:[1,0,0] neg_hi:[1,0,0]
	ds_read_b128 v[246:249], v1 offset:46368
	s_waitcnt lgkmcnt(14)
	v_pk_fma_f32 v[242:243], v[22:23], v[70:71], v[242:243] neg_lo:[1,0,0] neg_hi:[1,0,0]
	v_pk_fma_f32 v[244:245], v[24:25], v[72:73], v[244:245] neg_lo:[1,0,0] neg_hi:[1,0,0]
	ds_read_b128 v[66:69], v1 offset:46384
	s_waitcnt lgkmcnt(14)
	v_pk_fma_f32 v[242:243], v[26:27], v[74:75], v[242:243] neg_lo:[1,0,0] neg_hi:[1,0,0]
	v_pk_fma_f32 v[244:245], v[28:29], v[76:77], v[244:245] neg_lo:[1,0,0] neg_hi:[1,0,0]
	ds_read_b128 v[70:73], v1 offset:46400
	s_waitcnt lgkmcnt(14)
	v_pk_fma_f32 v[242:243], v[30:31], v[78:79], v[242:243] neg_lo:[1,0,0] neg_hi:[1,0,0]
	v_pk_fma_f32 v[244:245], v[32:33], v[80:81], v[244:245] neg_lo:[1,0,0] neg_hi:[1,0,0]
	ds_read_b128 v[74:77], v1 offset:46512
	s_waitcnt lgkmcnt(14)
	v_pk_fma_f32 v[242:243], v[34:35], v[82:83], v[242:243] neg_lo:[1,0,0] neg_hi:[1,0,0]
	v_pk_fma_f32 v[244:245], v[36:37], v[84:85], v[244:245] neg_lo:[1,0,0] neg_hi:[1,0,0]
	ds_read_b128 v[78:81], v1 offset:46528
	s_waitcnt lgkmcnt(14)
; #define SUB_LROW(buf, i_, j0_, n_) do { _Pragma("unroll") for (int j4 = 0; j4 < (n_); ++j4) buf[j4] = *(const f32x4*)(Ls + (i_) * 68 + 4 * ((j0_) + j4)); } while (0)
; #define SUB_FROW(buf, j0_, n_) do { _Pragma("unroll") for (int j4 = 0; j4 < (n_); ++j4) { const f32x4 l = buf[j4]; \
;                 acc -= l.x * x[4 * ((j0_) + j4)]; acc -= l.y * x[4 * ((j0_) + j4) + 1]; acc -= l.z * x[4 * ((j0_) + j4) + 2]; acc -= l.w * x[4 * ((j0_) + j4) + 3]; } } while (0)
; __device__ __forceinline__ void gdn_prep(KA a, int layer, unsigned char* lds, const int tid_, const int bid_) {
;     ...
;             for (int i = 33; i < 64; ++i) {
;                 float acc = x[i];
;                 SUB_LROW(bufB, i, 8, (i + 3) / 4 - 8); __builtin_amdgcn_sched_barrier(0);
;                 SUB_FROW(bufA, 0, 8); __builtin_amdgcn_sched_barrier(0);
;                 if (i + 1 < 64) SUB_LROW(bufA, i + 1, 0, 8);
;                 __builtin_amdgcn_sched_barrier(0);
;                 SUB_FROW(bufB, 8, (i + 3) / 4 - 8);
;                 x[i] = acc;
;                 __builtin_amdgcn_sched_barrier(0);
;             }
	v_pk_fma_f32 v[242:243], v[38:39], v[86:87], v[242:243] neg_lo:[1,0,0] neg_hi:[1,0,0]
	v_pk_fma_f32 v[244:245], v[40:41], v[88:89], v[244:245] neg_lo:[1,0,0] neg_hi:[1,0,0]
	ds_read_b128 v[82:85], v1 offset:46544
	s_waitcnt lgkmcnt(14)
	v_pk_fma_f32 v[242:243], v[42:43], v[116:117], v[242:243] neg_lo:[1,0,0] neg_hi:[1,0,0]
	v_pk_fma_f32 v[244:245], v[44:45], v[118:119], v[244:245] neg_lo:[1,0,0] neg_hi:[1,0,0]
	ds_read_b128 v[86:89], v1 offset:46560
	s_nop 0
	v_pk_add_f32 v[242:243], v[242:243], v[244:245]
	s_nop 0
	v_add_f32_e32 v242, v242, v243
	v_add_f32_e32 v43, v43, v242
	s_waitcnt lgkmcnt(14)
	v_pk_mul_f32 v[242:243], v[2:3], v[120:121] neg_lo:[1,0] neg_hi:[1,0]
	v_pk_mul_f32 v[244:245], v[4:5], v[122:123] neg_lo:[1,0] neg_hi:[1,0]
	ds_read_b128 v[116:119], v1 offset:46576
	s_waitcnt lgkmcnt(14)
	v_pk_fma_f32 v[242:243], v[6:7], v[124:125], v[242:243] neg_lo:[1,0,0] neg_hi:[1,0,0]
	v_pk_fma_f32 v[244:245], v[8:9], v[126:127], v[244:245] neg_lo:[1,0,0] neg_hi:[1,0,0]
	ds_read_b128 v[120:123], v1 offset:46592
	s_waitcnt lgkmcnt(14)
	v_pk_fma_f32 v[242:243], v[10:11], v[128:129], v[242:243] neg_lo:[1,0,0] neg_hi:[1,0,0]
	v_pk_fma_f32 v[244:245], v[12:13], v[130:131], v[244:245] neg_lo:[1,0,0] neg_hi:[1,0,0]
	ds_read_b128 v[124:127], v1 offset:46608
	s_waitcnt lgkmcnt(14)
	v_pk_fma_f32 v[242:243], v[14:15], v[132:133], v[242:243] neg_lo:[1,0,0] neg_hi:[1,0,0]
	v_pk_fma_f32 v[244:245], v[16:17], v[134:135], v[244:245] neg_lo:[1,0,0] neg_hi:[1,0,0]
	ds_read_b128 v[128:131], v1 offset:46624
	s_waitcnt lgkmcnt(14)
	v_pk_fma_f32 v[242:243], v[18:19], v[136:137], v[242:243] neg_lo:[1,0,0] neg_hi:[1,0,0]
	v_pk_fma_f32 v[244:245], v[20:21], v[138:139], v[244:245] neg_lo:[1,0,0] neg_hi:[1,0,0]
	ds_read_b128 v[132:135], v1 offset:46640
	s_waitcnt lgkmcnt(14)
	v_pk_fma_f32 v[242:243], v[22:23], v[140:141], v[242:243] neg_lo:[1,0,0] neg_hi:[1,0,0]
	v_pk_fma_f32 v[244:245], v[24:25], v[142:143], v[244:245] neg_lo:[1,0,0] neg_hi:[1,0,0]
	ds_read_b128 v[136:139], v1 offset:46656
	s_waitcnt lgkmcnt(14)
	v_pk_fma_f32 v[242:243], v[26:27], v[200:201], v[242:243] neg_lo:[1,0,0] neg_hi:[1,0,0]
	v_pk_fma_f32 v[244:245], v[28:29], v[202:203], v[244:245] neg_lo:[1,0,0] neg_hi:[1,0,0]
	ds_read_b128 v[140:143], v1 offset:46672
	s_waitcnt lgkmcnt(14)
	v_pk_fma_f32 v[242:243], v[30:31], v[204:205], v[242:243] neg_lo:[1,0,0] neg_hi:[1,0,0]
	v_pk_fma_f32 v[244:245], v[32:33], v[206:207], v[244:245] neg_lo:[1,0,0] neg_hi:[1,0,0]
	ds_read_b128 v[200:203], v1 offset:46784
	s_waitcnt lgkmcnt(14)
	v_pk_fma_f32 v[242:243], v[34:35], v[246:247], v[242:243] neg_lo:[1,0,0] neg_hi:[1,0,0]
	v_pk_fma_f32 v[244:245], v[36:37], v[248:249], v[244:245] neg_lo:[1,0,0] neg_hi:[1,0,0]
	ds_read_b128 v[204:207], v1 offset:46800
	s_waitcnt lgkmcnt(14)
	v_pk_fma_f32 v[242:243], v[38:39], v[66:67], v[242:243] neg_lo:[1,0,0] neg_hi:[1,0,0]
	v_pk_fma_f32 v[244:245], v[40:41], v[68:69], v[244:245] neg_lo:[1,0,0] neg_hi:[1,0,0]
	ds_read_b128 v[246:249], v1 offset:46816
	s_waitcnt lgkmcnt(14)
	v_pk_fma_f32 v[242:243], v[42:43], v[70:71], v[242:243] neg_lo:[1,0,0] neg_hi:[1,0,0]
	v_pk_fma_f32 v[244:245], v[44:45], v[72:73], v[244:245] neg_lo:[1,0,0] neg_hi:[1,0,0]
	ds_read_b128 v[66:69], v1 offset:46832
	s_nop 0
	v_pk_add_f32 v[242:243], v[242:243], v[244:245]
	s_nop 0
	v_add_f32_e32 v242, v242, v243
	v_add_f32_e32 v44, v44, v242
	s_waitcnt lgkmcnt(14)
	v_pk_mul_f32 v[242:243], v[2:3], v[74:75] neg_lo:[1,0] neg_hi:[1,0]
	v_pk_mul_f32 v[244:245], v[4:5], v[76:77] neg_lo:[1,0] neg_hi:[1,0]
	ds_read_b128 v[70:73], v1 offset:46848
	s_waitcnt lgkmcnt(14)
	v_pk_fma_f32 v[242:243], v[6:7], v[78:79], v[242:243] neg_lo:[1,0,0] neg_hi:[1,0,0]
	v_pk_fma_f32 v[244:245], v[8:9], v[80:81], v[244:245] neg_lo:[1,0,0] neg_hi:[1,0,0]
	ds_read_b128 v[74:77], v1 offset:46864
	s_waitcnt lgkmcnt(14)
	v_pk_fma_f32 v[242:243], v[10:11], v[82:83], v[242:243] neg_lo:[1,0,0] neg_hi:[1,0,0]
	v_pk_fma_f32 v[244:245], v[12:13], v[84:85], v[244:245] neg_lo:[1,0,0] neg_hi:[1,0,0]
	ds_read_b128 v[78:81], v1 offset:46880
	s_waitcnt lgkmcnt(14)
	v_pk_fma_f32 v[242:243], v[14:15], v[86:87], v[242:243] neg_lo:[1,0,0] neg_hi:[1,0,0]
	v_pk_fma_f32 v[244:245], v[16:17], v[88:89], v[244:245] neg_lo:[1,0,0] neg_hi:[1,0,0]
	ds_read_b128 v[82:85], v1 offset:46896
	s_waitcnt lgkmcnt(14)
	v_pk_fma_f32 v[242:243], v[18:19], v[116:117], v[242:243] neg_lo:[1,0,0] neg_hi:[1,0,0]
	v_pk_fma_f32 v[244:245], v[20:21], v[118:119], v[244:245] neg_lo:[1,0,0] neg_hi:[1,0,0]
	ds_read_b128 v[86:89], v1 offset:46912
	s_waitcnt lgkmcnt(14)
	v_pk_fma_f32 v[242:243], v[22:23], v[120:121], v[242:243] neg_lo:[1,0,0] neg_hi:[1,0,0]
	v_pk_fma_f32 v[244:245], v[24:25], v[122:123], v[244:245] neg_lo:[1,0,0] neg_hi:[1,0,0]
	ds_read_b128 v[116:119], v1 offset:46928
	s_waitcnt lgkmcnt(14)
	v_pk_fma_f32 v[242:243], v[26:27], v[124:125], v[242:243] neg_lo:[1,0,0] neg_hi:[1,0,0]
	v_pk_fma_f32 v[244:245], v[28:29], v[126:127], v[244:245] neg_lo:[1,0,0] neg_hi:[1,0,0]
	ds_read_b128 v[120:123], v1 offset:46944
	s_waitcnt lgkmcnt(14)
	v_pk_fma_f32 v[242:243], v[30:31], v[128:129], v[242:243] neg_lo:[1,0,0] neg_hi:[1,0,0]
	v_pk_fma_f32 v[244:245], v[32:33], v[130:131], v[244:245] neg_lo:[1,0,0] neg_hi:[1,0,0]
	ds_read_b128 v[124:127], v1 offset:47056
	s_waitcnt lgkmcnt(14)
	v_pk_fma_f32 v[242:243], v[34:35], v[132:133], v[242:243] neg_lo:[1,0,0] neg_hi:[1,0,0]
	v_pk_fma_f32 v[244:245], v[36:37], v[134:135], v[244:245] neg_lo:[1,0,0] neg_hi:[1,0,0]
	ds_read_b128 v[128:131], v1 offset:47072
	s_waitcnt lgkmcnt(14)
	v_pk_fma_f32 v[242:243], v[38:39], v[136:137], v[242:243] neg_lo:[1,0,0] neg_hi:[1,0,0]
	v_pk_fma_f32 v[244:245], v[40:41], v[138:139], v[244:245] neg_lo:[1,0,0] neg_hi:[1,0,0]
	ds_read_b128 v[132:135], v1 offset:47088
	s_waitcnt lgkmcnt(14)
; #define SUB_LROW(buf, i_, j0_, n_) do { _Pragma("unroll") for (int j4 = 0; j4 < (n_); ++j4) buf[j4] = *(const f32x4*)(Ls + (i_) * 68 + 4 * ((j0_) + j4)); } while (0)
; #define SUB_FROW(buf, j0_, n_) do { _Pragma("unroll") for (int j4 = 0; j4 < (n_); ++j4) { const f32x4 l = buf[j4]; \
;                 acc -= l.x * x[4 * ((j0_) + j4)]; acc -= l.y * x[4 * ((j0_) + j4) + 1]; acc -= l.z * x[4 * ((j0_) + j4) + 2]; acc -= l.w * x[4 * ((j0_) + j4) + 3]; } } while (0)
; __device__ __forceinline__ void gdn_prep(KA a, int layer, unsigned char* lds, const int tid_, const int bid_) {
;     ...
;             for (int i = 33; i < 64; ++i) {
;                 float acc = x[i];
;                 SUB_LROW(bufB, i, 8, (i + 3) / 4 - 8); __builtin_amdgcn_sched_barrier(0);
;                 SUB_FROW(bufA, 0, 8); __builtin_amdgcn_sched_barrier(0);
;                 if (i + 1 < 64) SUB_LROW(bufA, i + 1, 0, 8);
;                 __builtin_amdgcn_sched_barrier(0);
;                 SUB_FROW(bufB, 8, (i + 3) / 4 - 8);
;                 x[i] = acc;
;                 __builtin_amdgcn_sched_barrier(0);
;             }
	v_pk_fma_f32 v[242:243], v[42:43], v[140:141], v[242:243] neg_lo:[1,0,0] neg_hi:[1,0,0]
	v_pk_fma_f32 v[244:245], v[44:45], v[142:143], v[244:245] neg_lo:[1,0,0] neg_hi:[1,0,0]
	ds_read_b128 v[136:139], v1 offset:47104
	s_nop 0
	v_pk_add_f32 v[242:243], v[242:243], v[244:245]
	s_nop 0
	v_add_f32_e32 v242, v242, v243
	v_add_f32_e32 v45, v45, v242
	s_waitcnt lgkmcnt(14)
	v_pk_mul_f32 v[242:243], v[2:3], v[200:201] neg_lo:[1,0] neg_hi:[1,0]
	v_pk_mul_f32 v[244:245], v[4:5], v[202:203] neg_lo:[1,0] neg_hi:[1,0]
	ds_read_b128 v[140:143], v1 offset:47120
	s_waitcnt lgkmcnt(14)
	v_pk_fma_f32 v[242:243], v[6:7], v[204:205], v[242:243] neg_lo:[1,0,0] neg_hi:[1,0,0]
	v_pk_fma_f32 v[244:245], v[8:9], v[206:207], v[244:245] neg_lo:[1,0,0] neg_hi:[1,0,0]
	ds_read_b128 v[200:203], v1 offset:47136
	s_waitcnt lgkmcnt(14)
	v_pk_fma_f32 v[242:243], v[10:11], v[246:247], v[242:243] neg_lo:[1,0,0] neg_hi:[1,0,0]
	v_pk_fma_f32 v[244:245], v[12:13], v[248:249], v[244:245] neg_lo:[1,0,0] neg_hi:[1,0,0]
	ds_read_b128 v[204:207], v1 offset:47152
	s_waitcnt lgkmcnt(14)
	v_pk_fma_f32 v[242:243], v[14:15], v[66:67], v[242:243] neg_lo:[1,0,0] neg_hi:[1,0,0]
	v_pk_fma_f32 v[244:245], v[16:17], v[68:69], v[244:245] neg_lo:[1,0,0] neg_hi:[1,0,0]
	ds_read_b128 v[246:249], v1 offset:47168
	s_waitcnt lgkmcnt(14)
	v_pk_fma_f32 v[242:243], v[18:19], v[70:71], v[242:243] neg_lo:[1,0,0] neg_hi:[1,0,0]
	v_pk_fma_f32 v[244:245], v[20:21], v[72:73], v[244:245] neg_lo:[1,0,0] neg_hi:[1,0,0]
	ds_read_b128 v[66:69], v1 offset:47184
	s_waitcnt lgkmcnt(14)
	v_pk_fma_f32 v[242:243], v[22:23], v[74:75], v[242:243] neg_lo:[1,0,0] neg_hi:[1,0,0]
	v_pk_fma_f32 v[244:245], v[24:25], v[76:77], v[244:245] neg_lo:[1,0,0] neg_hi:[1,0,0]
	ds_read_b128 v[70:73], v1 offset:47200
	s_waitcnt lgkmcnt(14)
	v_pk_fma_f32 v[242:243], v[26:27], v[78:79], v[242:243] neg_lo:[1,0,0] neg_hi:[1,0,0]
	v_pk_fma_f32 v[244:245], v[28:29], v[80:81], v[244:245] neg_lo:[1,0,0] neg_hi:[1,0,0]
	ds_read_b128 v[74:77], v1 offset:47216
	s_waitcnt lgkmcnt(14)
	v_pk_fma_f32 v[242:243], v[30:31], v[82:83], v[242:243] neg_lo:[1,0,0] neg_hi:[1,0,0]
	v_pk_fma_f32 v[244:245], v[32:33], v[84:85], v[244:245] neg_lo:[1,0,0] neg_hi:[1,0,0]
	ds_read_b128 v[78:81], v1 offset:47232
	s_waitcnt lgkmcnt(14)
	v_pk_fma_f32 v[242:243], v[34:35], v[86:87], v[242:243] neg_lo:[1,0,0] neg_hi:[1,0,0]
	v_pk_fma_f32 v[244:245], v[36:37], v[88:89], v[244:245] neg_lo:[1,0,0] neg_hi:[1,0,0]
	ds_read_b128 v[82:85], v1 offset:47328
	s_waitcnt lgkmcnt(14)
	v_pk_fma_f32 v[242:243], v[38:39], v[116:117], v[242:243] neg_lo:[1,0,0] neg_hi:[1,0,0]
	v_pk_fma_f32 v[244:245], v[40:41], v[118:119], v[244:245] neg_lo:[1,0,0] neg_hi:[1,0,0]
	ds_read_b128 v[86:89], v1 offset:47344
	s_waitcnt lgkmcnt(14)
	v_pk_fma_f32 v[242:243], v[42:43], v[120:121], v[242:243] neg_lo:[1,0,0] neg_hi:[1,0,0]
	v_pk_fma_f32 v[244:245], v[44:45], v[122:123], v[244:245] neg_lo:[1,0,0] neg_hi:[1,0,0]
	ds_read_b128 v[116:119], v1 offset:47360
	s_nop 0
	v_pk_add_f32 v[242:243], v[242:243], v[244:245]
	s_nop 0
	v_add_f32_e32 v242, v242, v243
	v_add_f32_e32 v46, v46, v242
	s_waitcnt lgkmcnt(14)
	v_pk_mul_f32 v[242:243], v[2:3], v[124:125] neg_lo:[1,0] neg_hi:[1,0]
	v_pk_mul_f32 v[244:245], v[4:5], v[126:127] neg_lo:[1,0] neg_hi:[1,0]
	ds_read_b128 v[120:123], v1 offset:47376
	s_waitcnt lgkmcnt(14)
	v_pk_fma_f32 v[242:243], v[6:7], v[128:129], v[242:243] neg_lo:[1,0,0] neg_hi:[1,0,0]
	v_pk_fma_f32 v[244:245], v[8:9], v[130:131], v[244:245] neg_lo:[1,0,0] neg_hi:[1,0,0]
	ds_read_b128 v[124:127], v1 offset:47392
	s_waitcnt lgkmcnt(14)
	v_pk_fma_f32 v[242:243], v[10:11], v[132:133], v[242:243] neg_lo:[1,0,0] neg_hi:[1,0,0]
	v_pk_fma_f32 v[244:245], v[12:13], v[134:135], v[244:245] neg_lo:[1,0,0] neg_hi:[1,0,0]
	ds_read_b128 v[128:131], v1 offset:47408
	s_waitcnt lgkmcnt(14)
	v_pk_fma_f32 v[242:243], v[14:15], v[136:137], v[242:243] neg_lo:[1,0,0] neg_hi:[1,0,0]
	v_pk_fma_f32 v[244:245], v[16:17], v[138:139], v[244:245] neg_lo:[1,0,0] neg_hi:[1,0,0]
	ds_read_b128 v[132:135], v1 offset:47424
	s_waitcnt lgkmcnt(14)
	v_pk_fma_f32 v[242:243], v[18:19], v[140:141], v[242:243] neg_lo:[1,0,0] neg_hi:[1,0,0]
	v_pk_fma_f32 v[244:245], v[20:21], v[142:143], v[244:245] neg_lo:[1,0,0] neg_hi:[1,0,0]
	ds_read_b128 v[136:139], v1 offset:47440
	s_waitcnt lgkmcnt(14)
	v_pk_fma_f32 v[242:243], v[22:23], v[200:201], v[242:243] neg_lo:[1,0,0] neg_hi:[1,0,0]
	v_pk_fma_f32 v[244:245], v[24:25], v[202:203], v[244:245] neg_lo:[1,0,0] neg_hi:[1,0,0]
	ds_read_b128 v[140:143], v1 offset:47456
	s_waitcnt lgkmcnt(14)
	v_pk_fma_f32 v[242:243], v[26:27], v[204:205], v[242:243] neg_lo:[1,0,0] neg_hi:[1,0,0]
	v_pk_fma_f32 v[244:245], v[28:29], v[206:207], v[244:245] neg_lo:[1,0,0] neg_hi:[1,0,0]
	ds_read_b128 v[200:203], v1 offset:47472
	s_waitcnt lgkmcnt(14)
	v_pk_fma_f32 v[242:243], v[30:31], v[246:247], v[242:243] neg_lo:[1,0,0] neg_hi:[1,0,0]
	v_pk_fma_f32 v[244:245], v[32:33], v[248:249], v[244:245] neg_lo:[1,0,0] neg_hi:[1,0,0]
	ds_read_b128 v[204:207], v1 offset:47488
	s_waitcnt lgkmcnt(14)
	v_pk_fma_f32 v[242:243], v[34:35], v[66:67], v[242:243] neg_lo:[1,0,0] neg_hi:[1,0,0]
	v_pk_fma_f32 v[244:245], v[36:37], v[68:69], v[244:245] neg_lo:[1,0,0] neg_hi:[1,0,0]
	ds_read_b128 v[246:249], v1 offset:47504
	s_waitcnt lgkmcnt(14)
	v_pk_fma_f32 v[242:243], v[38:39], v[70:71], v[242:243] neg_lo:[1,0,0] neg_hi:[1,0,0]
	v_pk_fma_f32 v[244:245], v[40:41], v[72:73], v[244:245] neg_lo:[1,0,0] neg_hi:[1,0,0]
	ds_read_b128 v[66:69], v1 offset:47600
	s_waitcnt lgkmcnt(14)
	v_pk_fma_f32 v[242:243], v[42:43], v[74:75], v[242:243] neg_lo:[1,0,0] neg_hi:[1,0,0]
	v_pk_fma_f32 v[244:245], v[44:45], v[76:77], v[244:245] neg_lo:[1,0,0] neg_hi:[1,0,0]
	ds_read_b128 v[70:73], v1 offset:47616
	s_waitcnt lgkmcnt(14)
; #define SUB_LROW(buf, i_, j0_, n_) do { _Pragma("unroll") for (int j4 = 0; j4 < (n_); ++j4) buf[j4] = *(const f32x4*)(Ls + (i_) * 68 + 4 * ((j0_) + j4)); } while (0)
; #define SUB_FROW(buf, j0_, n_) do { _Pragma("unroll") for (int j4 = 0; j4 < (n_); ++j4) { const f32x4 l = buf[j4]; \
;                 acc -= l.x * x[4 * ((j0_) + j4)]; acc -= l.y * x[4 * ((j0_) + j4) + 1]; acc -= l.z * x[4 * ((j0_) + j4) + 2]; acc -= l.w * x[4 * ((j0_) + j4) + 3]; } } while (0)
; __device__ __forceinline__ void gdn_prep(KA a, int layer, unsigned char* lds, const int tid_, const int bid_) {
;     ...
;             for (int i = 33; i < 64; ++i) {
;                 float acc = x[i];
;                 SUB_LROW(bufB, i, 8, (i + 3) / 4 - 8); __builtin_amdgcn_sched_barrier(0);
;                 SUB_FROW(bufA, 0, 8); __builtin_amdgcn_sched_barrier(0);
;                 if (i + 1 < 64) SUB_LROW(bufA, i + 1, 0, 8);
;                 __builtin_amdgcn_sched_barrier(0);
;                 SUB_FROW(bufB, 8, (i + 3) / 4 - 8);
;                 x[i] = acc;
;                 __builtin_amdgcn_sched_barrier(0);
;             }
	v_pk_fma_f32 v[242:243], v[46:47], v[78:79], v[242:243] neg_lo:[1,0,0] neg_hi:[1,0,0]
	v_pk_fma_f32 v[244:245], v[48:49], v[80:81], v[244:245] neg_lo:[1,0,0] neg_hi:[1,0,0]
	ds_read_b128 v[74:77], v1 offset:47632
	s_nop 0
	v_pk_add_f32 v[242:243], v[242:243], v[244:245]
	s_nop 0
	v_add_f32_e32 v242, v242, v243
	v_add_f32_e32 v47, v47, v242
	s_waitcnt lgkmcnt(14)
	v_pk_mul_f32 v[242:243], v[2:3], v[82:83] neg_lo:[1,0] neg_hi:[1,0]
	v_pk_mul_f32 v[244:245], v[4:5], v[84:85] neg_lo:[1,0] neg_hi:[1,0]
	ds_read_b128 v[78:81], v1 offset:47648
	s_waitcnt lgkmcnt(14)
	v_pk_fma_f32 v[242:243], v[6:7], v[86:87], v[242:243] neg_lo:[1,0,0] neg_hi:[1,0,0]
	v_pk_fma_f32 v[244:245], v[8:9], v[88:89], v[244:245] neg_lo:[1,0,0] neg_hi:[1,0,0]
	ds_read_b128 v[82:85], v1 offset:47664
	s_waitcnt lgkmcnt(14)
	v_pk_fma_f32 v[242:243], v[10:11], v[116:117], v[242:243] neg_lo:[1,0,0] neg_hi:[1,0,0]
	v_pk_fma_f32 v[244:245], v[12:13], v[118:119], v[244:245] neg_lo:[1,0,0] neg_hi:[1,0,0]
	ds_read_b128 v[86:89], v1 offset:47680
	s_waitcnt lgkmcnt(14)
	v_pk_fma_f32 v[242:243], v[14:15], v[120:121], v[242:243] neg_lo:[1,0,0] neg_hi:[1,0,0]
	v_pk_fma_f32 v[244:245], v[16:17], v[122:123], v[244:245] neg_lo:[1,0,0] neg_hi:[1,0,0]
	ds_read_b128 v[116:119], v1 offset:47696
	s_waitcnt lgkmcnt(14)
	v_pk_fma_f32 v[242:243], v[18:19], v[124:125], v[242:243] neg_lo:[1,0,0] neg_hi:[1,0,0]
	v_pk_fma_f32 v[244:245], v[20:21], v[126:127], v[244:245] neg_lo:[1,0,0] neg_hi:[1,0,0]
	ds_read_b128 v[120:123], v1 offset:47712
	s_waitcnt lgkmcnt(14)
	v_pk_fma_f32 v[242:243], v[22:23], v[128:129], v[242:243] neg_lo:[1,0,0] neg_hi:[1,0,0]
	v_pk_fma_f32 v[244:245], v[24:25], v[130:131], v[244:245] neg_lo:[1,0,0] neg_hi:[1,0,0]
	ds_read_b128 v[124:127], v1 offset:47728
	s_waitcnt lgkmcnt(14)
	v_pk_fma_f32 v[242:243], v[26:27], v[132:133], v[242:243] neg_lo:[1,0,0] neg_hi:[1,0,0]
	v_pk_fma_f32 v[244:245], v[28:29], v[134:135], v[244:245] neg_lo:[1,0,0] neg_hi:[1,0,0]
	ds_read_b128 v[128:131], v1 offset:47744
	s_waitcnt lgkmcnt(14)
	v_pk_fma_f32 v[242:243], v[30:31], v[136:137], v[242:243] neg_lo:[1,0,0] neg_hi:[1,0,0]
	v_pk_fma_f32 v[244:245], v[32:33], v[138:139], v[244:245] neg_lo:[1,0,0] neg_hi:[1,0,0]
	ds_read_b128 v[132:135], v1 offset:47760
	s_waitcnt lgkmcnt(14)
	v_pk_fma_f32 v[242:243], v[34:35], v[140:141], v[242:243] neg_lo:[1,0,0] neg_hi:[1,0,0]
	v_pk_fma_f32 v[244:245], v[36:37], v[142:143], v[244:245] neg_lo:[1,0,0] neg_hi:[1,0,0]
	ds_read_b128 v[136:139], v1 offset:47776
	s_waitcnt lgkmcnt(14)
	v_pk_fma_f32 v[242:243], v[38:39], v[200:201], v[242:243] neg_lo:[1,0,0] neg_hi:[1,0,0]
	v_pk_fma_f32 v[244:245], v[40:41], v[202:203], v[244:245] neg_lo:[1,0,0] neg_hi:[1,0,0]
	ds_read_b128 v[140:143], v1 offset:47872
	s_waitcnt lgkmcnt(14)
	v_pk_fma_f32 v[242:243], v[42:43], v[204:205], v[242:243] neg_lo:[1,0,0] neg_hi:[1,0,0]
	v_pk_fma_f32 v[244:245], v[44:45], v[206:207], v[244:245] neg_lo:[1,0,0] neg_hi:[1,0,0]
	ds_read_b128 v[200:203], v1 offset:47888
	s_waitcnt lgkmcnt(14)
	v_pk_fma_f32 v[242:243], v[46:47], v[246:247], v[242:243] neg_lo:[1,0,0] neg_hi:[1,0,0]
	v_pk_fma_f32 v[244:245], v[48:49], v[248:249], v[244:245] neg_lo:[1,0,0] neg_hi:[1,0,0]
	ds_read_b128 v[204:207], v1 offset:47904
	s_nop 0
	v_pk_add_f32 v[242:243], v[242:243], v[244:245]
	s_nop 0
	v_add_f32_e32 v242, v242, v243
	v_add_f32_e32 v48, v48, v242
	s_waitcnt lgkmcnt(14)
	v_pk_mul_f32 v[242:243], v[2:3], v[66:67] neg_lo:[1,0] neg_hi:[1,0]
	v_pk_mul_f32 v[244:245], v[4:5], v[68:69] neg_lo:[1,0] neg_hi:[1,0]
	ds_read_b128 v[246:249], v1 offset:47920
	s_waitcnt lgkmcnt(14)
	v_pk_fma_f32 v[242:243], v[6:7], v[70:71], v[242:243] neg_lo:[1,0,0] neg_hi:[1,0,0]
	v_pk_fma_f32 v[244:245], v[8:9], v[72:73], v[244:245] neg_lo:[1,0,0] neg_hi:[1,0,0]
	ds_read_b128 v[66:69], v1 offset:47936
	s_waitcnt lgkmcnt(14)
	v_pk_fma_f32 v[242:243], v[10:11], v[74:75], v[242:243] neg_lo:[1,0,0] neg_hi:[1,0,0]
	v_pk_fma_f32 v[244:245], v[12:13], v[76:77], v[244:245] neg_lo:[1,0,0] neg_hi:[1,0,0]
	ds_read_b128 v[70:73], v1 offset:47952
	s_waitcnt lgkmcnt(14)
	v_pk_fma_f32 v[242:243], v[14:15], v[78:79], v[242:243] neg_lo:[1,0,0] neg_hi:[1,0,0]
	v_pk_fma_f32 v[244:245], v[16:17], v[80:81], v[244:245] neg_lo:[1,0,0] neg_hi:[1,0,0]
	ds_read_b128 v[74:77], v1 offset:47968
	s_waitcnt lgkmcnt(14)
	v_pk_fma_f32 v[242:243], v[18:19], v[82:83], v[242:243] neg_lo:[1,0,0] neg_hi:[1,0,0]
	v_pk_fma_f32 v[244:245], v[20:21], v[84:85], v[244:245] neg_lo:[1,0,0] neg_hi:[1,0,0]
	ds_read_b128 v[78:81], v1 offset:47984
	s_waitcnt lgkmcnt(14)
	v_pk_fma_f32 v[242:243], v[22:23], v[86:87], v[242:243] neg_lo:[1,0,0] neg_hi:[1,0,0]
	v_pk_fma_f32 v[244:245], v[24:25], v[88:89], v[244:245] neg_lo:[1,0,0] neg_hi:[1,0,0]
	ds_read_b128 v[82:85], v1 offset:48000
	s_waitcnt lgkmcnt(14)
	v_pk_fma_f32 v[242:243], v[26:27], v[116:117], v[242:243] neg_lo:[1,0,0] neg_hi:[1,0,0]
	v_pk_fma_f32 v[244:245], v[28:29], v[118:119], v[244:245] neg_lo:[1,0,0] neg_hi:[1,0,0]
	ds_read_b128 v[86:89], v1 offset:48016
	s_waitcnt lgkmcnt(14)
	v_pk_fma_f32 v[242:243], v[30:31], v[120:121], v[242:243] neg_lo:[1,0,0] neg_hi:[1,0,0]
	v_pk_fma_f32 v[244:245], v[32:33], v[122:123], v[244:245] neg_lo:[1,0,0] neg_hi:[1,0,0]
	ds_read_b128 v[116:119], v1 offset:48032
	s_waitcnt lgkmcnt(14)
	v_pk_fma_f32 v[242:243], v[34:35], v[124:125], v[242:243] neg_lo:[1,0,0] neg_hi:[1,0,0]
	v_pk_fma_f32 v[244:245], v[36:37], v[126:127], v[244:245] neg_lo:[1,0,0] neg_hi:[1,0,0]
	ds_read_b128 v[120:123], v1 offset:48048
	s_waitcnt lgkmcnt(14)
	v_pk_fma_f32 v[242:243], v[38:39], v[128:129], v[242:243] neg_lo:[1,0,0] neg_hi:[1,0,0]
	v_pk_fma_f32 v[244:245], v[40:41], v[130:131], v[244:245] neg_lo:[1,0,0] neg_hi:[1,0,0]
	ds_read_b128 v[124:127], v1 offset:48144
	s_waitcnt lgkmcnt(14)
; #define SUB_LROW(buf, i_, j0_, n_) do { _Pragma("unroll") for (int j4 = 0; j4 < (n_); ++j4) buf[j4] = *(const f32x4*)(Ls + (i_) * 68 + 4 * ((j0_) + j4)); } while (0)
; #define SUB_FROW(buf, j0_, n_) do { _Pragma("unroll") for (int j4 = 0; j4 < (n_); ++j4) { const f32x4 l = buf[j4]; \
;                 acc -= l.x * x[4 * ((j0_) + j4)]; acc -= l.y * x[4 * ((j0_) + j4) + 1]; acc -= l.z * x[4 * ((j0_) + j4) + 2]; acc -= l.w * x[4 * ((j0_) + j4) + 3]; } } while (0)
; __device__ __forceinline__ void gdn_prep(KA a, int layer, unsigned char* lds, const int tid_, const int bid_) {
;     ...
;             for (int i = 33; i < 64; ++i) {
;                 float acc = x[i];
;                 SUB_LROW(bufB, i, 8, (i + 3) / 4 - 8); __builtin_amdgcn_sched_barrier(0);
;                 SUB_FROW(bufA, 0, 8); __builtin_amdgcn_sched_barrier(0);
;                 if (i + 1 < 64) SUB_LROW(bufA, i + 1, 0, 8);
;                 __builtin_amdgcn_sched_barrier(0);
;                 SUB_FROW(bufB, 8, (i + 3) / 4 - 8);
;                 x[i] = acc;
;                 __builtin_amdgcn_sched_barrier(0);
;             }
	v_pk_fma_f32 v[242:243], v[42:43], v[132:133], v[242:243] neg_lo:[1,0,0] neg_hi:[1,0,0]
	v_pk_fma_f32 v[244:245], v[44:45], v[134:135], v[244:245] neg_lo:[1,0,0] neg_hi:[1,0,0]
	ds_read_b128 v[128:131], v1 offset:48160
	s_waitcnt lgkmcnt(14)
	v_pk_fma_f32 v[242:243], v[46:47], v[136:137], v[242:243] neg_lo:[1,0,0] neg_hi:[1,0,0]
	v_pk_fma_f32 v[244:245], v[48:49], v[138:139], v[244:245] neg_lo:[1,0,0] neg_hi:[1,0,0]
	ds_read_b128 v[132:135], v1 offset:48176
	s_nop 0
	v_pk_add_f32 v[242:243], v[242:243], v[244:245]
	s_nop 0
	v_add_f32_e32 v242, v242, v243
	v_add_f32_e32 v49, v49, v242
	s_waitcnt lgkmcnt(14)
	v_pk_mul_f32 v[242:243], v[2:3], v[140:141] neg_lo:[1,0] neg_hi:[1,0]
	v_pk_mul_f32 v[244:245], v[4:5], v[142:143] neg_lo:[1,0] neg_hi:[1,0]
	ds_read_b128 v[136:139], v1 offset:48192
	s_waitcnt lgkmcnt(14)
	v_pk_fma_f32 v[242:243], v[6:7], v[200:201], v[242:243] neg_lo:[1,0,0] neg_hi:[1,0,0]
	v_pk_fma_f32 v[244:245], v[8:9], v[202:203], v[244:245] neg_lo:[1,0,0] neg_hi:[1,0,0]
	ds_read_b128 v[140:143], v1 offset:48208
	s_waitcnt lgkmcnt(14)
	v_pk_fma_f32 v[242:243], v[10:11], v[204:205], v[242:243] neg_lo:[1,0,0] neg_hi:[1,0,0]
	v_pk_fma_f32 v[244:245], v[12:13], v[206:207], v[244:245] neg_lo:[1,0,0] neg_hi:[1,0,0]
	ds_read_b128 v[200:203], v1 offset:48224
	s_waitcnt lgkmcnt(14)
	v_pk_fma_f32 v[242:243], v[14:15], v[246:247], v[242:243] neg_lo:[1,0,0] neg_hi:[1,0,0]
	v_pk_fma_f32 v[244:245], v[16:17], v[248:249], v[244:245] neg_lo:[1,0,0] neg_hi:[1,0,0]
	ds_read_b128 v[204:207], v1 offset:48240
	s_waitcnt lgkmcnt(14)
	v_pk_fma_f32 v[242:243], v[18:19], v[66:67], v[242:243] neg_lo:[1,0,0] neg_hi:[1,0,0]
	v_pk_fma_f32 v[244:245], v[20:21], v[68:69], v[244:245] neg_lo:[1,0,0] neg_hi:[1,0,0]
	ds_read_b128 v[246:249], v1 offset:48256
	s_waitcnt lgkmcnt(14)
	v_pk_fma_f32 v[242:243], v[22:23], v[70:71], v[242:243] neg_lo:[1,0,0] neg_hi:[1,0,0]
	v_pk_fma_f32 v[244:245], v[24:25], v[72:73], v[244:245] neg_lo:[1,0,0] neg_hi:[1,0,0]
	ds_read_b128 v[66:69], v1 offset:48272
	s_waitcnt lgkmcnt(14)
	v_pk_fma_f32 v[242:243], v[26:27], v[74:75], v[242:243] neg_lo:[1,0,0] neg_hi:[1,0,0]
	v_pk_fma_f32 v[244:245], v[28:29], v[76:77], v[244:245] neg_lo:[1,0,0] neg_hi:[1,0,0]
	ds_read_b128 v[70:73], v1 offset:48288
	s_waitcnt lgkmcnt(14)
	v_pk_fma_f32 v[242:243], v[30:31], v[78:79], v[242:243] neg_lo:[1,0,0] neg_hi:[1,0,0]
	v_pk_fma_f32 v[244:245], v[32:33], v[80:81], v[244:245] neg_lo:[1,0,0] neg_hi:[1,0,0]
	ds_read_b128 v[74:77], v1 offset:48304
	s_waitcnt lgkmcnt(14)
	v_pk_fma_f32 v[242:243], v[34:35], v[82:83], v[242:243] neg_lo:[1,0,0] neg_hi:[1,0,0]
	v_pk_fma_f32 v[244:245], v[36:37], v[84:85], v[244:245] neg_lo:[1,0,0] neg_hi:[1,0,0]
	ds_read_b128 v[78:81], v1 offset:48320
	s_waitcnt lgkmcnt(14)
	v_pk_fma_f32 v[242:243], v[38:39], v[86:87], v[242:243] neg_lo:[1,0,0] neg_hi:[1,0,0]
	v_pk_fma_f32 v[244:245], v[40:41], v[88:89], v[244:245] neg_lo:[1,0,0] neg_hi:[1,0,0]
	ds_read_b128 v[82:85], v1 offset:48336
	s_waitcnt lgkmcnt(14)
	v_pk_fma_f32 v[242:243], v[42:43], v[116:117], v[242:243] neg_lo:[1,0,0] neg_hi:[1,0,0]
	v_pk_fma_f32 v[244:245], v[44:45], v[118:119], v[244:245] neg_lo:[1,0,0] neg_hi:[1,0,0]
	ds_read_b128 v[86:89], v1 offset:48416
	s_waitcnt lgkmcnt(14)
	v_pk_fma_f32 v[242:243], v[46:47], v[120:121], v[242:243] neg_lo:[1,0,0] neg_hi:[1,0,0]
	v_pk_fma_f32 v[244:245], v[48:49], v[122:123], v[244:245] neg_lo:[1,0,0] neg_hi:[1,0,0]
	ds_read_b128 v[116:119], v1 offset:48432
	s_nop 0
	v_pk_add_f32 v[242:243], v[242:243], v[244:245]
	s_nop 0
	v_add_f32_e32 v242, v242, v243
	v_add_f32_e32 v50, v50, v242
	s_waitcnt lgkmcnt(14)
	v_pk_mul_f32 v[242:243], v[2:3], v[124:125] neg_lo:[1,0] neg_hi:[1,0]
	v_pk_mul_f32 v[244:245], v[4:5], v[126:127] neg_lo:[1,0] neg_hi:[1,0]
	ds_read_b128 v[120:123], v1 offset:48448
	s_waitcnt lgkmcnt(14)
	v_pk_fma_f32 v[242:243], v[6:7], v[128:129], v[242:243] neg_lo:[1,0,0] neg_hi:[1,0,0]
	v_pk_fma_f32 v[244:245], v[8:9], v[130:131], v[244:245] neg_lo:[1,0,0] neg_hi:[1,0,0]
	ds_read_b128 v[124:127], v1 offset:48464
	s_waitcnt lgkmcnt(14)
	v_pk_fma_f32 v[242:243], v[10:11], v[132:133], v[242:243] neg_lo:[1,0,0] neg_hi:[1,0,0]
	v_pk_fma_f32 v[244:245], v[12:13], v[134:135], v[244:245] neg_lo:[1,0,0] neg_hi:[1,0,0]
	ds_read_b128 v[128:131], v1 offset:48480
	s_waitcnt lgkmcnt(14)
	v_pk_fma_f32 v[242:243], v[14:15], v[136:137], v[242:243] neg_lo:[1,0,0] neg_hi:[1,0,0]
	v_pk_fma_f32 v[244:245], v[16:17], v[138:139], v[244:245] neg_lo:[1,0,0] neg_hi:[1,0,0]
	ds_read_b128 v[132:135], v1 offset:48496
	s_waitcnt lgkmcnt(14)
	v_pk_fma_f32 v[242:243], v[18:19], v[140:141], v[242:243] neg_lo:[1,0,0] neg_hi:[1,0,0]
	v_pk_fma_f32 v[244:245], v[20:21], v[142:143], v[244:245] neg_lo:[1,0,0] neg_hi:[1,0,0]
	ds_read_b128 v[136:139], v1 offset:48512
	s_waitcnt lgkmcnt(14)
	v_pk_fma_f32 v[242:243], v[22:23], v[200:201], v[242:243] neg_lo:[1,0,0] neg_hi:[1,0,0]
	v_pk_fma_f32 v[244:245], v[24:25], v[202:203], v[244:245] neg_lo:[1,0,0] neg_hi:[1,0,0]
	ds_read_b128 v[140:143], v1 offset:48528
	s_waitcnt lgkmcnt(14)
	v_pk_fma_f32 v[242:243], v[26:27], v[204:205], v[242:243] neg_lo:[1,0,0] neg_hi:[1,0,0]
	v_pk_fma_f32 v[244:245], v[28:29], v[206:207], v[244:245] neg_lo:[1,0,0] neg_hi:[1,0,0]
	ds_read_b128 v[200:203], v1 offset:48544
	s_waitcnt lgkmcnt(14)
	v_pk_fma_f32 v[242:243], v[30:31], v[246:247], v[242:243] neg_lo:[1,0,0] neg_hi:[1,0,0]
	v_pk_fma_f32 v[244:245], v[32:33], v[248:249], v[244:245] neg_lo:[1,0,0] neg_hi:[1,0,0]
	ds_read_b128 v[204:207], v1 offset:48560
	s_waitcnt lgkmcnt(14)
	v_pk_fma_f32 v[242:243], v[34:35], v[66:67], v[242:243] neg_lo:[1,0,0] neg_hi:[1,0,0]
	v_pk_fma_f32 v[244:245], v[36:37], v[68:69], v[244:245] neg_lo:[1,0,0] neg_hi:[1,0,0]
	ds_read_b128 v[246:249], v1 offset:48576
	s_waitcnt lgkmcnt(14)
; #define SUB_LROW(buf, i_, j0_, n_) do { _Pragma("unroll") for (int j4 = 0; j4 < (n_); ++j4) buf[j4] = *(const f32x4*)(Ls + (i_) * 68 + 4 * ((j0_) + j4)); } while (0)
; #define SUB_FROW(buf, j0_, n_) do { _Pragma("unroll") for (int j4 = 0; j4 < (n_); ++j4) { const f32x4 l = buf[j4]; \
;                 acc -= l.x * x[4 * ((j0_) + j4)]; acc -= l.y * x[4 * ((j0_) + j4) + 1]; acc -= l.z * x[4 * ((j0_) + j4) + 2]; acc -= l.w * x[4 * ((j0_) + j4) + 3]; } } while (0)
; __device__ __forceinline__ void gdn_prep(KA a, int layer, unsigned char* lds, const int tid_, const int bid_) {
;     ...
;             for (int i = 33; i < 64; ++i) {
;                 float acc = x[i];
;                 SUB_LROW(bufB, i, 8, (i + 3) / 4 - 8); __builtin_amdgcn_sched_barrier(0);
;                 SUB_FROW(bufA, 0, 8); __builtin_amdgcn_sched_barrier(0);
;                 if (i + 1 < 64) SUB_LROW(bufA, i + 1, 0, 8);
;                 __builtin_amdgcn_sched_barrier(0);
;                 SUB_FROW(bufB, 8, (i + 3) / 4 - 8);
;                 x[i] = acc;
;                 __builtin_amdgcn_sched_barrier(0);
;             }
	v_pk_fma_f32 v[242:243], v[38:39], v[70:71], v[242:243] neg_lo:[1,0,0] neg_hi:[1,0,0]
	v_pk_fma_f32 v[244:245], v[40:41], v[72:73], v[244:245] neg_lo:[1,0,0] neg_hi:[1,0,0]
	ds_read_b128 v[66:69], v1 offset:48592
	s_waitcnt lgkmcnt(14)
	v_pk_fma_f32 v[242:243], v[42:43], v[74:75], v[242:243] neg_lo:[1,0,0] neg_hi:[1,0,0]
	v_pk_fma_f32 v[244:245], v[44:45], v[76:77], v[244:245] neg_lo:[1,0,0] neg_hi:[1,0,0]
	ds_read_b128 v[70:73], v1 offset:48608
	s_waitcnt lgkmcnt(14)
	v_pk_fma_f32 v[242:243], v[46:47], v[78:79], v[242:243] neg_lo:[1,0,0] neg_hi:[1,0,0]
	v_pk_fma_f32 v[244:245], v[48:49], v[80:81], v[244:245] neg_lo:[1,0,0] neg_hi:[1,0,0]
	ds_read_b128 v[74:77], v1 offset:48688
	s_waitcnt lgkmcnt(14)
	v_pk_fma_f32 v[242:243], v[50:51], v[82:83], v[242:243] neg_lo:[1,0,0] neg_hi:[1,0,0]
	v_pk_fma_f32 v[244:245], v[52:53], v[84:85], v[244:245] neg_lo:[1,0,0] neg_hi:[1,0,0]
	ds_read_b128 v[78:81], v1 offset:48704
	s_nop 0
	v_pk_add_f32 v[242:243], v[242:243], v[244:245]
	s_nop 0
	v_add_f32_e32 v242, v242, v243
	v_add_f32_e32 v51, v51, v242
	s_waitcnt lgkmcnt(14)
	v_pk_mul_f32 v[242:243], v[2:3], v[86:87] neg_lo:[1,0] neg_hi:[1,0]
	v_pk_mul_f32 v[244:245], v[4:5], v[88:89] neg_lo:[1,0] neg_hi:[1,0]
	ds_read_b128 v[82:85], v1 offset:48720
	s_waitcnt lgkmcnt(14)
	v_pk_fma_f32 v[242:243], v[6:7], v[116:117], v[242:243] neg_lo:[1,0,0] neg_hi:[1,0,0]
	v_pk_fma_f32 v[244:245], v[8:9], v[118:119], v[244:245] neg_lo:[1,0,0] neg_hi:[1,0,0]
	ds_read_b128 v[86:89], v1 offset:48736
	s_waitcnt lgkmcnt(14)
	v_pk_fma_f32 v[242:243], v[10:11], v[120:121], v[242:243] neg_lo:[1,0,0] neg_hi:[1,0,0]
	v_pk_fma_f32 v[244:245], v[12:13], v[122:123], v[244:245] neg_lo:[1,0,0] neg_hi:[1,0,0]
	ds_read_b128 v[116:119], v1 offset:48752
	s_waitcnt lgkmcnt(14)
	v_pk_fma_f32 v[242:243], v[14:15], v[124:125], v[242:243] neg_lo:[1,0,0] neg_hi:[1,0,0]
	v_pk_fma_f32 v[244:245], v[16:17], v[126:127], v[244:245] neg_lo:[1,0,0] neg_hi:[1,0,0]
	ds_read_b128 v[120:123], v1 offset:48768
	s_waitcnt lgkmcnt(14)
	v_pk_fma_f32 v[242:243], v[18:19], v[128:129], v[242:243] neg_lo:[1,0,0] neg_hi:[1,0,0]
	v_pk_fma_f32 v[244:245], v[20:21], v[130:131], v[244:245] neg_lo:[1,0,0] neg_hi:[1,0,0]
	ds_read_b128 v[124:127], v1 offset:48784
	s_waitcnt lgkmcnt(14)
	v_pk_fma_f32 v[242:243], v[22:23], v[132:133], v[242:243] neg_lo:[1,0,0] neg_hi:[1,0,0]
	v_pk_fma_f32 v[244:245], v[24:25], v[134:135], v[244:245] neg_lo:[1,0,0] neg_hi:[1,0,0]
	ds_read_b128 v[128:131], v1 offset:48800
	s_waitcnt lgkmcnt(14)
	v_pk_fma_f32 v[242:243], v[26:27], v[136:137], v[242:243] neg_lo:[1,0,0] neg_hi:[1,0,0]
	v_pk_fma_f32 v[244:245], v[28:29], v[138:139], v[244:245] neg_lo:[1,0,0] neg_hi:[1,0,0]
	ds_read_b128 v[132:135], v1 offset:48816
	s_waitcnt lgkmcnt(14)
	v_pk_fma_f32 v[242:243], v[30:31], v[140:141], v[242:243] neg_lo:[1,0,0] neg_hi:[1,0,0]
	v_pk_fma_f32 v[244:245], v[32:33], v[142:143], v[244:245] neg_lo:[1,0,0] neg_hi:[1,0,0]
	ds_read_b128 v[136:139], v1 offset:48832
	s_waitcnt lgkmcnt(14)
	v_pk_fma_f32 v[242:243], v[34:35], v[200:201], v[242:243] neg_lo:[1,0,0] neg_hi:[1,0,0]
	v_pk_fma_f32 v[244:245], v[36:37], v[202:203], v[244:245] neg_lo:[1,0,0] neg_hi:[1,0,0]
	ds_read_b128 v[140:143], v1 offset:48848
	s_waitcnt lgkmcnt(14)
	v_pk_fma_f32 v[242:243], v[38:39], v[204:205], v[242:243] neg_lo:[1,0,0] neg_hi:[1,0,0]
	v_pk_fma_f32 v[244:245], v[40:41], v[206:207], v[244:245] neg_lo:[1,0,0] neg_hi:[1,0,0]
	ds_read_b128 v[200:203], v1 offset:48864
	s_waitcnt lgkmcnt(14)
	v_pk_fma_f32 v[242:243], v[42:43], v[246:247], v[242:243] neg_lo:[1,0,0] neg_hi:[1,0,0]
	v_pk_fma_f32 v[244:245], v[44:45], v[248:249], v[244:245] neg_lo:[1,0,0] neg_hi:[1,0,0]
	ds_read_b128 v[204:207], v1 offset:48880
	s_waitcnt lgkmcnt(14)
	v_pk_fma_f32 v[242:243], v[46:47], v[66:67], v[242:243] neg_lo:[1,0,0] neg_hi:[1,0,0]
	v_pk_fma_f32 v[244:245], v[48:49], v[68:69], v[244:245] neg_lo:[1,0,0] neg_hi:[1,0,0]
	ds_read_b128 v[246:249], v1 offset:48960
	s_waitcnt lgkmcnt(14)
	v_pk_fma_f32 v[242:243], v[50:51], v[70:71], v[242:243] neg_lo:[1,0,0] neg_hi:[1,0,0]
	v_pk_fma_f32 v[244:245], v[52:53], v[72:73], v[244:245] neg_lo:[1,0,0] neg_hi:[1,0,0]
	ds_read_b128 v[66:69], v1 offset:48976
	s_nop 0
	v_pk_add_f32 v[242:243], v[242:243], v[244:245]
	s_nop 0
	v_add_f32_e32 v242, v242, v243
	v_add_f32_e32 v52, v52, v242
	s_waitcnt lgkmcnt(14)
	v_pk_mul_f32 v[242:243], v[2:3], v[74:75] neg_lo:[1,0] neg_hi:[1,0]
	v_pk_mul_f32 v[244:245], v[4:5], v[76:77] neg_lo:[1,0] neg_hi:[1,0]
	ds_read_b128 v[70:73], v1 offset:48992
	s_waitcnt lgkmcnt(14)
	v_pk_fma_f32 v[242:243], v[6:7], v[78:79], v[242:243] neg_lo:[1,0,0] neg_hi:[1,0,0]
	v_pk_fma_f32 v[244:245], v[8:9], v[80:81], v[244:245] neg_lo:[1,0,0] neg_hi:[1,0,0]
	ds_read_b128 v[74:77], v1 offset:49008
	s_waitcnt lgkmcnt(14)
	v_pk_fma_f32 v[242:243], v[10:11], v[82:83], v[242:243] neg_lo:[1,0,0] neg_hi:[1,0,0]
	v_pk_fma_f32 v[244:245], v[12:13], v[84:85], v[244:245] neg_lo:[1,0,0] neg_hi:[1,0,0]
	ds_read_b128 v[78:81], v1 offset:49024
	s_waitcnt lgkmcnt(14)
	v_pk_fma_f32 v[242:243], v[14:15], v[86:87], v[242:243] neg_lo:[1,0,0] neg_hi:[1,0,0]
	v_pk_fma_f32 v[244:245], v[16:17], v[88:89], v[244:245] neg_lo:[1,0,0] neg_hi:[1,0,0]
	ds_read_b128 v[82:85], v1 offset:49040
	s_waitcnt lgkmcnt(14)
	v_pk_fma_f32 v[242:243], v[18:19], v[116:117], v[242:243] neg_lo:[1,0,0] neg_hi:[1,0,0]
	v_pk_fma_f32 v[244:245], v[20:21], v[118:119], v[244:245] neg_lo:[1,0,0] neg_hi:[1,0,0]
	ds_read_b128 v[86:89], v1 offset:49056
	s_waitcnt lgkmcnt(14)
	v_pk_fma_f32 v[242:243], v[22:23], v[120:121], v[242:243] neg_lo:[1,0,0] neg_hi:[1,0,0]
	v_pk_fma_f32 v[244:245], v[24:25], v[122:123], v[244:245] neg_lo:[1,0,0] neg_hi:[1,0,0]
	ds_read_b128 v[116:119], v1 offset:49072
	s_waitcnt lgkmcnt(14)
; #define SUB_LROW(buf, i_, j0_, n_) do { _Pragma("unroll") for (int j4 = 0; j4 < (n_); ++j4) buf[j4] = *(const f32x4*)(Ls + (i_) * 68 + 4 * ((j0_) + j4)); } while (0)
; #define SUB_FROW(buf, j0_, n_) do { _Pragma("unroll") for (int j4 = 0; j4 < (n_); ++j4) { const f32x4 l = buf[j4]; \
;                 acc -= l.x * x[4 * ((j0_) + j4)]; acc -= l.y * x[4 * ((j0_) + j4) + 1]; acc -= l.z * x[4 * ((j0_) + j4) + 2]; acc -= l.w * x[4 * ((j0_) + j4) + 3]; } } while (0)
; __device__ __forceinline__ void gdn_prep(KA a, int layer, unsigned char* lds, const int tid_, const int bid_) {
;     ...
; #pragma unroll
;             for (int j4 = 0; j4 < 8; ++j4) { bufA[j4] = (f32x4){0.f, 0.f, 0.f, 0.f}; bufB[j4] = (f32x4){0.f, 0.f, 0.f, 0.f}; }
;             SUB_LROW(bufA, 1, 0, 1);
; #pragma unroll
;             for (int i = 1; i <= 32; ++i) {
;                 const int nn = (i + 4) / 4 < 8 ? (i + 4) / 4 : 8;
;                 float acc = x[i];
;                 if (i & 1) { SUB_LROW(bufB, i + 1, 0, nn); __builtin_amdgcn_sched_barrier(0); SUB_FROW(bufA, 0, (i + 3) / 4); }
;                 else       { SUB_LROW(bufA, i + 1, 0, nn); __builtin_amdgcn_sched_barrier(0); SUB_FROW(bufB, 0, (i + 3) / 4); }
;                 x[i] = acc;
;                 __builtin_amdgcn_sched_barrier(0);
;             }
; #pragma unroll
;             for (int i = 33; i < 64; ++i) {
;                 float acc = x[i];
;                 SUB_LROW(bufB, i, 8, (i + 3) / 4 - 8); __builtin_amdgcn_sched_barrier(0);
;                 SUB_FROW(bufA, 0, 8); __builtin_amdgcn_sched_barrier(0);
;                 if (i + 1 < 64) SUB_LROW(bufA, i + 1, 0, 8);
;                 __builtin_amdgcn_sched_barrier(0);
;                 SUB_FROW(bufB, 8, (i + 3) / 4 - 8);
;                 x[i] = acc;
;                 __builtin_amdgcn_sched_barrier(0);
;             }
	v_pk_fma_f32 v[242:243], v[26:27], v[124:125], v[242:243] neg_lo:[1,0,0] neg_hi:[1,0,0]
	v_pk_fma_f32 v[244:245], v[28:29], v[126:127], v[244:245] neg_lo:[1,0,0] neg_hi:[1,0,0]
	ds_read_b128 v[120:123], v1 offset:49088
	s_waitcnt lgkmcnt(14)
	v_pk_fma_f32 v[242:243], v[30:31], v[128:129], v[242:243] neg_lo:[1,0,0] neg_hi:[1,0,0]
	v_pk_fma_f32 v[244:245], v[32:33], v[130:131], v[244:245] neg_lo:[1,0,0] neg_hi:[1,0,0]
	ds_read_b128 v[124:127], v1 offset:49104
	s_waitcnt lgkmcnt(14)
	v_pk_fma_f32 v[242:243], v[34:35], v[132:133], v[242:243] neg_lo:[1,0,0] neg_hi:[1,0,0]
	v_pk_fma_f32 v[244:245], v[36:37], v[134:135], v[244:245] neg_lo:[1,0,0] neg_hi:[1,0,0]
	ds_read_b128 v[128:131], v1 offset:49120
	s_waitcnt lgkmcnt(14)
	v_pk_fma_f32 v[242:243], v[38:39], v[136:137], v[242:243] neg_lo:[1,0,0] neg_hi:[1,0,0]
	v_pk_fma_f32 v[244:245], v[40:41], v[138:139], v[244:245] neg_lo:[1,0,0] neg_hi:[1,0,0]
	ds_read_b128 v[132:135], v1 offset:49136
	s_waitcnt lgkmcnt(14)
	v_pk_fma_f32 v[242:243], v[42:43], v[140:141], v[242:243] neg_lo:[1,0,0] neg_hi:[1,0,0]
	v_pk_fma_f32 v[244:245], v[44:45], v[142:143], v[244:245] neg_lo:[1,0,0] neg_hi:[1,0,0]
	ds_read_b128 v[136:139], v1 offset:49152
	s_waitcnt lgkmcnt(14)
	v_pk_fma_f32 v[242:243], v[46:47], v[200:201], v[242:243] neg_lo:[1,0,0] neg_hi:[1,0,0]
	v_pk_fma_f32 v[244:245], v[48:49], v[202:203], v[244:245] neg_lo:[1,0,0] neg_hi:[1,0,0]
	ds_read_b128 v[140:143], v1 offset:49232
	s_waitcnt lgkmcnt(14)
	v_pk_fma_f32 v[242:243], v[50:51], v[204:205], v[242:243] neg_lo:[1,0,0] neg_hi:[1,0,0]
	v_pk_fma_f32 v[244:245], v[52:53], v[206:207], v[244:245] neg_lo:[1,0,0] neg_hi:[1,0,0]
	ds_read_b128 v[200:203], v1 offset:49248
	s_nop 0
	v_pk_add_f32 v[242:243], v[242:243], v[244:245]
	s_nop 0
	v_add_f32_e32 v242, v242, v243
	v_add_f32_e32 v53, v53, v242
	s_waitcnt lgkmcnt(14)
	v_pk_mul_f32 v[242:243], v[2:3], v[246:247] neg_lo:[1,0] neg_hi:[1,0]
	v_pk_mul_f32 v[244:245], v[4:5], v[248:249] neg_lo:[1,0] neg_hi:[1,0]
	ds_read_b128 v[204:207], v1 offset:49264
	s_waitcnt lgkmcnt(14)
	v_pk_fma_f32 v[242:243], v[6:7], v[66:67], v[242:243] neg_lo:[1,0,0] neg_hi:[1,0,0]
	v_pk_fma_f32 v[244:245], v[8:9], v[68:69], v[244:245] neg_lo:[1,0,0] neg_hi:[1,0,0]
	ds_read_b128 v[246:249], v1 offset:49280
	s_waitcnt lgkmcnt(14)
	v_pk_fma_f32 v[242:243], v[10:11], v[70:71], v[242:243] neg_lo:[1,0,0] neg_hi:[1,0,0]
	v_pk_fma_f32 v[244:245], v[12:13], v[72:73], v[244:245] neg_lo:[1,0,0] neg_hi:[1,0,0]
	ds_read_b128 v[66:69], v1 offset:49296
	s_waitcnt lgkmcnt(14)
	v_pk_fma_f32 v[242:243], v[14:15], v[74:75], v[242:243] neg_lo:[1,0,0] neg_hi:[1,0,0]
	v_pk_fma_f32 v[244:245], v[16:17], v[76:77], v[244:245] neg_lo:[1,0,0] neg_hi:[1,0,0]
	ds_read_b128 v[70:73], v1 offset:49312
	s_waitcnt lgkmcnt(14)
	v_pk_fma_f32 v[242:243], v[18:19], v[78:79], v[242:243] neg_lo:[1,0,0] neg_hi:[1,0,0]
	v_pk_fma_f32 v[244:245], v[20:21], v[80:81], v[244:245] neg_lo:[1,0,0] neg_hi:[1,0,0]
	ds_read_b128 v[74:77], v1 offset:49328
	s_waitcnt lgkmcnt(14)
	v_pk_fma_f32 v[242:243], v[22:23], v[82:83], v[242:243] neg_lo:[1,0,0] neg_hi:[1,0,0]
	v_pk_fma_f32 v[244:245], v[24:25], v[84:85], v[244:245] neg_lo:[1,0,0] neg_hi:[1,0,0]
	ds_read_b128 v[78:81], v1 offset:49344
	s_waitcnt lgkmcnt(14)
	v_pk_fma_f32 v[242:243], v[26:27], v[86:87], v[242:243] neg_lo:[1,0,0] neg_hi:[1,0,0]
	v_pk_fma_f32 v[244:245], v[28:29], v[88:89], v[244:245] neg_lo:[1,0,0] neg_hi:[1,0,0]
	ds_read_b128 v[82:85], v1 offset:49360
	s_waitcnt lgkmcnt(14)
	v_pk_fma_f32 v[242:243], v[30:31], v[116:117], v[242:243] neg_lo:[1,0,0] neg_hi:[1,0,0]
	v_pk_fma_f32 v[244:245], v[32:33], v[118:119], v[244:245] neg_lo:[1,0,0] neg_hi:[1,0,0]
	ds_read_b128 v[86:89], v1 offset:49376
	s_waitcnt lgkmcnt(14)
	v_pk_fma_f32 v[242:243], v[34:35], v[120:121], v[242:243] neg_lo:[1,0,0] neg_hi:[1,0,0]
	v_pk_fma_f32 v[244:245], v[36:37], v[122:123], v[244:245] neg_lo:[1,0,0] neg_hi:[1,0,0]
	ds_read_b128 v[116:119], v1 offset:49392
	s_waitcnt lgkmcnt(14)
	v_pk_fma_f32 v[242:243], v[38:39], v[124:125], v[242:243] neg_lo:[1,0,0] neg_hi:[1,0,0]
	v_pk_fma_f32 v[244:245], v[40:41], v[126:127], v[244:245] neg_lo:[1,0,0] neg_hi:[1,0,0]
	ds_read_b128 v[120:123], v1 offset:49408
	s_waitcnt lgkmcnt(14)
	v_pk_fma_f32 v[242:243], v[42:43], v[128:129], v[242:243] neg_lo:[1,0,0] neg_hi:[1,0,0]
	v_pk_fma_f32 v[244:245], v[44:45], v[130:131], v[244:245] neg_lo:[1,0,0] neg_hi:[1,0,0]
	ds_read_b128 v[124:127], v1 offset:49424
	s_waitcnt lgkmcnt(14)
	v_pk_fma_f32 v[242:243], v[46:47], v[132:133], v[242:243] neg_lo:[1,0,0] neg_hi:[1,0,0]
	v_pk_fma_f32 v[244:245], v[48:49], v[134:135], v[244:245] neg_lo:[1,0,0] neg_hi:[1,0,0]
	ds_read_b128 v[128:131], v1 offset:49440
	s_waitcnt lgkmcnt(14)
	v_pk_fma_f32 v[242:243], v[50:51], v[136:137], v[242:243] neg_lo:[1,0,0] neg_hi:[1,0,0]
	v_pk_fma_f32 v[244:245], v[52:53], v[138:139], v[244:245] neg_lo:[1,0,0] neg_hi:[1,0,0]
	ds_read_b128 v[132:135], v1 offset:49504
	s_nop 0
	v_pk_add_f32 v[242:243], v[242:243], v[244:245]
	s_nop 0
	v_add_f32_e32 v242, v242, v243
	v_add_f32_e32 v54, v54, v242
	s_waitcnt lgkmcnt(14)
	v_pk_mul_f32 v[242:243], v[2:3], v[140:141] neg_lo:[1,0] neg_hi:[1,0]
	v_pk_mul_f32 v[244:245], v[4:5], v[142:143] neg_lo:[1,0] neg_hi:[1,0]
	ds_read_b128 v[136:139], v1 offset:49520
	s_waitcnt lgkmcnt(14)
	v_pk_fma_f32 v[242:243], v[6:7], v[200:201], v[242:243] neg_lo:[1,0,0] neg_hi:[1,0,0]
	v_pk_fma_f32 v[244:245], v[8:9], v[202:203], v[244:245] neg_lo:[1,0,0] neg_hi:[1,0,0]
	ds_read_b128 v[140:143], v1 offset:49536
	s_waitcnt lgkmcnt(14)
	v_pk_fma_f32 v[242:243], v[10:11], v[204:205], v[242:243] neg_lo:[1,0,0] neg_hi:[1,0,0]
	v_pk_fma_f32 v[244:245], v[12:13], v[206:207], v[244:245] neg_lo:[1,0,0] neg_hi:[1,0,0]
	ds_read_b128 v[200:203], v1 offset:49552
	s_waitcnt lgkmcnt(14)
; #define SUB_LROW(buf, i_, j0_, n_) do { _Pragma("unroll") for (int j4 = 0; j4 < (n_); ++j4) buf[j4] = *(const f32x4*)(Ls + (i_) * 68 + 4 * ((j0_) + j4)); } while (0)
; #define SUB_FROW(buf, j0_, n_) do { _Pragma("unroll") for (int j4 = 0; j4 < (n_); ++j4) { const f32x4 l = buf[j4]; \
;                 acc -= l.x * x[4 * ((j0_) + j4)]; acc -= l.y * x[4 * ((j0_) + j4) + 1]; acc -= l.z * x[4 * ((j0_) + j4) + 2]; acc -= l.w * x[4 * ((j0_) + j4) + 3]; } } while (0)
; __device__ __forceinline__ void gdn_prep(KA a, int layer, unsigned char* lds, const int tid_, const int bid_) {
;     ...
; #pragma unroll
;             for (int j4 = 0; j4 < 8; ++j4) { bufA[j4] = (f32x4){0.f, 0.f, 0.f, 0.f}; bufB[j4] = (f32x4){0.f, 0.f, 0.f, 0.f}; }
;             SUB_LROW(bufA, 1, 0, 1);
; #pragma unroll
;             for (int i = 1; i <= 32; ++i) {
;                 const int nn = (i + 4) / 4 < 8 ? (i + 4) / 4 : 8;
;                 float acc = x[i];
;                 if (i & 1) { SUB_LROW(bufB, i + 1, 0, nn); __builtin_amdgcn_sched_barrier(0); SUB_FROW(bufA, 0, (i + 3) / 4); }
;                 else       { SUB_LROW(bufA, i + 1, 0, nn); __builtin_amdgcn_sched_barrier(0); SUB_FROW(bufB, 0, (i + 3) / 4); }
;                 x[i] = acc;
;                 __builtin_amdgcn_sched_barrier(0);
;             }
; #pragma unroll
;             for (int i = 33; i < 64; ++i) {
;                 float acc = x[i];
;                 SUB_LROW(bufB, i, 8, (i + 3) / 4 - 8); __builtin_amdgcn_sched_barrier(0);
;                 SUB_FROW(bufA, 0, 8); __builtin_amdgcn_sched_barrier(0);
;                 if (i + 1 < 64) SUB_LROW(bufA, i + 1, 0, 8);
;                 __builtin_amdgcn_sched_barrier(0);
;                 SUB_FROW(bufB, 8, (i + 3) / 4 - 8);
;                 x[i] = acc;
;                 __builtin_amdgcn_sched_barrier(0);
;             }
	v_pk_fma_f32 v[242:243], v[14:15], v[246:247], v[242:243] neg_lo:[1,0,0] neg_hi:[1,0,0]
	v_pk_fma_f32 v[244:245], v[16:17], v[248:249], v[244:245] neg_lo:[1,0,0] neg_hi:[1,0,0]
	ds_read_b128 v[204:207], v1 offset:49568
	s_waitcnt lgkmcnt(14)
	v_pk_fma_f32 v[242:243], v[18:19], v[66:67], v[242:243] neg_lo:[1,0,0] neg_hi:[1,0,0]
	v_pk_fma_f32 v[244:245], v[20:21], v[68:69], v[244:245] neg_lo:[1,0,0] neg_hi:[1,0,0]
	ds_read_b128 v[246:249], v1 offset:49584
	s_waitcnt lgkmcnt(14)
	v_pk_fma_f32 v[242:243], v[22:23], v[70:71], v[242:243] neg_lo:[1,0,0] neg_hi:[1,0,0]
	v_pk_fma_f32 v[244:245], v[24:25], v[72:73], v[244:245] neg_lo:[1,0,0] neg_hi:[1,0,0]
	ds_read_b128 v[66:69], v1 offset:49600
	s_waitcnt lgkmcnt(14)
	v_pk_fma_f32 v[242:243], v[26:27], v[74:75], v[242:243] neg_lo:[1,0,0] neg_hi:[1,0,0]
	v_pk_fma_f32 v[244:245], v[28:29], v[76:77], v[244:245] neg_lo:[1,0,0] neg_hi:[1,0,0]
	ds_read_b128 v[70:73], v1 offset:49616
	s_waitcnt lgkmcnt(14)
	v_pk_fma_f32 v[242:243], v[30:31], v[78:79], v[242:243] neg_lo:[1,0,0] neg_hi:[1,0,0]
	v_pk_fma_f32 v[244:245], v[32:33], v[80:81], v[244:245] neg_lo:[1,0,0] neg_hi:[1,0,0]
	ds_read_b128 v[74:77], v1 offset:49632
	s_waitcnt lgkmcnt(14)
	v_pk_fma_f32 v[242:243], v[34:35], v[82:83], v[242:243] neg_lo:[1,0,0] neg_hi:[1,0,0]
	v_pk_fma_f32 v[244:245], v[36:37], v[84:85], v[244:245] neg_lo:[1,0,0] neg_hi:[1,0,0]
	ds_read_b128 v[78:81], v1 offset:49648
	s_waitcnt lgkmcnt(14)
	v_pk_fma_f32 v[242:243], v[38:39], v[86:87], v[242:243] neg_lo:[1,0,0] neg_hi:[1,0,0]
	v_pk_fma_f32 v[244:245], v[40:41], v[88:89], v[244:245] neg_lo:[1,0,0] neg_hi:[1,0,0]
	ds_read_b128 v[82:85], v1 offset:49664
	s_waitcnt lgkmcnt(14)
	v_pk_fma_f32 v[242:243], v[42:43], v[116:117], v[242:243] neg_lo:[1,0,0] neg_hi:[1,0,0]
	v_pk_fma_f32 v[244:245], v[44:45], v[118:119], v[244:245] neg_lo:[1,0,0] neg_hi:[1,0,0]
	ds_read_b128 v[86:89], v1 offset:49680
	s_waitcnt lgkmcnt(14)
	v_pk_fma_f32 v[242:243], v[46:47], v[120:121], v[242:243] neg_lo:[1,0,0] neg_hi:[1,0,0]
	v_pk_fma_f32 v[244:245], v[48:49], v[122:123], v[244:245] neg_lo:[1,0,0] neg_hi:[1,0,0]
	ds_read_b128 v[116:119], v1 offset:49696
	s_waitcnt lgkmcnt(14)
	v_pk_fma_f32 v[242:243], v[50:51], v[124:125], v[242:243] neg_lo:[1,0,0] neg_hi:[1,0,0]
	v_pk_fma_f32 v[244:245], v[52:53], v[126:127], v[244:245] neg_lo:[1,0,0] neg_hi:[1,0,0]
	ds_read_b128 v[120:123], v1 offset:49712
	s_waitcnt lgkmcnt(14)
	v_pk_fma_f32 v[242:243], v[54:55], v[128:129], v[242:243] neg_lo:[1,0,0] neg_hi:[1,0,0]
	v_pk_fma_f32 v[244:245], v[56:57], v[130:131], v[244:245] neg_lo:[1,0,0] neg_hi:[1,0,0]
	ds_read_b128 v[124:127], v1 offset:49776
	s_nop 0
	v_pk_add_f32 v[242:243], v[242:243], v[244:245]
	s_nop 0
	v_add_f32_e32 v242, v242, v243
	v_add_f32_e32 v55, v55, v242
	s_waitcnt lgkmcnt(14)
	v_pk_mul_f32 v[242:243], v[2:3], v[132:133] neg_lo:[1,0] neg_hi:[1,0]
	v_pk_mul_f32 v[244:245], v[4:5], v[134:135] neg_lo:[1,0] neg_hi:[1,0]
	ds_read_b128 v[128:131], v1 offset:49792
	s_waitcnt lgkmcnt(14)
	v_pk_fma_f32 v[242:243], v[6:7], v[136:137], v[242:243] neg_lo:[1,0,0] neg_hi:[1,0,0]
	v_pk_fma_f32 v[244:245], v[8:9], v[138:139], v[244:245] neg_lo:[1,0,0] neg_hi:[1,0,0]
	ds_read_b128 v[132:135], v1 offset:49808
	s_waitcnt lgkmcnt(14)
	v_pk_fma_f32 v[242:243], v[10:11], v[140:141], v[242:243] neg_lo:[1,0,0] neg_hi:[1,0,0]
	v_pk_fma_f32 v[244:245], v[12:13], v[142:143], v[244:245] neg_lo:[1,0,0] neg_hi:[1,0,0]
	ds_read_b128 v[136:139], v1 offset:49824
	s_waitcnt lgkmcnt(14)
	v_pk_fma_f32 v[242:243], v[14:15], v[200:201], v[242:243] neg_lo:[1,0,0] neg_hi:[1,0,0]
	v_pk_fma_f32 v[244:245], v[16:17], v[202:203], v[244:245] neg_lo:[1,0,0] neg_hi:[1,0,0]
	ds_read_b128 v[140:143], v1 offset:49840
	s_waitcnt lgkmcnt(14)
	v_pk_fma_f32 v[242:243], v[18:19], v[204:205], v[242:243] neg_lo:[1,0,0] neg_hi:[1,0,0]
	v_pk_fma_f32 v[244:245], v[20:21], v[206:207], v[244:245] neg_lo:[1,0,0] neg_hi:[1,0,0]
	ds_read_b128 v[200:203], v1 offset:49856
	s_waitcnt lgkmcnt(14)
	v_pk_fma_f32 v[242:243], v[22:23], v[246:247], v[242:243] neg_lo:[1,0,0] neg_hi:[1,0,0]
	v_pk_fma_f32 v[244:245], v[24:25], v[248:249], v[244:245] neg_lo:[1,0,0] neg_hi:[1,0,0]
	ds_read_b128 v[204:207], v1 offset:49872
	s_waitcnt lgkmcnt(14)
	v_pk_fma_f32 v[242:243], v[26:27], v[66:67], v[242:243] neg_lo:[1,0,0] neg_hi:[1,0,0]
	v_pk_fma_f32 v[244:245], v[28:29], v[68:69], v[244:245] neg_lo:[1,0,0] neg_hi:[1,0,0]
	ds_read_b128 v[246:249], v1 offset:49888
	s_waitcnt lgkmcnt(14)
	v_pk_fma_f32 v[242:243], v[30:31], v[70:71], v[242:243] neg_lo:[1,0,0] neg_hi:[1,0,0]
	v_pk_fma_f32 v[244:245], v[32:33], v[72:73], v[244:245] neg_lo:[1,0,0] neg_hi:[1,0,0]
	ds_read_b128 v[66:69], v1 offset:49904
	s_waitcnt lgkmcnt(14)
	v_pk_fma_f32 v[242:243], v[34:35], v[74:75], v[242:243] neg_lo:[1,0,0] neg_hi:[1,0,0]
	v_pk_fma_f32 v[244:245], v[36:37], v[76:77], v[244:245] neg_lo:[1,0,0] neg_hi:[1,0,0]
	ds_read_b128 v[70:73], v1 offset:49920
	s_waitcnt lgkmcnt(14)
	v_pk_fma_f32 v[242:243], v[38:39], v[78:79], v[242:243] neg_lo:[1,0,0] neg_hi:[1,0,0]
	v_pk_fma_f32 v[244:245], v[40:41], v[80:81], v[244:245] neg_lo:[1,0,0] neg_hi:[1,0,0]
	ds_read_b128 v[74:77], v1 offset:49936
	s_waitcnt lgkmcnt(14)
	v_pk_fma_f32 v[242:243], v[42:43], v[82:83], v[242:243] neg_lo:[1,0,0] neg_hi:[1,0,0]
	v_pk_fma_f32 v[244:245], v[44:45], v[84:85], v[244:245] neg_lo:[1,0,0] neg_hi:[1,0,0]
	ds_read_b128 v[78:81], v1 offset:49952
	s_waitcnt lgkmcnt(14)
	v_pk_fma_f32 v[242:243], v[46:47], v[86:87], v[242:243] neg_lo:[1,0,0] neg_hi:[1,0,0]
	v_pk_fma_f32 v[244:245], v[48:49], v[88:89], v[244:245] neg_lo:[1,0,0] neg_hi:[1,0,0]
	ds_read_b128 v[82:85], v1 offset:49968
	s_waitcnt lgkmcnt(14)
; #define SUB_LROW(buf, i_, j0_, n_) do { _Pragma("unroll") for (int j4 = 0; j4 < (n_); ++j4) buf[j4] = *(const f32x4*)(Ls + (i_) * 68 + 4 * ((j0_) + j4)); } while (0)
; #define SUB_FROW(buf, j0_, n_) do { _Pragma("unroll") for (int j4 = 0; j4 < (n_); ++j4) { const f32x4 l = buf[j4]; \
;                 acc -= l.x * x[4 * ((j0_) + j4)]; acc -= l.y * x[4 * ((j0_) + j4) + 1]; acc -= l.z * x[4 * ((j0_) + j4) + 2]; acc -= l.w * x[4 * ((j0_) + j4) + 3]; } } while (0)
; __device__ __forceinline__ void gdn_prep(KA a, int layer, unsigned char* lds, const int tid_, const int bid_) {
;     ...
; #pragma unroll
;             for (int j4 = 0; j4 < 8; ++j4) { bufA[j4] = (f32x4){0.f, 0.f, 0.f, 0.f}; bufB[j4] = (f32x4){0.f, 0.f, 0.f, 0.f}; }
;             SUB_LROW(bufA, 1, 0, 1);
; #pragma unroll
;             for (int i = 1; i <= 32; ++i) {
;                 const int nn = (i + 4) / 4 < 8 ? (i + 4) / 4 : 8;
;                 float acc = x[i];
;                 if (i & 1) { SUB_LROW(bufB, i + 1, 0, nn); __builtin_amdgcn_sched_barrier(0); SUB_FROW(bufA, 0, (i + 3) / 4); }
;                 else       { SUB_LROW(bufA, i + 1, 0, nn); __builtin_amdgcn_sched_barrier(0); SUB_FROW(bufB, 0, (i + 3) / 4); }
;                 x[i] = acc;
;                 __builtin_amdgcn_sched_barrier(0);
;             }
; #pragma unroll
;             for (int i = 33; i < 64; ++i) {
;                 float acc = x[i];
;                 SUB_LROW(bufB, i, 8, (i + 3) / 4 - 8); __builtin_amdgcn_sched_barrier(0);
;                 SUB_FROW(bufA, 0, 8); __builtin_amdgcn_sched_barrier(0);
;                 if (i + 1 < 64) SUB_LROW(bufA, i + 1, 0, 8);
;                 __builtin_amdgcn_sched_barrier(0);
;                 SUB_FROW(bufB, 8, (i + 3) / 4 - 8);
;                 x[i] = acc;
;                 __builtin_amdgcn_sched_barrier(0);
;             }
	v_pk_fma_f32 v[242:243], v[50:51], v[116:117], v[242:243] neg_lo:[1,0,0] neg_hi:[1,0,0]
	v_pk_fma_f32 v[244:245], v[52:53], v[118:119], v[244:245] neg_lo:[1,0,0] neg_hi:[1,0,0]
	ds_read_b128 v[86:89], v1 offset:49984
	s_waitcnt lgkmcnt(14)
	v_pk_fma_f32 v[242:243], v[54:55], v[120:121], v[242:243] neg_lo:[1,0,0] neg_hi:[1,0,0]
	v_pk_fma_f32 v[244:245], v[56:57], v[122:123], v[244:245] neg_lo:[1,0,0] neg_hi:[1,0,0]
	ds_read_b128 v[116:119], v1 offset:50048
	s_nop 0
	v_pk_add_f32 v[242:243], v[242:243], v[244:245]
	s_nop 0
	v_add_f32_e32 v242, v242, v243
	v_add_f32_e32 v56, v56, v242
	s_waitcnt lgkmcnt(14)
	v_pk_mul_f32 v[242:243], v[2:3], v[124:125] neg_lo:[1,0] neg_hi:[1,0]
	v_pk_mul_f32 v[244:245], v[4:5], v[126:127] neg_lo:[1,0] neg_hi:[1,0]
	ds_read_b128 v[120:123], v1 offset:50064
	s_waitcnt lgkmcnt(14)
	v_pk_fma_f32 v[242:243], v[6:7], v[128:129], v[242:243] neg_lo:[1,0,0] neg_hi:[1,0,0]
	v_pk_fma_f32 v[244:245], v[8:9], v[130:131], v[244:245] neg_lo:[1,0,0] neg_hi:[1,0,0]
	ds_read_b128 v[124:127], v1 offset:50080
	s_waitcnt lgkmcnt(14)
	v_pk_fma_f32 v[242:243], v[10:11], v[132:133], v[242:243] neg_lo:[1,0,0] neg_hi:[1,0,0]
	v_pk_fma_f32 v[244:245], v[12:13], v[134:135], v[244:245] neg_lo:[1,0,0] neg_hi:[1,0,0]
	ds_read_b128 v[128:131], v1 offset:50096
	s_waitcnt lgkmcnt(14)
	v_pk_fma_f32 v[242:243], v[14:15], v[136:137], v[242:243] neg_lo:[1,0,0] neg_hi:[1,0,0]
	v_pk_fma_f32 v[244:245], v[16:17], v[138:139], v[244:245] neg_lo:[1,0,0] neg_hi:[1,0,0]
	ds_read_b128 v[132:135], v1 offset:50112
	s_waitcnt lgkmcnt(14)
	v_pk_fma_f32 v[242:243], v[18:19], v[140:141], v[242:243] neg_lo:[1,0,0] neg_hi:[1,0,0]
	v_pk_fma_f32 v[244:245], v[20:21], v[142:143], v[244:245] neg_lo:[1,0,0] neg_hi:[1,0,0]
	ds_read_b128 v[136:139], v1 offset:50128
	s_waitcnt lgkmcnt(14)
	v_pk_fma_f32 v[242:243], v[22:23], v[200:201], v[242:243] neg_lo:[1,0,0] neg_hi:[1,0,0]
	v_pk_fma_f32 v[244:245], v[24:25], v[202:203], v[244:245] neg_lo:[1,0,0] neg_hi:[1,0,0]
	ds_read_b128 v[140:143], v1 offset:50144
	s_waitcnt lgkmcnt(14)
	v_pk_fma_f32 v[242:243], v[26:27], v[204:205], v[242:243] neg_lo:[1,0,0] neg_hi:[1,0,0]
	v_pk_fma_f32 v[244:245], v[28:29], v[206:207], v[244:245] neg_lo:[1,0,0] neg_hi:[1,0,0]
	ds_read_b128 v[200:203], v1 offset:50160
	s_waitcnt lgkmcnt(14)
	v_pk_fma_f32 v[242:243], v[30:31], v[246:247], v[242:243] neg_lo:[1,0,0] neg_hi:[1,0,0]
	v_pk_fma_f32 v[244:245], v[32:33], v[248:249], v[244:245] neg_lo:[1,0,0] neg_hi:[1,0,0]
	ds_read_b128 v[204:207], v1 offset:50176
	s_waitcnt lgkmcnt(14)
	v_pk_fma_f32 v[242:243], v[34:35], v[66:67], v[242:243] neg_lo:[1,0,0] neg_hi:[1,0,0]
	v_pk_fma_f32 v[244:245], v[36:37], v[68:69], v[244:245] neg_lo:[1,0,0] neg_hi:[1,0,0]
	ds_read_b128 v[246:249], v1 offset:50192
	s_waitcnt lgkmcnt(14)
	v_pk_fma_f32 v[242:243], v[38:39], v[70:71], v[242:243] neg_lo:[1,0,0] neg_hi:[1,0,0]
	v_pk_fma_f32 v[244:245], v[40:41], v[72:73], v[244:245] neg_lo:[1,0,0] neg_hi:[1,0,0]
	ds_read_b128 v[66:69], v1 offset:50208
	s_waitcnt lgkmcnt(14)
	v_pk_fma_f32 v[242:243], v[42:43], v[74:75], v[242:243] neg_lo:[1,0,0] neg_hi:[1,0,0]
	v_pk_fma_f32 v[244:245], v[44:45], v[76:77], v[244:245] neg_lo:[1,0,0] neg_hi:[1,0,0]
	ds_read_b128 v[70:73], v1 offset:50224
	s_waitcnt lgkmcnt(14)
	v_pk_fma_f32 v[242:243], v[46:47], v[78:79], v[242:243] neg_lo:[1,0,0] neg_hi:[1,0,0]
	v_pk_fma_f32 v[244:245], v[48:49], v[80:81], v[244:245] neg_lo:[1,0,0] neg_hi:[1,0,0]
	ds_read_b128 v[74:77], v1 offset:50240
	s_waitcnt lgkmcnt(14)
	v_pk_fma_f32 v[242:243], v[50:51], v[82:83], v[242:243] neg_lo:[1,0,0] neg_hi:[1,0,0]
	v_pk_fma_f32 v[244:245], v[52:53], v[84:85], v[244:245] neg_lo:[1,0,0] neg_hi:[1,0,0]
	ds_read_b128 v[78:81], v1 offset:50256
	s_waitcnt lgkmcnt(14)
	v_pk_fma_f32 v[242:243], v[54:55], v[86:87], v[242:243] neg_lo:[1,0,0] neg_hi:[1,0,0]
	v_pk_fma_f32 v[244:245], v[56:57], v[88:89], v[244:245] neg_lo:[1,0,0] neg_hi:[1,0,0]
	ds_read_b128 v[82:85], v1 offset:50320
	s_nop 0
	v_pk_add_f32 v[242:243], v[242:243], v[244:245]
	s_nop 0
	v_add_f32_e32 v242, v242, v243
	v_add_f32_e32 v57, v57, v242
	s_waitcnt lgkmcnt(14)
	v_pk_mul_f32 v[242:243], v[2:3], v[116:117] neg_lo:[1,0] neg_hi:[1,0]
	v_pk_mul_f32 v[244:245], v[4:5], v[118:119] neg_lo:[1,0] neg_hi:[1,0]
	ds_read_b128 v[86:89], v1 offset:50336
	s_waitcnt lgkmcnt(14)
	v_pk_fma_f32 v[242:243], v[6:7], v[120:121], v[242:243] neg_lo:[1,0,0] neg_hi:[1,0,0]
	v_pk_fma_f32 v[244:245], v[8:9], v[122:123], v[244:245] neg_lo:[1,0,0] neg_hi:[1,0,0]
	ds_read_b128 v[116:119], v1 offset:50352
	s_waitcnt lgkmcnt(14)
	v_pk_fma_f32 v[242:243], v[10:11], v[124:125], v[242:243] neg_lo:[1,0,0] neg_hi:[1,0,0]
	v_pk_fma_f32 v[244:245], v[12:13], v[126:127], v[244:245] neg_lo:[1,0,0] neg_hi:[1,0,0]
	ds_read_b128 v[120:123], v1 offset:50368
	s_waitcnt lgkmcnt(14)
	v_pk_fma_f32 v[242:243], v[14:15], v[128:129], v[242:243] neg_lo:[1,0,0] neg_hi:[1,0,0]
	v_pk_fma_f32 v[244:245], v[16:17], v[130:131], v[244:245] neg_lo:[1,0,0] neg_hi:[1,0,0]
	ds_read_b128 v[124:127], v1 offset:50384
	s_waitcnt lgkmcnt(14)
	v_pk_fma_f32 v[242:243], v[18:19], v[132:133], v[242:243] neg_lo:[1,0,0] neg_hi:[1,0,0]
	v_pk_fma_f32 v[244:245], v[20:21], v[134:135], v[244:245] neg_lo:[1,0,0] neg_hi:[1,0,0]
	ds_read_b128 v[128:131], v1 offset:50400
	s_waitcnt lgkmcnt(14)
	v_pk_fma_f32 v[242:243], v[22:23], v[136:137], v[242:243] neg_lo:[1,0,0] neg_hi:[1,0,0]
	v_pk_fma_f32 v[244:245], v[24:25], v[138:139], v[244:245] neg_lo:[1,0,0] neg_hi:[1,0,0]
	ds_read_b128 v[132:135], v1 offset:50416
	s_waitcnt lgkmcnt(14)
	v_pk_fma_f32 v[242:243], v[26:27], v[140:141], v[242:243] neg_lo:[1,0,0] neg_hi:[1,0,0]
	v_pk_fma_f32 v[244:245], v[28:29], v[142:143], v[244:245] neg_lo:[1,0,0] neg_hi:[1,0,0]
	ds_read_b128 v[136:139], v1 offset:50432
	s_waitcnt lgkmcnt(14)
; #define SUB_LROW(buf, i_, j0_, n_) do { _Pragma("unroll") for (int j4 = 0; j4 < (n_); ++j4) buf[j4] = *(const f32x4*)(Ls + (i_) * 68 + 4 * ((j0_) + j4)); } while (0)
; #define SUB_FROW(buf, j0_, n_) do { _Pragma("unroll") for (int j4 = 0; j4 < (n_); ++j4) { const f32x4 l = buf[j4]; \
;                 acc -= l.x * x[4 * ((j0_) + j4)]; acc -= l.y * x[4 * ((j0_) + j4) + 1]; acc -= l.z * x[4 * ((j0_) + j4) + 2]; acc -= l.w * x[4 * ((j0_) + j4) + 3]; } } while (0)
; __device__ __forceinline__ void gdn_prep(KA a, int layer, unsigned char* lds, const int tid_, const int bid_) {
;     ...
; #pragma unroll
;             for (int j4 = 0; j4 < 8; ++j4) { bufA[j4] = (f32x4){0.f, 0.f, 0.f, 0.f}; bufB[j4] = (f32x4){0.f, 0.f, 0.f, 0.f}; }
;             SUB_LROW(bufA, 1, 0, 1);
; #pragma unroll
;             for (int i = 1; i <= 32; ++i) {
;                 const int nn = (i + 4) / 4 < 8 ? (i + 4) / 4 : 8;
;                 float acc = x[i];
;                 if (i & 1) { SUB_LROW(bufB, i + 1, 0, nn); __builtin_amdgcn_sched_barrier(0); SUB_FROW(bufA, 0, (i + 3) / 4); }
;                 else       { SUB_LROW(bufA, i + 1, 0, nn); __builtin_amdgcn_sched_barrier(0); SUB_FROW(bufB, 0, (i + 3) / 4); }
;                 x[i] = acc;
;                 __builtin_amdgcn_sched_barrier(0);
;             }
; #pragma unroll
;             for (int i = 33; i < 64; ++i) {
;                 float acc = x[i];
;                 SUB_LROW(bufB, i, 8, (i + 3) / 4 - 8); __builtin_amdgcn_sched_barrier(0);
;                 SUB_FROW(bufA, 0, 8); __builtin_amdgcn_sched_barrier(0);
;                 if (i + 1 < 64) SUB_LROW(bufA, i + 1, 0, 8);
;                 __builtin_amdgcn_sched_barrier(0);
;                 SUB_FROW(bufB, 8, (i + 3) / 4 - 8);
;                 x[i] = acc;
;                 __builtin_amdgcn_sched_barrier(0);
;             }
	v_pk_fma_f32 v[242:243], v[30:31], v[200:201], v[242:243] neg_lo:[1,0,0] neg_hi:[1,0,0]
	v_pk_fma_f32 v[244:245], v[32:33], v[202:203], v[244:245] neg_lo:[1,0,0] neg_hi:[1,0,0]
	ds_read_b128 v[140:143], v1 offset:50448
	s_waitcnt lgkmcnt(14)
	v_pk_fma_f32 v[242:243], v[34:35], v[204:205], v[242:243] neg_lo:[1,0,0] neg_hi:[1,0,0]
	v_pk_fma_f32 v[244:245], v[36:37], v[206:207], v[244:245] neg_lo:[1,0,0] neg_hi:[1,0,0]
	ds_read_b128 v[200:203], v1 offset:50464
	s_waitcnt lgkmcnt(14)
	v_pk_fma_f32 v[242:243], v[38:39], v[246:247], v[242:243] neg_lo:[1,0,0] neg_hi:[1,0,0]
	v_pk_fma_f32 v[244:245], v[40:41], v[248:249], v[244:245] neg_lo:[1,0,0] neg_hi:[1,0,0]
	ds_read_b128 v[204:207], v1 offset:50480
	s_waitcnt lgkmcnt(14)
	v_pk_fma_f32 v[242:243], v[42:43], v[66:67], v[242:243] neg_lo:[1,0,0] neg_hi:[1,0,0]
	v_pk_fma_f32 v[244:245], v[44:45], v[68:69], v[244:245] neg_lo:[1,0,0] neg_hi:[1,0,0]
	ds_read_b128 v[246:249], v1 offset:50496
	s_waitcnt lgkmcnt(14)
	v_pk_fma_f32 v[242:243], v[46:47], v[70:71], v[242:243] neg_lo:[1,0,0] neg_hi:[1,0,0]
	v_pk_fma_f32 v[244:245], v[48:49], v[72:73], v[244:245] neg_lo:[1,0,0] neg_hi:[1,0,0]
	ds_read_b128 v[66:69], v1 offset:50512
	s_waitcnt lgkmcnt(14)
	v_pk_fma_f32 v[242:243], v[50:51], v[74:75], v[242:243] neg_lo:[1,0,0] neg_hi:[1,0,0]
	v_pk_fma_f32 v[244:245], v[52:53], v[76:77], v[244:245] neg_lo:[1,0,0] neg_hi:[1,0,0]
	ds_read_b128 v[70:73], v1 offset:50528
	s_waitcnt lgkmcnt(14)
	v_pk_fma_f32 v[242:243], v[54:55], v[78:79], v[242:243] neg_lo:[1,0,0] neg_hi:[1,0,0]
	v_pk_fma_f32 v[244:245], v[56:57], v[80:81], v[244:245] neg_lo:[1,0,0] neg_hi:[1,0,0]
	ds_read_b128 v[74:77], v1 offset:50544
	s_nop 0
	v_pk_add_f32 v[242:243], v[242:243], v[244:245]
	s_nop 0
	v_add_f32_e32 v242, v242, v243
	v_add_f32_e32 v58, v58, v242
	s_waitcnt lgkmcnt(14)
	v_pk_mul_f32 v[242:243], v[2:3], v[82:83] neg_lo:[1,0] neg_hi:[1,0]
	v_pk_mul_f32 v[244:245], v[4:5], v[84:85] neg_lo:[1,0] neg_hi:[1,0]
	ds_read_b128 v[78:81], v1 offset:50592
	s_waitcnt lgkmcnt(14)
	v_pk_fma_f32 v[242:243], v[6:7], v[86:87], v[242:243] neg_lo:[1,0,0] neg_hi:[1,0,0]
	v_pk_fma_f32 v[244:245], v[8:9], v[88:89], v[244:245] neg_lo:[1,0,0] neg_hi:[1,0,0]
	ds_read_b128 v[82:85], v1 offset:50608
	s_waitcnt lgkmcnt(14)
	v_pk_fma_f32 v[242:243], v[10:11], v[116:117], v[242:243] neg_lo:[1,0,0] neg_hi:[1,0,0]
	v_pk_fma_f32 v[244:245], v[12:13], v[118:119], v[244:245] neg_lo:[1,0,0] neg_hi:[1,0,0]
	ds_read_b128 v[86:89], v1 offset:50624
	s_waitcnt lgkmcnt(14)
	v_pk_fma_f32 v[242:243], v[14:15], v[120:121], v[242:243] neg_lo:[1,0,0] neg_hi:[1,0,0]
	v_pk_fma_f32 v[244:245], v[16:17], v[122:123], v[244:245] neg_lo:[1,0,0] neg_hi:[1,0,0]
	ds_read_b128 v[116:119], v1 offset:50640
	s_waitcnt lgkmcnt(14)
	v_pk_fma_f32 v[242:243], v[18:19], v[124:125], v[242:243] neg_lo:[1,0,0] neg_hi:[1,0,0]
	v_pk_fma_f32 v[244:245], v[20:21], v[126:127], v[244:245] neg_lo:[1,0,0] neg_hi:[1,0,0]
	ds_read_b128 v[120:123], v1 offset:50656
	s_waitcnt lgkmcnt(14)
	v_pk_fma_f32 v[242:243], v[22:23], v[128:129], v[242:243] neg_lo:[1,0,0] neg_hi:[1,0,0]
	v_pk_fma_f32 v[244:245], v[24:25], v[130:131], v[244:245] neg_lo:[1,0,0] neg_hi:[1,0,0]
	ds_read_b128 v[124:127], v1 offset:50672
	s_waitcnt lgkmcnt(14)
	v_pk_fma_f32 v[242:243], v[26:27], v[132:133], v[242:243] neg_lo:[1,0,0] neg_hi:[1,0,0]
	v_pk_fma_f32 v[244:245], v[28:29], v[134:135], v[244:245] neg_lo:[1,0,0] neg_hi:[1,0,0]
	ds_read_b128 v[128:131], v1 offset:50688
	s_waitcnt lgkmcnt(14)
	v_pk_fma_f32 v[242:243], v[30:31], v[136:137], v[242:243] neg_lo:[1,0,0] neg_hi:[1,0,0]
	v_pk_fma_f32 v[244:245], v[32:33], v[138:139], v[244:245] neg_lo:[1,0,0] neg_hi:[1,0,0]
	ds_read_b128 v[132:135], v1 offset:50704
	s_waitcnt lgkmcnt(14)
	v_pk_fma_f32 v[242:243], v[34:35], v[140:141], v[242:243] neg_lo:[1,0,0] neg_hi:[1,0,0]
	v_pk_fma_f32 v[244:245], v[36:37], v[142:143], v[244:245] neg_lo:[1,0,0] neg_hi:[1,0,0]
	ds_read_b128 v[136:139], v1 offset:50720
	s_waitcnt lgkmcnt(14)
	v_pk_fma_f32 v[242:243], v[38:39], v[200:201], v[242:243] neg_lo:[1,0,0] neg_hi:[1,0,0]
	v_pk_fma_f32 v[244:245], v[40:41], v[202:203], v[244:245] neg_lo:[1,0,0] neg_hi:[1,0,0]
	ds_read_b128 v[140:143], v1 offset:50736
	s_waitcnt lgkmcnt(14)
	v_pk_fma_f32 v[242:243], v[42:43], v[204:205], v[242:243] neg_lo:[1,0,0] neg_hi:[1,0,0]
	v_pk_fma_f32 v[244:245], v[44:45], v[206:207], v[244:245] neg_lo:[1,0,0] neg_hi:[1,0,0]
	ds_read_b128 v[200:203], v1 offset:50752
	s_waitcnt lgkmcnt(14)
	v_pk_fma_f32 v[242:243], v[46:47], v[246:247], v[242:243] neg_lo:[1,0,0] neg_hi:[1,0,0]
	v_pk_fma_f32 v[244:245], v[48:49], v[248:249], v[244:245] neg_lo:[1,0,0] neg_hi:[1,0,0]
	ds_read_b128 v[204:207], v1 offset:50768
	s_waitcnt lgkmcnt(14)
	v_pk_fma_f32 v[242:243], v[50:51], v[66:67], v[242:243] neg_lo:[1,0,0] neg_hi:[1,0,0]
	v_pk_fma_f32 v[244:245], v[52:53], v[68:69], v[244:245] neg_lo:[1,0,0] neg_hi:[1,0,0]
	ds_read_b128 v[246:249], v1 offset:50784
	s_waitcnt lgkmcnt(14)
	v_pk_fma_f32 v[242:243], v[54:55], v[70:71], v[242:243] neg_lo:[1,0,0] neg_hi:[1,0,0]
	v_pk_fma_f32 v[244:245], v[56:57], v[72:73], v[244:245] neg_lo:[1,0,0] neg_hi:[1,0,0]
	ds_read_b128 v[66:69], v1 offset:50800
	s_waitcnt lgkmcnt(14)
	v_pk_fma_f32 v[242:243], v[58:59], v[74:75], v[242:243] neg_lo:[1,0,0] neg_hi:[1,0,0]
	v_pk_fma_f32 v[244:245], v[60:61], v[76:77], v[244:245] neg_lo:[1,0,0] neg_hi:[1,0,0]
	ds_read_b128 v[70:73], v1 offset:50816
	s_nop 0
	v_pk_add_f32 v[242:243], v[242:243], v[244:245]
	s_nop 0
	v_add_f32_e32 v242, v242, v243
	v_add_f32_e32 v59, v59, v242
	s_waitcnt lgkmcnt(14)
	v_pk_mul_f32 v[242:243], v[2:3], v[78:79] neg_lo:[1,0] neg_hi:[1,0]
	v_pk_mul_f32 v[244:245], v[4:5], v[80:81] neg_lo:[1,0] neg_hi:[1,0]
	ds_read_b128 v[74:77], v1 offset:50864
	s_waitcnt lgkmcnt(14)
; #define SUB_LROW(buf, i_, j0_, n_) do { _Pragma("unroll") for (int j4 = 0; j4 < (n_); ++j4) buf[j4] = *(const f32x4*)(Ls + (i_) * 68 + 4 * ((j0_) + j4)); } while (0)
; #define SUB_FROW(buf, j0_, n_) do { _Pragma("unroll") for (int j4 = 0; j4 < (n_); ++j4) { const f32x4 l = buf[j4]; \
;                 acc -= l.x * x[4 * ((j0_) + j4)]; acc -= l.y * x[4 * ((j0_) + j4) + 1]; acc -= l.z * x[4 * ((j0_) + j4) + 2]; acc -= l.w * x[4 * ((j0_) + j4) + 3]; } } while (0)
; __device__ __forceinline__ void gdn_prep(KA a, int layer, unsigned char* lds, const int tid_, const int bid_) {
;     ...
; #pragma unroll
;             for (int j4 = 0; j4 < 8; ++j4) { bufA[j4] = (f32x4){0.f, 0.f, 0.f, 0.f}; bufB[j4] = (f32x4){0.f, 0.f, 0.f, 0.f}; }
;             SUB_LROW(bufA, 1, 0, 1);
; #pragma unroll
;             for (int i = 1; i <= 32; ++i) {
;                 const int nn = (i + 4) / 4 < 8 ? (i + 4) / 4 : 8;
;                 float acc = x[i];
;                 if (i & 1) { SUB_LROW(bufB, i + 1, 0, nn); __builtin_amdgcn_sched_barrier(0); SUB_FROW(bufA, 0, (i + 3) / 4); }
;                 else       { SUB_LROW(bufA, i + 1, 0, nn); __builtin_amdgcn_sched_barrier(0); SUB_FROW(bufB, 0, (i + 3) / 4); }
;                 x[i] = acc;
;                 __builtin_amdgcn_sched_barrier(0);
;             }
; #pragma unroll
;             for (int i = 33; i < 64; ++i) {
;                 float acc = x[i];
;                 SUB_LROW(bufB, i, 8, (i + 3) / 4 - 8); __builtin_amdgcn_sched_barrier(0);
;                 SUB_FROW(bufA, 0, 8); __builtin_amdgcn_sched_barrier(0);
;                 if (i + 1 < 64) SUB_LROW(bufA, i + 1, 0, 8);
;                 __builtin_amdgcn_sched_barrier(0);
;                 SUB_FROW(bufB, 8, (i + 3) / 4 - 8);
;                 x[i] = acc;
;                 __builtin_amdgcn_sched_barrier(0);
;             }
	v_pk_fma_f32 v[242:243], v[6:7], v[82:83], v[242:243] neg_lo:[1,0,0] neg_hi:[1,0,0]
	v_pk_fma_f32 v[244:245], v[8:9], v[84:85], v[244:245] neg_lo:[1,0,0] neg_hi:[1,0,0]
	ds_read_b128 v[78:81], v1 offset:50880
	s_waitcnt lgkmcnt(14)
	v_pk_fma_f32 v[242:243], v[10:11], v[86:87], v[242:243] neg_lo:[1,0,0] neg_hi:[1,0,0]
	v_pk_fma_f32 v[244:245], v[12:13], v[88:89], v[244:245] neg_lo:[1,0,0] neg_hi:[1,0,0]
	ds_read_b128 v[82:85], v1 offset:50896
	s_waitcnt lgkmcnt(14)
	v_pk_fma_f32 v[242:243], v[14:15], v[116:117], v[242:243] neg_lo:[1,0,0] neg_hi:[1,0,0]
	v_pk_fma_f32 v[244:245], v[16:17], v[118:119], v[244:245] neg_lo:[1,0,0] neg_hi:[1,0,0]
	ds_read_b128 v[86:89], v1 offset:50912
	s_waitcnt lgkmcnt(14)
	v_pk_fma_f32 v[242:243], v[18:19], v[120:121], v[242:243] neg_lo:[1,0,0] neg_hi:[1,0,0]
	v_pk_fma_f32 v[244:245], v[20:21], v[122:123], v[244:245] neg_lo:[1,0,0] neg_hi:[1,0,0]
	ds_read_b128 v[116:119], v1 offset:50928
	s_waitcnt lgkmcnt(14)
	v_pk_fma_f32 v[242:243], v[22:23], v[124:125], v[242:243] neg_lo:[1,0,0] neg_hi:[1,0,0]
	v_pk_fma_f32 v[244:245], v[24:25], v[126:127], v[244:245] neg_lo:[1,0,0] neg_hi:[1,0,0]
	ds_read_b128 v[120:123], v1 offset:50944
	s_waitcnt lgkmcnt(14)
	v_pk_fma_f32 v[242:243], v[26:27], v[128:129], v[242:243] neg_lo:[1,0,0] neg_hi:[1,0,0]
	v_pk_fma_f32 v[244:245], v[28:29], v[130:131], v[244:245] neg_lo:[1,0,0] neg_hi:[1,0,0]
	ds_read_b128 v[124:127], v1 offset:50960
	s_waitcnt lgkmcnt(14)
	v_pk_fma_f32 v[242:243], v[30:31], v[132:133], v[242:243] neg_lo:[1,0,0] neg_hi:[1,0,0]
	v_pk_fma_f32 v[244:245], v[32:33], v[134:135], v[244:245] neg_lo:[1,0,0] neg_hi:[1,0,0]
	ds_read_b128 v[128:131], v1 offset:50976
	s_waitcnt lgkmcnt(14)
	v_pk_fma_f32 v[242:243], v[34:35], v[136:137], v[242:243] neg_lo:[1,0,0] neg_hi:[1,0,0]
	v_pk_fma_f32 v[244:245], v[36:37], v[138:139], v[244:245] neg_lo:[1,0,0] neg_hi:[1,0,0]
	ds_read_b128 v[132:135], v1 offset:50992
	s_waitcnt lgkmcnt(14)
	v_pk_fma_f32 v[242:243], v[38:39], v[140:141], v[242:243] neg_lo:[1,0,0] neg_hi:[1,0,0]
	v_pk_fma_f32 v[244:245], v[40:41], v[142:143], v[244:245] neg_lo:[1,0,0] neg_hi:[1,0,0]
	ds_read_b128 v[136:139], v1 offset:51008
	s_waitcnt lgkmcnt(14)
	v_pk_fma_f32 v[242:243], v[42:43], v[200:201], v[242:243] neg_lo:[1,0,0] neg_hi:[1,0,0]
	v_pk_fma_f32 v[244:245], v[44:45], v[202:203], v[244:245] neg_lo:[1,0,0] neg_hi:[1,0,0]
	ds_read_b128 v[140:143], v1 offset:51024
	s_waitcnt lgkmcnt(14)
	v_pk_fma_f32 v[242:243], v[46:47], v[204:205], v[242:243] neg_lo:[1,0,0] neg_hi:[1,0,0]
	v_pk_fma_f32 v[244:245], v[48:49], v[206:207], v[244:245] neg_lo:[1,0,0] neg_hi:[1,0,0]
	ds_read_b128 v[200:203], v1 offset:51040
	s_waitcnt lgkmcnt(14)
	v_pk_fma_f32 v[242:243], v[50:51], v[246:247], v[242:243] neg_lo:[1,0,0] neg_hi:[1,0,0]
	v_pk_fma_f32 v[244:245], v[52:53], v[248:249], v[244:245] neg_lo:[1,0,0] neg_hi:[1,0,0]
	ds_read_b128 v[204:207], v1 offset:51056
	s_waitcnt lgkmcnt(14)
	v_pk_fma_f32 v[242:243], v[54:55], v[66:67], v[242:243] neg_lo:[1,0,0] neg_hi:[1,0,0]
	v_pk_fma_f32 v[244:245], v[56:57], v[68:69], v[244:245] neg_lo:[1,0,0] neg_hi:[1,0,0]
	ds_read_b128 v[246:249], v1 offset:51072
	s_waitcnt lgkmcnt(14)
	v_pk_fma_f32 v[242:243], v[58:59], v[70:71], v[242:243] neg_lo:[1,0,0] neg_hi:[1,0,0]
	v_pk_fma_f32 v[244:245], v[60:61], v[72:73], v[244:245] neg_lo:[1,0,0] neg_hi:[1,0,0]
	ds_read_b128 v[66:69], v1 offset:51088
	s_nop 0
	v_pk_add_f32 v[242:243], v[242:243], v[244:245]
	s_nop 0
	v_add_f32_e32 v242, v242, v243
	v_add_f32_e32 v60, v60, v242
	s_waitcnt lgkmcnt(14)
	v_pk_mul_f32 v[242:243], v[2:3], v[74:75] neg_lo:[1,0] neg_hi:[1,0]
	v_pk_mul_f32 v[244:245], v[4:5], v[76:77] neg_lo:[1,0] neg_hi:[1,0]
	ds_read_b128 v[70:73], v1 offset:51136
	s_waitcnt lgkmcnt(14)
	v_pk_fma_f32 v[242:243], v[6:7], v[78:79], v[242:243] neg_lo:[1,0,0] neg_hi:[1,0,0]
	v_pk_fma_f32 v[244:245], v[8:9], v[80:81], v[244:245] neg_lo:[1,0,0] neg_hi:[1,0,0]
	ds_read_b128 v[74:77], v1 offset:51152
	s_waitcnt lgkmcnt(14)
	v_pk_fma_f32 v[242:243], v[10:11], v[82:83], v[242:243] neg_lo:[1,0,0] neg_hi:[1,0,0]
	v_pk_fma_f32 v[244:245], v[12:13], v[84:85], v[244:245] neg_lo:[1,0,0] neg_hi:[1,0,0]
	ds_read_b128 v[78:81], v1 offset:51168
	s_waitcnt lgkmcnt(14)
	v_pk_fma_f32 v[242:243], v[14:15], v[86:87], v[242:243] neg_lo:[1,0,0] neg_hi:[1,0,0]
	v_pk_fma_f32 v[244:245], v[16:17], v[88:89], v[244:245] neg_lo:[1,0,0] neg_hi:[1,0,0]
	ds_read_b128 v[82:85], v1 offset:51184
	s_waitcnt lgkmcnt(14)
	v_pk_fma_f32 v[242:243], v[18:19], v[116:117], v[242:243] neg_lo:[1,0,0] neg_hi:[1,0,0]
	v_pk_fma_f32 v[244:245], v[20:21], v[118:119], v[244:245] neg_lo:[1,0,0] neg_hi:[1,0,0]
	ds_read_b128 v[86:89], v1 offset:51200
	s_waitcnt lgkmcnt(14)
	v_pk_fma_f32 v[242:243], v[22:23], v[120:121], v[242:243] neg_lo:[1,0,0] neg_hi:[1,0,0]
	v_pk_fma_f32 v[244:245], v[24:25], v[122:123], v[244:245] neg_lo:[1,0,0] neg_hi:[1,0,0]
	ds_read_b128 v[116:119], v1 offset:51216
	s_waitcnt lgkmcnt(14)
	v_pk_fma_f32 v[242:243], v[26:27], v[124:125], v[242:243] neg_lo:[1,0,0] neg_hi:[1,0,0]
	v_pk_fma_f32 v[244:245], v[28:29], v[126:127], v[244:245] neg_lo:[1,0,0] neg_hi:[1,0,0]
	ds_read_b128 v[120:123], v1 offset:51232
	s_waitcnt lgkmcnt(14)
	v_pk_fma_f32 v[242:243], v[30:31], v[128:129], v[242:243] neg_lo:[1,0,0] neg_hi:[1,0,0]
	v_pk_fma_f32 v[244:245], v[32:33], v[130:131], v[244:245] neg_lo:[1,0,0] neg_hi:[1,0,0]
	ds_read_b128 v[124:127], v1 offset:51248
	s_waitcnt lgkmcnt(14)
	v_pk_fma_f32 v[242:243], v[34:35], v[132:133], v[242:243] neg_lo:[1,0,0] neg_hi:[1,0,0]
	v_pk_fma_f32 v[244:245], v[36:37], v[134:135], v[244:245] neg_lo:[1,0,0] neg_hi:[1,0,0]
	ds_read_b128 v[128:131], v1 offset:51264
	s_waitcnt lgkmcnt(14)
; #define SUB_LROW(buf, i_, j0_, n_) do { _Pragma("unroll") for (int j4 = 0; j4 < (n_); ++j4) buf[j4] = *(const f32x4*)(Ls + (i_) * 68 + 4 * ((j0_) + j4)); } while (0)
; #define SUB_FROW(buf, j0_, n_) do { _Pragma("unroll") for (int j4 = 0; j4 < (n_); ++j4) { const f32x4 l = buf[j4]; \
;                 acc -= l.x * x[4 * ((j0_) + j4)]; acc -= l.y * x[4 * ((j0_) + j4) + 1]; acc -= l.z * x[4 * ((j0_) + j4) + 2]; acc -= l.w * x[4 * ((j0_) + j4) + 3]; } } while (0)
; __device__ __forceinline__ void gdn_prep(KA a, int layer, unsigned char* lds, const int tid_, const int bid_) {
;     ...
; #pragma unroll
;             for (int j4 = 0; j4 < 8; ++j4) { bufA[j4] = (f32x4){0.f, 0.f, 0.f, 0.f}; bufB[j4] = (f32x4){0.f, 0.f, 0.f, 0.f}; }
;             SUB_LROW(bufA, 1, 0, 1);
; #pragma unroll
;             for (int i = 1; i <= 32; ++i) {
;                 const int nn = (i + 4) / 4 < 8 ? (i + 4) / 4 : 8;
;                 float acc = x[i];
;                 if (i & 1) { SUB_LROW(bufB, i + 1, 0, nn); __builtin_amdgcn_sched_barrier(0); SUB_FROW(bufA, 0, (i + 3) / 4); }
;                 else       { SUB_LROW(bufA, i + 1, 0, nn); __builtin_amdgcn_sched_barrier(0); SUB_FROW(bufB, 0, (i + 3) / 4); }
;                 x[i] = acc;
;                 __builtin_amdgcn_sched_barrier(0);
;             }
; #pragma unroll
;             for (int i = 33; i < 64; ++i) {
;                 float acc = x[i];
;                 SUB_LROW(bufB, i, 8, (i + 3) / 4 - 8); __builtin_amdgcn_sched_barrier(0);
;                 SUB_FROW(bufA, 0, 8); __builtin_amdgcn_sched_barrier(0);
;                 if (i + 1 < 64) SUB_LROW(bufA, i + 1, 0, 8);
;                 __builtin_amdgcn_sched_barrier(0);
;                 SUB_FROW(bufB, 8, (i + 3) / 4 - 8);
;                 x[i] = acc;
;                 __builtin_amdgcn_sched_barrier(0);
;             }
	v_pk_fma_f32 v[242:243], v[38:39], v[136:137], v[242:243] neg_lo:[1,0,0] neg_hi:[1,0,0]
	v_pk_fma_f32 v[244:245], v[40:41], v[138:139], v[244:245] neg_lo:[1,0,0] neg_hi:[1,0,0]
	ds_read_b128 v[132:135], v1 offset:51280
	s_waitcnt lgkmcnt(14)
	v_pk_fma_f32 v[242:243], v[42:43], v[140:141], v[242:243] neg_lo:[1,0,0] neg_hi:[1,0,0]
	v_pk_fma_f32 v[244:245], v[44:45], v[142:143], v[244:245] neg_lo:[1,0,0] neg_hi:[1,0,0]
	ds_read_b128 v[136:139], v1 offset:51296
	s_waitcnt lgkmcnt(14)
	v_pk_fma_f32 v[242:243], v[46:47], v[200:201], v[242:243] neg_lo:[1,0,0] neg_hi:[1,0,0]
	v_pk_fma_f32 v[244:245], v[48:49], v[202:203], v[244:245] neg_lo:[1,0,0] neg_hi:[1,0,0]
	ds_read_b128 v[140:143], v1 offset:51312
	s_waitcnt lgkmcnt(14)
	v_pk_fma_f32 v[242:243], v[50:51], v[204:205], v[242:243] neg_lo:[1,0,0] neg_hi:[1,0,0]
	v_pk_fma_f32 v[244:245], v[52:53], v[206:207], v[244:245] neg_lo:[1,0,0] neg_hi:[1,0,0]
	ds_read_b128 v[200:203], v1 offset:51328
	s_waitcnt lgkmcnt(14)
	v_pk_fma_f32 v[242:243], v[54:55], v[246:247], v[242:243] neg_lo:[1,0,0] neg_hi:[1,0,0]
	v_pk_fma_f32 v[244:245], v[56:57], v[248:249], v[244:245] neg_lo:[1,0,0] neg_hi:[1,0,0]
	ds_read_b128 v[204:207], v1 offset:51344
	s_waitcnt lgkmcnt(14)
	v_pk_fma_f32 v[242:243], v[58:59], v[66:67], v[242:243] neg_lo:[1,0,0] neg_hi:[1,0,0]
	v_pk_fma_f32 v[244:245], v[60:61], v[68:69], v[244:245] neg_lo:[1,0,0] neg_hi:[1,0,0]
	ds_read_b128 v[246:249], v1 offset:51360
	s_nop 0
	v_pk_add_f32 v[242:243], v[242:243], v[244:245]
	s_nop 0
	v_add_f32_e32 v242, v242, v243
	v_add_f32_e32 v61, v61, v242
	s_waitcnt lgkmcnt(14)
	v_pk_mul_f32 v[242:243], v[2:3], v[70:71] neg_lo:[1,0] neg_hi:[1,0]
	v_pk_mul_f32 v[244:245], v[4:5], v[72:73] neg_lo:[1,0] neg_hi:[1,0]
	ds_read_b128 v[66:69], v1 offset:51408
	s_waitcnt lgkmcnt(14)
	v_pk_fma_f32 v[242:243], v[6:7], v[74:75], v[242:243] neg_lo:[1,0,0] neg_hi:[1,0,0]
	v_pk_fma_f32 v[244:245], v[8:9], v[76:77], v[244:245] neg_lo:[1,0,0] neg_hi:[1,0,0]
	ds_read_b128 v[70:73], v1 offset:51424
	s_waitcnt lgkmcnt(14)
	v_pk_fma_f32 v[242:243], v[10:11], v[78:79], v[242:243] neg_lo:[1,0,0] neg_hi:[1,0,0]
	v_pk_fma_f32 v[244:245], v[12:13], v[80:81], v[244:245] neg_lo:[1,0,0] neg_hi:[1,0,0]
	ds_read_b128 v[74:77], v1 offset:51440
	s_waitcnt lgkmcnt(14)
	v_pk_fma_f32 v[242:243], v[14:15], v[82:83], v[242:243] neg_lo:[1,0,0] neg_hi:[1,0,0]
	v_pk_fma_f32 v[244:245], v[16:17], v[84:85], v[244:245] neg_lo:[1,0,0] neg_hi:[1,0,0]
	ds_read_b128 v[78:81], v1 offset:51456
	s_waitcnt lgkmcnt(14)
	v_pk_fma_f32 v[242:243], v[18:19], v[86:87], v[242:243] neg_lo:[1,0,0] neg_hi:[1,0,0]
	v_pk_fma_f32 v[244:245], v[20:21], v[88:89], v[244:245] neg_lo:[1,0,0] neg_hi:[1,0,0]
	ds_read_b128 v[82:85], v1 offset:51472
	s_waitcnt lgkmcnt(14)
	v_pk_fma_f32 v[242:243], v[22:23], v[116:117], v[242:243] neg_lo:[1,0,0] neg_hi:[1,0,0]
	v_pk_fma_f32 v[244:245], v[24:25], v[118:119], v[244:245] neg_lo:[1,0,0] neg_hi:[1,0,0]
	ds_read_b128 v[86:89], v1 offset:51488
	s_waitcnt lgkmcnt(14)
	v_pk_fma_f32 v[242:243], v[26:27], v[120:121], v[242:243] neg_lo:[1,0,0] neg_hi:[1,0,0]
	v_pk_fma_f32 v[244:245], v[28:29], v[122:123], v[244:245] neg_lo:[1,0,0] neg_hi:[1,0,0]
	ds_read_b128 v[116:119], v1 offset:51504
	s_waitcnt lgkmcnt(14)
	v_pk_fma_f32 v[242:243], v[30:31], v[124:125], v[242:243] neg_lo:[1,0,0] neg_hi:[1,0,0]
	v_pk_fma_f32 v[244:245], v[32:33], v[126:127], v[244:245] neg_lo:[1,0,0] neg_hi:[1,0,0]
	ds_read_b128 v[120:123], v1 offset:51520
	s_waitcnt lgkmcnt(14)
	v_pk_fma_f32 v[242:243], v[34:35], v[128:129], v[242:243] neg_lo:[1,0,0] neg_hi:[1,0,0]
	v_pk_fma_f32 v[244:245], v[36:37], v[130:131], v[244:245] neg_lo:[1,0,0] neg_hi:[1,0,0]
	ds_read_b128 v[124:127], v1 offset:51536
	s_waitcnt lgkmcnt(14)
	v_pk_fma_f32 v[242:243], v[38:39], v[132:133], v[242:243] neg_lo:[1,0,0] neg_hi:[1,0,0]
	v_pk_fma_f32 v[244:245], v[40:41], v[134:135], v[244:245] neg_lo:[1,0,0] neg_hi:[1,0,0]
	ds_read_b128 v[128:131], v1 offset:51552
	s_waitcnt lgkmcnt(14)
	v_pk_fma_f32 v[242:243], v[42:43], v[136:137], v[242:243] neg_lo:[1,0,0] neg_hi:[1,0,0]
	v_pk_fma_f32 v[244:245], v[44:45], v[138:139], v[244:245] neg_lo:[1,0,0] neg_hi:[1,0,0]
	ds_read_b128 v[132:135], v1 offset:51568
	s_waitcnt lgkmcnt(14)
	v_pk_fma_f32 v[242:243], v[46:47], v[140:141], v[242:243] neg_lo:[1,0,0] neg_hi:[1,0,0]
	v_pk_fma_f32 v[244:245], v[48:49], v[142:143], v[244:245] neg_lo:[1,0,0] neg_hi:[1,0,0]
	ds_read_b128 v[136:139], v1 offset:51584
	s_waitcnt lgkmcnt(14)
	v_pk_fma_f32 v[242:243], v[50:51], v[200:201], v[242:243] neg_lo:[1,0,0] neg_hi:[1,0,0]
	v_pk_fma_f32 v[244:245], v[52:53], v[202:203], v[244:245] neg_lo:[1,0,0] neg_hi:[1,0,0]
	ds_read_b128 v[140:143], v1 offset:51600
	s_waitcnt lgkmcnt(14)
	v_pk_fma_f32 v[242:243], v[54:55], v[204:205], v[242:243] neg_lo:[1,0,0] neg_hi:[1,0,0]
	v_pk_fma_f32 v[244:245], v[56:57], v[206:207], v[244:245] neg_lo:[1,0,0] neg_hi:[1,0,0]
	ds_read_b128 v[200:203], v1 offset:51616
	s_waitcnt lgkmcnt(14)
	v_pk_fma_f32 v[242:243], v[58:59], v[246:247], v[242:243] neg_lo:[1,0,0] neg_hi:[1,0,0]
	v_pk_fma_f32 v[244:245], v[60:61], v[248:249], v[244:245] neg_lo:[1,0,0] neg_hi:[1,0,0]
	ds_read_b128 v[204:207], v1 offset:51632
	s_nop 0
	v_pk_add_f32 v[242:243], v[242:243], v[244:245]
	s_nop 0
	v_add_f32_e32 v242, v242, v243
	v_add_f32_e32 v62, v62, v242
	s_waitcnt lgkmcnt(14)
	v_pk_mul_f32 v[242:243], v[2:3], v[66:67] neg_lo:[1,0] neg_hi:[1,0]
	v_pk_mul_f32 v[244:245], v[4:5], v[68:69] neg_lo:[1,0] neg_hi:[1,0]
	ds_read_b128 v[246:249], v1 offset:51648
	s_waitcnt lgkmcnt(14)
	v_pk_fma_f32 v[242:243], v[6:7], v[70:71], v[242:243] neg_lo:[1,0,0] neg_hi:[1,0,0]
	v_pk_fma_f32 v[244:245], v[8:9], v[72:73], v[244:245] neg_lo:[1,0,0] neg_hi:[1,0,0]
	ds_read_b128 v[66:69], v1 offset:51680
	s_waitcnt lgkmcnt(14)
; #define SUB_LROW(buf, i_, j0_, n_) do { _Pragma("unroll") for (int j4 = 0; j4 < (n_); ++j4) buf[j4] = *(const f32x4*)(Ls + (i_) * 68 + 4 * ((j0_) + j4)); } while (0)
; #define SUB_FROW(buf, j0_, n_) do { _Pragma("unroll") for (int j4 = 0; j4 < (n_); ++j4) { const f32x4 l = buf[j4]; \
;                 acc -= l.x * x[4 * ((j0_) + j4)]; acc -= l.y * x[4 * ((j0_) + j4) + 1]; acc -= l.z * x[4 * ((j0_) + j4) + 2]; acc -= l.w * x[4 * ((j0_) + j4) + 3]; } } while (0)
; __device__ __forceinline__ void gdn_prep(KA a, int layer, unsigned char* lds, const int tid_, const int bid_) {
;     ...
; #pragma unroll
;             for (int j4 = 0; j4 < 8; ++j4) { bufA[j4] = (f32x4){0.f, 0.f, 0.f, 0.f}; bufB[j4] = (f32x4){0.f, 0.f, 0.f, 0.f}; }
;             SUB_LROW(bufA, 1, 0, 1);
; #pragma unroll
;             for (int i = 1; i <= 32; ++i) {
;                 const int nn = (i + 4) / 4 < 8 ? (i + 4) / 4 : 8;
;                 float acc = x[i];
;                 if (i & 1) { SUB_LROW(bufB, i + 1, 0, nn); __builtin_amdgcn_sched_barrier(0); SUB_FROW(bufA, 0, (i + 3) / 4); }
;                 else       { SUB_LROW(bufA, i + 1, 0, nn); __builtin_amdgcn_sched_barrier(0); SUB_FROW(bufB, 0, (i + 3) / 4); }
;                 x[i] = acc;
;                 __builtin_amdgcn_sched_barrier(0);
;             }
; #pragma unroll
;             for (int i = 33; i < 64; ++i) {
;                 float acc = x[i];
;                 SUB_LROW(bufB, i, 8, (i + 3) / 4 - 8); __builtin_amdgcn_sched_barrier(0);
;                 SUB_FROW(bufA, 0, 8); __builtin_amdgcn_sched_barrier(0);
;                 if (i + 1 < 64) SUB_LROW(bufA, i + 1, 0, 8);
;                 __builtin_amdgcn_sched_barrier(0);
;                 SUB_FROW(bufB, 8, (i + 3) / 4 - 8);
;                 x[i] = acc;
;                 __builtin_amdgcn_sched_barrier(0);
;             }
	v_pk_fma_f32 v[242:243], v[10:11], v[74:75], v[242:243] neg_lo:[1,0,0] neg_hi:[1,0,0]
	v_pk_fma_f32 v[244:245], v[12:13], v[76:77], v[244:245] neg_lo:[1,0,0] neg_hi:[1,0,0]
	ds_read_b128 v[70:73], v1 offset:51696
	s_waitcnt lgkmcnt(14)
	v_pk_fma_f32 v[242:243], v[14:15], v[78:79], v[242:243] neg_lo:[1,0,0] neg_hi:[1,0,0]
	v_pk_fma_f32 v[244:245], v[16:17], v[80:81], v[244:245] neg_lo:[1,0,0] neg_hi:[1,0,0]
	ds_read_b128 v[74:77], v1 offset:51712
	s_waitcnt lgkmcnt(14)
	v_pk_fma_f32 v[242:243], v[18:19], v[82:83], v[242:243] neg_lo:[1,0,0] neg_hi:[1,0,0]
	v_pk_fma_f32 v[244:245], v[20:21], v[84:85], v[244:245] neg_lo:[1,0,0] neg_hi:[1,0,0]
	ds_read_b128 v[78:81], v1 offset:51728
	s_waitcnt lgkmcnt(14)
	v_pk_fma_f32 v[242:243], v[22:23], v[86:87], v[242:243] neg_lo:[1,0,0] neg_hi:[1,0,0]
	v_pk_fma_f32 v[244:245], v[24:25], v[88:89], v[244:245] neg_lo:[1,0,0] neg_hi:[1,0,0]
	ds_read_b128 v[82:85], v1 offset:51744
	s_waitcnt lgkmcnt(14)
	v_pk_fma_f32 v[242:243], v[26:27], v[116:117], v[242:243] neg_lo:[1,0,0] neg_hi:[1,0,0]
	v_pk_fma_f32 v[244:245], v[28:29], v[118:119], v[244:245] neg_lo:[1,0,0] neg_hi:[1,0,0]
	ds_read_b128 v[86:89], v1 offset:51760
	s_waitcnt lgkmcnt(14)
	v_pk_fma_f32 v[242:243], v[30:31], v[120:121], v[242:243] neg_lo:[1,0,0] neg_hi:[1,0,0]
	v_pk_fma_f32 v[244:245], v[32:33], v[122:123], v[244:245] neg_lo:[1,0,0] neg_hi:[1,0,0]
	ds_read_b128 v[116:119], v1 offset:51776
	s_waitcnt lgkmcnt(14)
	v_pk_fma_f32 v[242:243], v[34:35], v[124:125], v[242:243] neg_lo:[1,0,0] neg_hi:[1,0,0]
	v_pk_fma_f32 v[244:245], v[36:37], v[126:127], v[244:245] neg_lo:[1,0,0] neg_hi:[1,0,0]
	ds_read_b128 v[120:123], v1 offset:51792
	s_waitcnt lgkmcnt(14)
	v_pk_fma_f32 v[242:243], v[38:39], v[128:129], v[242:243] neg_lo:[1,0,0] neg_hi:[1,0,0]
	v_pk_fma_f32 v[244:245], v[40:41], v[130:131], v[244:245] neg_lo:[1,0,0] neg_hi:[1,0,0]
	ds_read_b128 v[124:127], v1 offset:51808
	s_waitcnt lgkmcnt(14)
	v_pk_fma_f32 v[242:243], v[42:43], v[132:133], v[242:243] neg_lo:[1,0,0] neg_hi:[1,0,0]
	v_pk_fma_f32 v[244:245], v[44:45], v[134:135], v[244:245] neg_lo:[1,0,0] neg_hi:[1,0,0]
	ds_read_b128 v[128:131], v1 offset:51824
	s_waitcnt lgkmcnt(14)
	v_pk_fma_f32 v[242:243], v[46:47], v[136:137], v[242:243] neg_lo:[1,0,0] neg_hi:[1,0,0]
	v_pk_fma_f32 v[244:245], v[48:49], v[138:139], v[244:245] neg_lo:[1,0,0] neg_hi:[1,0,0]
	ds_read_b128 v[132:135], v1 offset:51840
	s_waitcnt lgkmcnt(14)
	v_pk_fma_f32 v[242:243], v[50:51], v[140:141], v[242:243] neg_lo:[1,0,0] neg_hi:[1,0,0]
	v_pk_fma_f32 v[244:245], v[52:53], v[142:143], v[244:245] neg_lo:[1,0,0] neg_hi:[1,0,0]
	ds_read_b128 v[136:139], v1 offset:51856
	s_waitcnt lgkmcnt(14)
	v_pk_fma_f32 v[242:243], v[54:55], v[200:201], v[242:243] neg_lo:[1,0,0] neg_hi:[1,0,0]
	v_pk_fma_f32 v[244:245], v[56:57], v[202:203], v[244:245] neg_lo:[1,0,0] neg_hi:[1,0,0]
	ds_read_b128 v[140:143], v1 offset:51872
	s_waitcnt lgkmcnt(14)
	v_pk_fma_f32 v[242:243], v[58:59], v[204:205], v[242:243] neg_lo:[1,0,0] neg_hi:[1,0,0]
	v_pk_fma_f32 v[244:245], v[60:61], v[206:207], v[244:245] neg_lo:[1,0,0] neg_hi:[1,0,0]
	ds_read_b128 v[200:203], v1 offset:51888
	s_waitcnt lgkmcnt(14)
	v_pk_fma_f32 v[242:243], v[62:63], v[246:247], v[242:243] neg_lo:[1,0,0] neg_hi:[1,0,0]
	v_pk_fma_f32 v[244:245], v[64:65], v[248:249], v[244:245] neg_lo:[1,0,0] neg_hi:[1,0,0]
	ds_read_b128 v[204:207], v1 offset:51904
	s_nop 0
	v_pk_add_f32 v[242:243], v[242:243], v[244:245]
	s_nop 0
	v_add_f32_e32 v242, v242, v243
	v_add_f32_e32 v63, v63, v242
	s_waitcnt lgkmcnt(14)
	v_pk_mul_f32 v[242:243], v[2:3], v[66:67] neg_lo:[1,0] neg_hi:[1,0]
	v_pk_mul_f32 v[244:245], v[4:5], v[68:69] neg_lo:[1,0] neg_hi:[1,0]
	ds_read_b128 v[246:249], v1 offset:51920
	s_waitcnt lgkmcnt(14)
	v_pk_fma_f32 v[242:243], v[6:7], v[70:71], v[242:243] neg_lo:[1,0,0] neg_hi:[1,0,0]
	v_pk_fma_f32 v[244:245], v[8:9], v[72:73], v[244:245] neg_lo:[1,0,0] neg_hi:[1,0,0]
	ds_read_b128 v[66:69], v1 offset:51952
	s_waitcnt lgkmcnt(14)
	v_pk_fma_f32 v[242:243], v[10:11], v[74:75], v[242:243] neg_lo:[1,0,0] neg_hi:[1,0,0]
	v_pk_fma_f32 v[244:245], v[12:13], v[76:77], v[244:245] neg_lo:[1,0,0] neg_hi:[1,0,0]
	ds_read_b128 v[70:73], v1 offset:51968
	s_waitcnt lgkmcnt(14)
	v_pk_fma_f32 v[242:243], v[14:15], v[78:79], v[242:243] neg_lo:[1,0,0] neg_hi:[1,0,0]
	v_pk_fma_f32 v[244:245], v[16:17], v[80:81], v[244:245] neg_lo:[1,0,0] neg_hi:[1,0,0]
	ds_read_b128 v[74:77], v1 offset:51984
	s_waitcnt lgkmcnt(14)
	v_pk_fma_f32 v[242:243], v[18:19], v[82:83], v[242:243] neg_lo:[1,0,0] neg_hi:[1,0,0]
	v_pk_fma_f32 v[244:245], v[20:21], v[84:85], v[244:245] neg_lo:[1,0,0] neg_hi:[1,0,0]
	ds_read_b128 v[78:81], v1 offset:52000
	s_waitcnt lgkmcnt(14)
	v_pk_fma_f32 v[242:243], v[22:23], v[86:87], v[242:243] neg_lo:[1,0,0] neg_hi:[1,0,0]
	v_pk_fma_f32 v[244:245], v[24:25], v[88:89], v[244:245] neg_lo:[1,0,0] neg_hi:[1,0,0]
	ds_read_b128 v[82:85], v1 offset:52016
	s_waitcnt lgkmcnt(14)
	v_pk_fma_f32 v[242:243], v[26:27], v[116:117], v[242:243] neg_lo:[1,0,0] neg_hi:[1,0,0]
	v_pk_fma_f32 v[244:245], v[28:29], v[118:119], v[244:245] neg_lo:[1,0,0] neg_hi:[1,0,0]
	ds_read_b128 v[86:89], v1 offset:52032
	s_waitcnt lgkmcnt(14)
	v_pk_fma_f32 v[242:243], v[30:31], v[120:121], v[242:243] neg_lo:[1,0,0] neg_hi:[1,0,0]
	v_pk_fma_f32 v[244:245], v[32:33], v[122:123], v[244:245] neg_lo:[1,0,0] neg_hi:[1,0,0]
	ds_read_b128 v[116:119], v1 offset:52048
	s_waitcnt lgkmcnt(14)
	v_pk_fma_f32 v[242:243], v[34:35], v[124:125], v[242:243] neg_lo:[1,0,0] neg_hi:[1,0,0]
	v_pk_fma_f32 v[244:245], v[36:37], v[126:127], v[244:245] neg_lo:[1,0,0] neg_hi:[1,0,0]
	ds_read_b128 v[120:123], v1 offset:52064
	s_waitcnt lgkmcnt(14)
; #define SUB_LROW(buf, i_, j0_, n_) do { _Pragma("unroll") for (int j4 = 0; j4 < (n_); ++j4) buf[j4] = *(const f32x4*)(Ls + (i_) * 68 + 4 * ((j0_) + j4)); } while (0)
; #define SUB_FROW(buf, j0_, n_) do { _Pragma("unroll") for (int j4 = 0; j4 < (n_); ++j4) { const f32x4 l = buf[j4]; \
;                 acc -= l.x * x[4 * ((j0_) + j4)]; acc -= l.y * x[4 * ((j0_) + j4) + 1]; acc -= l.z * x[4 * ((j0_) + j4) + 2]; acc -= l.w * x[4 * ((j0_) + j4) + 3]; } } while (0)
; __device__ __forceinline__ void gdn_prep(KA a, int layer, unsigned char* lds, const int tid_, const int bid_) {
;     ...
; #pragma unroll
;             for (int j4 = 0; j4 < 8; ++j4) { bufA[j4] = (f32x4){0.f, 0.f, 0.f, 0.f}; bufB[j4] = (f32x4){0.f, 0.f, 0.f, 0.f}; }
;             SUB_LROW(bufA, 1, 0, 1);
; #pragma unroll
;             for (int i = 1; i <= 32; ++i) {
;                 const int nn = (i + 4) / 4 < 8 ? (i + 4) / 4 : 8;
;                 float acc = x[i];
;                 if (i & 1) { SUB_LROW(bufB, i + 1, 0, nn); __builtin_amdgcn_sched_barrier(0); SUB_FROW(bufA, 0, (i + 3) / 4); }
;                 else       { SUB_LROW(bufA, i + 1, 0, nn); __builtin_amdgcn_sched_barrier(0); SUB_FROW(bufB, 0, (i + 3) / 4); }
;                 x[i] = acc;
;                 __builtin_amdgcn_sched_barrier(0);
;             }
; #pragma unroll
;             for (int i = 33; i < 64; ++i) {
;                 float acc = x[i];
;                 SUB_LROW(bufB, i, 8, (i + 3) / 4 - 8); __builtin_amdgcn_sched_barrier(0);
;                 SUB_FROW(bufA, 0, 8); __builtin_amdgcn_sched_barrier(0);
;                 if (i + 1 < 64) SUB_LROW(bufA, i + 1, 0, 8);
;                 __builtin_amdgcn_sched_barrier(0);
;                 SUB_FROW(bufB, 8, (i + 3) / 4 - 8);
;                 x[i] = acc;
;                 __builtin_amdgcn_sched_barrier(0);
;             }
	v_pk_fma_f32 v[242:243], v[38:39], v[128:129], v[242:243] neg_lo:[1,0,0] neg_hi:[1,0,0]
	v_pk_fma_f32 v[244:245], v[40:41], v[130:131], v[244:245] neg_lo:[1,0,0] neg_hi:[1,0,0]
	ds_read_b128 v[124:127], v1 offset:52080
	s_waitcnt lgkmcnt(14)
	v_pk_fma_f32 v[242:243], v[42:43], v[132:133], v[242:243] neg_lo:[1,0,0] neg_hi:[1,0,0]
	v_pk_fma_f32 v[244:245], v[44:45], v[134:135], v[244:245] neg_lo:[1,0,0] neg_hi:[1,0,0]
	ds_read_b128 v[128:131], v1 offset:52096
	s_waitcnt lgkmcnt(14)
	v_pk_fma_f32 v[242:243], v[46:47], v[136:137], v[242:243] neg_lo:[1,0,0] neg_hi:[1,0,0]
	v_pk_fma_f32 v[244:245], v[48:49], v[138:139], v[244:245] neg_lo:[1,0,0] neg_hi:[1,0,0]
	ds_read_b128 v[132:135], v1 offset:52112
	s_waitcnt lgkmcnt(14)
	v_pk_fma_f32 v[242:243], v[50:51], v[140:141], v[242:243] neg_lo:[1,0,0] neg_hi:[1,0,0]
	v_pk_fma_f32 v[244:245], v[52:53], v[142:143], v[244:245] neg_lo:[1,0,0] neg_hi:[1,0,0]
	ds_read_b128 v[136:139], v1 offset:52128
	s_waitcnt lgkmcnt(14)
	v_pk_fma_f32 v[242:243], v[54:55], v[200:201], v[242:243] neg_lo:[1,0,0] neg_hi:[1,0,0]
	v_pk_fma_f32 v[244:245], v[56:57], v[202:203], v[244:245] neg_lo:[1,0,0] neg_hi:[1,0,0]
	ds_read_b128 v[140:143], v1 offset:52144
	s_waitcnt lgkmcnt(14)
	v_pk_fma_f32 v[242:243], v[58:59], v[204:205], v[242:243] neg_lo:[1,0,0] neg_hi:[1,0,0]
	v_pk_fma_f32 v[244:245], v[60:61], v[206:207], v[244:245] neg_lo:[1,0,0] neg_hi:[1,0,0]
	ds_read_b128 v[200:203], v1 offset:52160
	s_waitcnt lgkmcnt(14)
	v_pk_fma_f32 v[242:243], v[62:63], v[246:247], v[242:243] neg_lo:[1,0,0] neg_hi:[1,0,0]
	v_pk_fma_f32 v[244:245], v[64:65], v[248:249], v[244:245] neg_lo:[1,0,0] neg_hi:[1,0,0]
	ds_read_b128 v[204:207], v1 offset:52176
	s_nop 0
	v_pk_add_f32 v[242:243], v[242:243], v[244:245]
	s_nop 0
	v_add_f32_e32 v242, v242, v243
	v_add_f32_e32 v64, v64, v242
	s_waitcnt lgkmcnt(14)
	v_pk_mul_f32 v[242:243], v[2:3], v[66:67] neg_lo:[1,0] neg_hi:[1,0]
	v_pk_mul_f32 v[244:245], v[4:5], v[68:69] neg_lo:[1,0] neg_hi:[1,0]
	ds_read_b128 v[246:249], v1 offset:52192
	s_waitcnt lgkmcnt(14)
	v_pk_fma_f32 v[242:243], v[6:7], v[70:71], v[242:243] neg_lo:[1,0,0] neg_hi:[1,0,0]
	v_pk_fma_f32 v[244:245], v[8:9], v[72:73], v[244:245] neg_lo:[1,0,0] neg_hi:[1,0,0]
	s_waitcnt lgkmcnt(13)
	v_pk_fma_f32 v[242:243], v[10:11], v[74:75], v[242:243] neg_lo:[1,0,0] neg_hi:[1,0,0]
	v_pk_fma_f32 v[244:245], v[12:13], v[76:77], v[244:245] neg_lo:[1,0,0] neg_hi:[1,0,0]
	s_waitcnt lgkmcnt(12)
	v_pk_fma_f32 v[242:243], v[14:15], v[78:79], v[242:243] neg_lo:[1,0,0] neg_hi:[1,0,0]
	v_pk_fma_f32 v[244:245], v[16:17], v[80:81], v[244:245] neg_lo:[1,0,0] neg_hi:[1,0,0]
	s_waitcnt lgkmcnt(11)
	v_pk_fma_f32 v[242:243], v[18:19], v[82:83], v[242:243] neg_lo:[1,0,0] neg_hi:[1,0,0]
	v_pk_fma_f32 v[244:245], v[20:21], v[84:85], v[244:245] neg_lo:[1,0,0] neg_hi:[1,0,0]
	s_waitcnt lgkmcnt(10)
	v_pk_fma_f32 v[242:243], v[22:23], v[86:87], v[242:243] neg_lo:[1,0,0] neg_hi:[1,0,0]
	v_pk_fma_f32 v[244:245], v[24:25], v[88:89], v[244:245] neg_lo:[1,0,0] neg_hi:[1,0,0]
	s_waitcnt lgkmcnt(9)
	v_pk_fma_f32 v[242:243], v[26:27], v[116:117], v[242:243] neg_lo:[1,0,0] neg_hi:[1,0,0]
	v_pk_fma_f32 v[244:245], v[28:29], v[118:119], v[244:245] neg_lo:[1,0,0] neg_hi:[1,0,0]
	s_waitcnt lgkmcnt(8)
	v_pk_fma_f32 v[242:243], v[30:31], v[120:121], v[242:243] neg_lo:[1,0,0] neg_hi:[1,0,0]
	v_pk_fma_f32 v[244:245], v[32:33], v[122:123], v[244:245] neg_lo:[1,0,0] neg_hi:[1,0,0]
	s_waitcnt lgkmcnt(7)
	v_pk_fma_f32 v[242:243], v[34:35], v[124:125], v[242:243] neg_lo:[1,0,0] neg_hi:[1,0,0]
	v_pk_fma_f32 v[244:245], v[36:37], v[126:127], v[244:245] neg_lo:[1,0,0] neg_hi:[1,0,0]
	s_waitcnt lgkmcnt(6)
	v_pk_fma_f32 v[242:243], v[38:39], v[128:129], v[242:243] neg_lo:[1,0,0] neg_hi:[1,0,0]
	v_pk_fma_f32 v[244:245], v[40:41], v[130:131], v[244:245] neg_lo:[1,0,0] neg_hi:[1,0,0]
	s_waitcnt lgkmcnt(5)
; #define SUB_LROW(buf, i_, j0_, n_) do { _Pragma("unroll") for (int j4 = 0; j4 < (n_); ++j4) buf[j4] = *(const f32x4*)(Ls + (i_) * 68 + 4 * ((j0_) + j4)); } while (0)
; #define SUB_FROW(buf, j0_, n_) do { _Pragma("unroll") for (int j4 = 0; j4 < (n_); ++j4) { const f32x4 l = buf[j4]; \
;                 acc -= l.x * x[4 * ((j0_) + j4)]; acc -= l.y * x[4 * ((j0_) + j4) + 1]; acc -= l.z * x[4 * ((j0_) + j4) + 2]; acc -= l.w * x[4 * ((j0_) + j4) + 3]; } } while (0)
; __device__ __forceinline__ void gdn_prep(KA a, int layer, unsigned char* lds, const int tid_, const int bid_) {
;     ...
;             for (int i = 33; i < 64; ++i) {
;                 float acc = x[i];
;                 SUB_LROW(bufB, i, 8, (i + 3) / 4 - 8); __builtin_amdgcn_sched_barrier(0);
;                 SUB_FROW(bufA, 0, 8); __builtin_amdgcn_sched_barrier(0);
;                 if (i + 1 < 64) SUB_LROW(bufA, i + 1, 0, 8);
;                 __builtin_amdgcn_sched_barrier(0);
;                 SUB_FROW(bufB, 8, (i + 3) / 4 - 8);
;                 x[i] = acc;
;                 __builtin_amdgcn_sched_barrier(0);
;             }
;     ...
; #pragma unroll
;             for (int i = 0; i < 64; ++i) RHS[i * 260 + tid] = x[i];
	v_pk_fma_f32 v[242:243], v[42:43], v[132:133], v[242:243] neg_lo:[1,0,0] neg_hi:[1,0,0]
	v_pk_fma_f32 v[244:245], v[44:45], v[134:135], v[244:245] neg_lo:[1,0,0] neg_hi:[1,0,0]
	s_waitcnt lgkmcnt(4)
	v_pk_fma_f32 v[242:243], v[46:47], v[136:137], v[242:243] neg_lo:[1,0,0] neg_hi:[1,0,0]
	v_pk_fma_f32 v[244:245], v[48:49], v[138:139], v[244:245] neg_lo:[1,0,0] neg_hi:[1,0,0]
	s_waitcnt lgkmcnt(3)
	v_pk_fma_f32 v[242:243], v[50:51], v[140:141], v[242:243] neg_lo:[1,0,0] neg_hi:[1,0,0]
	v_pk_fma_f32 v[244:245], v[52:53], v[142:143], v[244:245] neg_lo:[1,0,0] neg_hi:[1,0,0]
	s_waitcnt lgkmcnt(2)
	v_pk_fma_f32 v[242:243], v[54:55], v[200:201], v[242:243] neg_lo:[1,0,0] neg_hi:[1,0,0]
	v_pk_fma_f32 v[244:245], v[56:57], v[202:203], v[244:245] neg_lo:[1,0,0] neg_hi:[1,0,0]
	s_waitcnt lgkmcnt(1)
	v_pk_fma_f32 v[242:243], v[58:59], v[204:205], v[242:243] neg_lo:[1,0,0] neg_hi:[1,0,0]
	v_pk_fma_f32 v[244:245], v[60:61], v[206:207], v[244:245] neg_lo:[1,0,0] neg_hi:[1,0,0]
	s_waitcnt lgkmcnt(0)
	v_pk_fma_f32 v[242:243], v[62:63], v[246:247], v[242:243] neg_lo:[1,0,0] neg_hi:[1,0,0]
	v_pk_fma_f32 v[244:245], v[64:65], v[248:249], v[244:245] neg_lo:[1,0,0] neg_hi:[1,0,0]
	s_nop 0
	v_pk_add_f32 v[242:243], v[242:243], v[244:245]
	s_nop 0
	v_add_f32_e32 v242, v242, v243
	v_add_f32_e32 v65, v65, v242
	s_ashr_i32 s19, s18, 31
	ds_write_b32 v154, v2 offset:52224
	ds_write_b32 v154, v3 offset:53264
	ds_write_b32 v154, v4 offset:54304
	ds_write_b32 v154, v5 offset:55344
	ds_write_b32 v154, v6 offset:56384
	ds_write_b32 v154, v7 offset:57424
	ds_write_b32 v154, v8 offset:58464
	ds_write_b32 v154, v9 offset:59504
	ds_write_b32 v154, v10 offset:60544
	ds_write_b32 v154, v11 offset:61584
	ds_write_b32 v154, v12 offset:62624
	ds_write_b32 v154, v13 offset:63664
	ds_write_b32 v154, v14 offset:64704
	ds_write_b32 v155, v15 offset:13520
	ds_write_b32 v155, v16 offset:14560
	ds_write_b32 v155, v17 offset:15600
	ds_write_b32 v155, v18 offset:16640
	ds_write_b32 v155, v19 offset:17680
	ds_write_b32 v155, v20 offset:18720
	ds_write_b32 v155, v21 offset:19760
	ds_write_b32 v155, v22 offset:20800
	ds_write_b32 v155, v23 offset:21840
	ds_write_b32 v155, v24 offset:22880
	ds_write_b32 v155, v25 offset:23920
	ds_write_b32 v155, v26 offset:24960
	ds_write_b32 v155, v27 offset:26000
	ds_write_b32 v155, v28 offset:27040
	ds_write_b32 v155, v29 offset:28080
	ds_write_b32 v155, v30 offset:29120
	ds_write_b32 v155, v31 offset:30160
	ds_write_b32 v155, v32 offset:31200
	ds_write_b32 v155, v33 offset:32240
	ds_write_b32 v155, v34 offset:33280
	ds_write_b32 v155, v35 offset:34320
	ds_write_b32 v155, v36 offset:35360
	ds_write_b32 v155, v37 offset:36400
	ds_write_b32 v155, v38 offset:37440
	ds_write_b32 v155, v39 offset:38480
	ds_write_b32 v155, v40 offset:39520
	ds_write_b32 v155, v41 offset:40560
	ds_write_b32 v155, v42 offset:41600
	ds_write_b32 v155, v43 offset:42640
	ds_write_b32 v155, v44 offset:43680
	ds_write_b32 v155, v45 offset:44720
	ds_write_b32 v155, v46 offset:45760
	ds_write_b32 v155, v47 offset:46800
	ds_write_b32 v155, v48 offset:47840
	ds_write_b32 v155, v49 offset:48880
	ds_write_b32 v155, v50 offset:49920
	ds_write_b32 v155, v51 offset:50960
	ds_write_b32 v155, v52 offset:52000
	ds_write_b32 v155, v53 offset:53040
	ds_write_b32 v155, v54 offset:54080
	ds_write_b32 v155, v55 offset:55120
	ds_write_b32 v155, v56 offset:56160
	ds_write_b32 v155, v57 offset:57200
	ds_write_b32 v155, v58 offset:58240
	ds_write_b32 v155, v59 offset:59280
	ds_write_b32 v155, v60 offset:60320
	ds_write_b32 v155, v61 offset:61360
	ds_write_b32 v155, v62 offset:62400
	ds_write_b32 v155, v63 offset:63440
	ds_write_b32 v155, v64 offset:64480
	ds_write_b32 v155, v65 offset:65520
	v_mov_b64_e32 v[2:3], s[18:19]
	s_branch .LBB0_208
